# PROBE2: all per-phase s_setprio flips removed from the GEMM K loops
# speedup vs baseline: 1.0150x; 1.0143x over previous
.LBB0_195:
	v_mov_b32_e32 v127, 0
	s_andn2_b64 vcc, exec, s[80:81]
	v_mov_b32_e32 v126, v127
	v_mov_b32_e32 v125, v127
	v_mov_b32_e32 v124, v127
	v_mov_b32_e32 v123, v127
	v_mov_b32_e32 v122, v127
	v_mov_b32_e32 v121, v127
	v_mov_b32_e32 v120, v127
	v_mov_b32_e32 v111, v127
	v_mov_b32_e32 v110, v127
	v_mov_b32_e32 v109, v127
	v_mov_b32_e32 v108, v127
	v_mov_b32_e32 v107, v127
	v_mov_b32_e32 v106, v127
	v_mov_b32_e32 v105, v127
	v_mov_b32_e32 v104, v127
	v_mov_b32_e32 v95, v127
	v_mov_b32_e32 v94, v127
	v_mov_b32_e32 v93, v127
	v_mov_b32_e32 v92, v127
	v_mov_b32_e32 v91, v127
	v_mov_b32_e32 v90, v127
	v_mov_b32_e32 v89, v127
	v_mov_b32_e32 v88, v127
	v_mov_b32_e32 v79, v127
	v_mov_b32_e32 v78, v127
	v_mov_b32_e32 v77, v127
	v_mov_b32_e32 v76, v127
	v_mov_b32_e32 v75, v127
	v_mov_b32_e32 v74, v127
	v_mov_b32_e32 v73, v127
	v_mov_b32_e32 v72, v127
	v_mov_b32_e32 v119, v127
	v_mov_b32_e32 v118, v127
	v_mov_b32_e32 v117, v127
	v_mov_b32_e32 v116, v127
	v_mov_b32_e32 v115, v127
	v_mov_b32_e32 v114, v127
	v_mov_b32_e32 v113, v127
	v_mov_b32_e32 v112, v127
	v_mov_b32_e32 v103, v127
	v_mov_b32_e32 v102, v127
	v_mov_b32_e32 v101, v127
	v_mov_b32_e32 v100, v127
	v_mov_b32_e32 v99, v127
	v_mov_b32_e32 v98, v127
	v_mov_b32_e32 v97, v127
	v_mov_b32_e32 v96, v127
	v_mov_b32_e32 v87, v127
	v_mov_b32_e32 v86, v127
	v_mov_b32_e32 v85, v127
	v_mov_b32_e32 v84, v127
	v_mov_b32_e32 v83, v127
	v_mov_b32_e32 v82, v127
	v_mov_b32_e32 v81, v127
	v_mov_b32_e32 v80, v127
	v_mov_b32_e32 v71, v127
	v_mov_b32_e32 v70, v127
	v_mov_b32_e32 v69, v127
	v_mov_b32_e32 v68, v127
	v_mov_b32_e32 v67, v127
	v_mov_b32_e32 v66, v127
	v_mov_b32_e32 v65, v127
	v_mov_b32_e32 v64, v127
	v_mov_b32_e32 v63, v127
	v_mov_b32_e32 v62, v127
	v_mov_b32_e32 v61, v127
	v_mov_b32_e32 v60, v127
	v_mov_b32_e32 v59, v127
	v_mov_b32_e32 v58, v127
	v_mov_b32_e32 v57, v127
	v_mov_b32_e32 v56, v127
	v_mov_b32_e32 v47, v127
	v_mov_b32_e32 v46, v127
	v_mov_b32_e32 v45, v127
	v_mov_b32_e32 v44, v127
	v_mov_b32_e32 v43, v127
	v_mov_b32_e32 v42, v127
	v_mov_b32_e32 v41, v127
	v_mov_b32_e32 v40, v127
	v_mov_b32_e32 v31, v127
	v_mov_b32_e32 v30, v127
	v_mov_b32_e32 v29, v127
	v_mov_b32_e32 v28, v127
	v_mov_b32_e32 v27, v127
	v_mov_b32_e32 v26, v127
	v_mov_b32_e32 v25, v127
	v_mov_b32_e32 v24, v127
	v_mov_b32_e32 v15, v127
	v_mov_b32_e32 v14, v127
	v_mov_b32_e32 v13, v127
	v_mov_b32_e32 v12, v127
	v_mov_b32_e32 v11, v127
	v_mov_b32_e32 v10, v127
	v_mov_b32_e32 v9, v127
	v_mov_b32_e32 v8, v127
	v_mov_b32_e32 v55, v127
	v_mov_b32_e32 v54, v127
	v_mov_b32_e32 v53, v127
	v_mov_b32_e32 v52, v127
	v_mov_b32_e32 v51, v127
	v_mov_b32_e32 v50, v127
	v_mov_b32_e32 v49, v127
	v_mov_b32_e32 v48, v127
	v_mov_b32_e32 v39, v127
	v_mov_b32_e32 v38, v127
	v_mov_b32_e32 v37, v127
	v_mov_b32_e32 v36, v127
	v_mov_b32_e32 v35, v127
	v_mov_b32_e32 v34, v127
	v_mov_b32_e32 v33, v127
	v_mov_b32_e32 v32, v127
	v_mov_b32_e32 v23, v127
	v_mov_b32_e32 v22, v127
	v_mov_b32_e32 v21, v127
	v_mov_b32_e32 v20, v127
	v_mov_b32_e32 v19, v127
	v_mov_b32_e32 v18, v127
	v_mov_b32_e32 v17, v127
	v_mov_b32_e32 v16, v127
	v_mov_b32_e32 v7, v127
	v_mov_b32_e32 v6, v127
	v_mov_b32_e32 v5, v127
	v_mov_b32_e32 v4, v127
	v_mov_b32_e32 v3, v127
	v_mov_b32_e32 v2, v127
	v_mov_b32_e32 v1, v127
	v_mov_b32_e32 v0, v127
	s_cbranch_vccnz .LBB0_198
	s_add_u32 s10, s6, 0x100
	s_addc_u32 s40, s7, 0
	s_add_u32 s6, s38, 0x80
	s_addc_u32 s7, s39, 0
	s_mov_b32 s2, 0
	s_add_i32 s41, s2, 2
	s_add_u32 s21, s6, 0x80
	s_addc_u32 s3, s7, 0
	s_add_i32 s42, 0, 0x10000
	v_add_u32_e32 v140, s42, v154
	ds_read_b128 v[142:145], v140
	ds_read_b128 v[162:165], v140 offset:1024
	ds_read_b128 v[166:169], v140 offset:2048
	ds_read_b128 v[170:173], v140 offset:3072
	s_cmp_eq_u32 s9, s2
	s_cselect_b32 s2, s68, s21
	s_cselect_b32 s3, s69, s3
	s_cselect_b32 s39, s95, s40
	s_cselect_b32 s38, s94, s10
	v_lshl_add_u64 v[226:227], s[6:7], 0, v[138:139]
	s_add_i32 m0, s79, 0xc000
	ds_read_b128 v[174:177], v155
	ds_read_b128 v[178:181], v155 offset:1024
	ds_read_b128 v[182:185], v155 offset:2048
	ds_read_b128 v[186:189], v155 offset:3072
	ds_read_b128 v[206:209], v155 offset:4096
	ds_read_b128 v[214:217], v155 offset:5120
	ds_read_b128 v[218:221], v155 offset:6144
	ds_read_b128 v[222:225], v155 offset:7168
	global_load_lds_dwordx4 v[226:227], off
	v_lshl_add_u64 v[226:227], s[6:7], 0, v[136:137]
	s_add_i32 m0, s79, 0xe000
	s_nop 0
	global_load_lds_dwordx4 v[226:227], off
	s_waitcnt lgkmcnt(8)
	s_barrier
	s_waitcnt lgkmcnt(0)
	s_waitcnt lgkmcnt(0)
	v_mfma_f32_16x16x32_bf16 v[124:127], v[142:145], v[174:177], 0
	v_mfma_f32_16x16x32_bf16 v[120:123], v[166:169], v[174:177], 0
	v_mfma_f32_16x16x32_bf16 v[108:111], v[142:145], v[182:185], 0
	v_mfma_f32_16x16x32_bf16 v[104:107], v[166:169], v[182:185], 0
	v_mfma_f32_16x16x32_bf16 v[92:95], v[142:145], v[206:209], 0
	v_mfma_f32_16x16x32_bf16 v[88:91], v[166:169], v[206:209], 0
	v_mfma_f32_16x16x32_bf16 v[76:79], v[142:145], v[218:221], 0
	v_mfma_f32_16x16x32_bf16 v[72:75], v[166:169], v[218:221], 0
	v_mfma_f32_16x16x32_bf16 v[124:127], v[162:165], v[178:181], v[124:127]
	v_mfma_f32_16x16x32_bf16 v[120:123], v[170:173], v[178:181], v[120:123]
	v_mfma_f32_16x16x32_bf16 v[108:111], v[162:165], v[186:189], v[108:111]
	v_mfma_f32_16x16x32_bf16 v[104:107], v[170:173], v[186:189], v[104:107]
	v_mfma_f32_16x16x32_bf16 v[92:95], v[162:165], v[214:217], v[92:95]
	v_mfma_f32_16x16x32_bf16 v[88:91], v[170:173], v[214:217], v[88:91]
	v_mfma_f32_16x16x32_bf16 v[76:79], v[162:165], v[222:225], v[76:79]
	v_mfma_f32_16x16x32_bf16 v[72:75], v[170:173], v[222:225], v[72:75]
	s_barrier
	s_add_i32 s21, 0, 0x14000
	s_add_i32 s42, s42, s54
	v_add_u32_e32 v140, s21, v154
	v_lshl_add_u64 v[242:243], s[38:39], 0, v[130:131]
	s_mov_b32 m0, s42
	ds_read_b128 v[226:229], v140
	ds_read_b128 v[230:233], v140 offset:1024
	ds_read_b128 v[234:237], v140 offset:2048
	ds_read_b128 v[238:241], v140 offset:3072
	global_load_lds_dwordx4 v[242:243], off
	v_lshl_add_u64 v[244:245], s[38:39], 0, v[128:129]
	s_add_i32 m0, s42, 0x2000
	s_nop 0
	global_load_lds_dwordx4 v[244:245], off
	s_barrier
	s_waitcnt lgkmcnt(0)
	s_waitcnt lgkmcnt(0)
	v_mfma_f32_16x16x32_bf16 v[116:119], v[226:229], v[174:177], 0
	v_mfma_f32_16x16x32_bf16 v[112:115], v[234:237], v[174:177], 0
	v_mfma_f32_16x16x32_bf16 v[100:103], v[226:229], v[182:185], 0
	v_mfma_f32_16x16x32_bf16 v[96:99], v[234:237], v[182:185], 0
	v_mfma_f32_16x16x32_bf16 v[84:87], v[226:229], v[206:209], 0
	v_mfma_f32_16x16x32_bf16 v[80:83], v[234:237], v[206:209], 0
	v_mfma_f32_16x16x32_bf16 v[68:71], v[226:229], v[218:221], 0
	v_mfma_f32_16x16x32_bf16 v[64:67], v[234:237], v[218:221], 0
	v_mfma_f32_16x16x32_bf16 v[116:119], v[230:233], v[178:181], v[116:119]
	v_mfma_f32_16x16x32_bf16 v[112:115], v[238:241], v[178:181], v[112:115]
	v_mfma_f32_16x16x32_bf16 v[100:103], v[230:233], v[186:189], v[100:103]
	v_mfma_f32_16x16x32_bf16 v[96:99], v[238:241], v[186:189], v[96:99]
	v_mfma_f32_16x16x32_bf16 v[84:87], v[230:233], v[214:217], v[84:87]
	v_mfma_f32_16x16x32_bf16 v[80:83], v[238:241], v[214:217], v[80:83]
	v_mfma_f32_16x16x32_bf16 v[68:71], v[230:233], v[222:225], v[68:71]
	v_mfma_f32_16x16x32_bf16 v[64:67], v[238:241], v[222:225], v[64:67]
	s_mov_b32 m0, s79
	v_lshl_add_u64 v[246:247], s[2:3], 0, v[130:131]
	s_barrier
	ds_read_b128 v[174:177], v155 offset:16384
	ds_read_b128 v[178:181], v155 offset:17408
	ds_read_b128 v[182:185], v155 offset:18432
	ds_read_b128 v[186:189], v155 offset:19456
	ds_read_b128 v[206:209], v155 offset:20480
	ds_read_b128 v[214:217], v155 offset:21504
	ds_read_b128 v[218:221], v155 offset:22528
	ds_read_b128 v[222:225], v155 offset:23552
	global_load_lds_dwordx4 v[246:247], off
	v_lshl_add_u64 v[248:249], s[2:3], 0, v[128:129]
	s_mov_b32 m0, s34
	s_nop 0
	global_load_lds_dwordx4 v[248:249], off
	s_barrier
	s_waitcnt lgkmcnt(0)
	s_waitcnt lgkmcnt(0)
	v_mfma_f32_16x16x32_bf16 v[60:63], v[142:145], v[174:177], 0
	v_mfma_f32_16x16x32_bf16 v[56:59], v[166:169], v[174:177], 0
	v_mfma_f32_16x16x32_bf16 v[44:47], v[142:145], v[182:185], 0
	v_mfma_f32_16x16x32_bf16 v[40:43], v[166:169], v[182:185], 0
	v_mfma_f32_16x16x32_bf16 v[28:31], v[142:145], v[206:209], 0
	v_mfma_f32_16x16x32_bf16 v[24:27], v[166:169], v[206:209], 0
	v_mfma_f32_16x16x32_bf16 v[12:15], v[142:145], v[218:221], 0
	v_mfma_f32_16x16x32_bf16 v[8:11], v[166:169], v[218:221], 0
	v_mfma_f32_16x16x32_bf16 v[60:63], v[162:165], v[178:181], v[60:63]
	v_mfma_f32_16x16x32_bf16 v[56:59], v[170:173], v[178:181], v[56:59]
	v_mfma_f32_16x16x32_bf16 v[44:47], v[162:165], v[186:189], v[44:47]
	v_mfma_f32_16x16x32_bf16 v[40:43], v[170:173], v[186:189], v[40:43]
	v_mfma_f32_16x16x32_bf16 v[28:31], v[162:165], v[214:217], v[28:31]
	v_mfma_f32_16x16x32_bf16 v[24:27], v[170:173], v[214:217], v[24:27]
	v_mfma_f32_16x16x32_bf16 v[12:15], v[162:165], v[222:225], v[12:15]
	v_mfma_f32_16x16x32_bf16 v[8:11], v[170:173], v[222:225], v[8:11]
	s_barrier
	s_add_u32 s38, s38, s88
	s_addc_u32 s39, s39, s89
	s_add_i32 s21, s21, s54
	v_lshl_add_u64 v[250:251], s[38:39], 0, v[130:131]
	s_mov_b32 m0, s21
	v_lshl_add_u64 v[252:253], s[38:39], 0, v[128:129]
	global_load_lds_dwordx4 v[250:251], off
	s_add_i32 m0, s21, 0x2000
	s_nop 0
	global_load_lds_dwordx4 v[252:253], off
	s_waitcnt vmcnt(6)
	s_barrier
	v_mfma_f32_16x16x32_bf16 v[52:55], v[226:229], v[174:177], 0
	v_mfma_f32_16x16x32_bf16 v[48:51], v[234:237], v[174:177], 0
	v_mfma_f32_16x16x32_bf16 v[36:39], v[226:229], v[182:185], 0
	v_mfma_f32_16x16x32_bf16 v[32:35], v[234:237], v[182:185], 0
	v_mfma_f32_16x16x32_bf16 v[20:23], v[226:229], v[206:209], 0
	v_mfma_f32_16x16x32_bf16 v[16:19], v[234:237], v[206:209], 0
	v_mfma_f32_16x16x32_bf16 v[4:7], v[226:229], v[218:221], 0
	v_mfma_f32_16x16x32_bf16 v[0:3], v[234:237], v[218:221], 0
	v_mfma_f32_16x16x32_bf16 v[52:55], v[230:233], v[178:181], v[52:55]
	v_mfma_f32_16x16x32_bf16 v[48:51], v[238:241], v[178:181], v[48:51]
	v_mfma_f32_16x16x32_bf16 v[36:39], v[230:233], v[186:189], v[36:39]
	v_mfma_f32_16x16x32_bf16 v[32:35], v[238:241], v[186:189], v[32:35]
	v_mfma_f32_16x16x32_bf16 v[20:23], v[230:233], v[214:217], v[20:23]
	v_mfma_f32_16x16x32_bf16 v[16:19], v[238:241], v[214:217], v[16:19]
	v_mfma_f32_16x16x32_bf16 v[4:7], v[230:233], v[222:225], v[4:7]
	v_mfma_f32_16x16x32_bf16 v[0:3], v[238:241], v[222:225], v[0:3]
	s_add_i32 s21, 0, 0x18000
	v_add_u32_e32 v140, s21, v154
	s_barrier
	ds_read_b128 v[142:145], v140
	ds_read_b128 v[162:165], v140 offset:1024
	ds_read_b128 v[166:169], v140 offset:2048
	ds_read_b128 v[170:173], v140 offset:3072
	s_add_u32 s2, s2, s88
	s_addc_u32 s3, s3, s89
	s_mov_b32 m0, s35
	v_lshl_add_u64 v[226:227], s[2:3], 0, v[130:131]
	ds_read_b128 v[174:177], v155 offset:32768
	ds_read_b128 v[178:181], v155 offset:33792
	ds_read_b128 v[182:185], v155 offset:34816
	ds_read_b128 v[186:189], v155 offset:35840
	ds_read_b128 v[206:209], v155 offset:36864
	ds_read_b128 v[214:217], v155 offset:37888
	ds_read_b128 v[218:221], v155 offset:38912
	ds_read_b128 v[222:225], v155 offset:39936
	global_load_lds_dwordx4 v[226:227], off
	v_lshl_add_u64 v[226:227], s[2:3], 0, v[128:129]
	s_mov_b32 m0, s44
	s_nop 0
	global_load_lds_dwordx4 v[226:227], off
	s_waitcnt lgkmcnt(8)
	s_barrier
	s_waitcnt lgkmcnt(0)
	s_waitcnt lgkmcnt(0)
	v_mfma_f32_16x16x32_bf16 v[124:127], v[142:145], v[174:177], v[124:127]
	v_mfma_f32_16x16x32_bf16 v[120:123], v[166:169], v[174:177], v[120:123]
	v_mfma_f32_16x16x32_bf16 v[108:111], v[142:145], v[182:185], v[108:111]
	v_mfma_f32_16x16x32_bf16 v[104:107], v[166:169], v[182:185], v[104:107]
	v_mfma_f32_16x16x32_bf16 v[92:95], v[142:145], v[206:209], v[92:95]
	v_mfma_f32_16x16x32_bf16 v[88:91], v[166:169], v[206:209], v[88:91]
	v_mfma_f32_16x16x32_bf16 v[76:79], v[142:145], v[218:221], v[76:79]
	v_mfma_f32_16x16x32_bf16 v[72:75], v[166:169], v[218:221], v[72:75]
	v_mfma_f32_16x16x32_bf16 v[124:127], v[162:165], v[178:181], v[124:127]
	v_mfma_f32_16x16x32_bf16 v[120:123], v[170:173], v[178:181], v[120:123]
	v_mfma_f32_16x16x32_bf16 v[108:111], v[162:165], v[186:189], v[108:111]
	v_mfma_f32_16x16x32_bf16 v[104:107], v[170:173], v[186:189], v[104:107]
	v_mfma_f32_16x16x32_bf16 v[92:95], v[162:165], v[214:217], v[92:95]
	v_mfma_f32_16x16x32_bf16 v[88:91], v[170:173], v[214:217], v[88:91]
	v_mfma_f32_16x16x32_bf16 v[76:79], v[162:165], v[222:225], v[76:79]
	v_mfma_f32_16x16x32_bf16 v[72:75], v[170:173], v[222:225], v[72:75]
	s_barrier
	s_add_i32 s2, 0, 0x1c000
	s_add_i32 s3, s21, s54
	v_add_u32_e32 v140, s2, v154
	v_lshl_add_u64 v[242:243], v[242:243], 0, s[50:51]
	s_mov_b32 m0, s3
	ds_read_b128 v[226:229], v140
	ds_read_b128 v[230:233], v140 offset:1024
	ds_read_b128 v[234:237], v140 offset:2048
	ds_read_b128 v[238:241], v140 offset:3072
	global_load_lds_dwordx4 v[242:243], off
	v_lshl_add_u64 v[242:243], v[244:245], 0, s[50:51]
	s_add_i32 m0, s3, 0x2000
	s_nop 0
	global_load_lds_dwordx4 v[242:243], off
	s_barrier
	s_waitcnt lgkmcnt(0)
	s_waitcnt lgkmcnt(0)
	v_mfma_f32_16x16x32_bf16 v[116:119], v[226:229], v[174:177], v[116:119]
	v_mfma_f32_16x16x32_bf16 v[112:115], v[234:237], v[174:177], v[112:115]
	v_mfma_f32_16x16x32_bf16 v[100:103], v[226:229], v[182:185], v[100:103]
	v_mfma_f32_16x16x32_bf16 v[96:99], v[234:237], v[182:185], v[96:99]
	v_mfma_f32_16x16x32_bf16 v[84:87], v[226:229], v[206:209], v[84:87]
	v_mfma_f32_16x16x32_bf16 v[80:83], v[234:237], v[206:209], v[80:83]
	v_mfma_f32_16x16x32_bf16 v[68:71], v[226:229], v[218:221], v[68:71]
	v_mfma_f32_16x16x32_bf16 v[64:67], v[234:237], v[218:221], v[64:67]
	v_mfma_f32_16x16x32_bf16 v[116:119], v[230:233], v[178:181], v[116:119]
	v_mfma_f32_16x16x32_bf16 v[112:115], v[238:241], v[178:181], v[112:115]
	v_mfma_f32_16x16x32_bf16 v[100:103], v[230:233], v[186:189], v[100:103]
	v_mfma_f32_16x16x32_bf16 v[96:99], v[238:241], v[186:189], v[96:99]
	v_mfma_f32_16x16x32_bf16 v[84:87], v[230:233], v[214:217], v[84:87]
	v_mfma_f32_16x16x32_bf16 v[80:83], v[238:241], v[214:217], v[80:83]
	v_mfma_f32_16x16x32_bf16 v[68:71], v[230:233], v[222:225], v[68:71]
	v_mfma_f32_16x16x32_bf16 v[64:67], v[238:241], v[222:225], v[64:67]
	s_mov_b32 m0, s82
	v_lshl_add_u64 v[242:243], v[246:247], 0, s[50:51]
	s_barrier
	ds_read_b128 v[174:177], v155 offset:49152
	ds_read_b128 v[178:181], v155 offset:50176
	ds_read_b128 v[182:185], v155 offset:51200
	ds_read_b128 v[186:189], v155 offset:52224
	ds_read_b128 v[206:209], v155 offset:53248
	ds_read_b128 v[214:217], v155 offset:54272
	ds_read_b128 v[218:221], v155 offset:55296
	ds_read_b128 v[222:225], v155 offset:56320
	global_load_lds_dwordx4 v[242:243], off
	v_lshl_add_u64 v[242:243], v[248:249], 0, s[50:51]
	s_mov_b32 m0, s83
	s_nop 0
	global_load_lds_dwordx4 v[242:243], off
	s_barrier
	s_waitcnt lgkmcnt(0)
	s_waitcnt lgkmcnt(0)
	v_mfma_f32_16x16x32_bf16 v[60:63], v[142:145], v[174:177], v[60:63]
	v_mfma_f32_16x16x32_bf16 v[56:59], v[166:169], v[174:177], v[56:59]
	v_mfma_f32_16x16x32_bf16 v[44:47], v[142:145], v[182:185], v[44:47]
	v_mfma_f32_16x16x32_bf16 v[40:43], v[166:169], v[182:185], v[40:43]
	v_mfma_f32_16x16x32_bf16 v[28:31], v[142:145], v[206:209], v[28:31]
	v_mfma_f32_16x16x32_bf16 v[24:27], v[166:169], v[206:209], v[24:27]
	v_mfma_f32_16x16x32_bf16 v[12:15], v[142:145], v[218:221], v[12:15]
	v_mfma_f32_16x16x32_bf16 v[8:11], v[166:169], v[218:221], v[8:11]
	v_mfma_f32_16x16x32_bf16 v[60:63], v[162:165], v[178:181], v[60:63]
	v_mfma_f32_16x16x32_bf16 v[56:59], v[170:173], v[178:181], v[56:59]
	v_mfma_f32_16x16x32_bf16 v[44:47], v[162:165], v[186:189], v[44:47]
	v_mfma_f32_16x16x32_bf16 v[40:43], v[170:173], v[186:189], v[40:43]
	v_mfma_f32_16x16x32_bf16 v[28:31], v[162:165], v[214:217], v[28:31]
	v_mfma_f32_16x16x32_bf16 v[24:27], v[170:173], v[214:217], v[24:27]
	v_mfma_f32_16x16x32_bf16 v[12:15], v[162:165], v[222:225], v[12:15]
	v_mfma_f32_16x16x32_bf16 v[8:11], v[170:173], v[222:225], v[8:11]
	s_barrier
	s_add_i32 s2, s2, s54
	v_lshl_add_u64 v[142:143], v[250:251], 0, s[50:51]
	s_mov_b32 m0, s2
	s_nop 0
	global_load_lds_dwordx4 v[142:143], off
	v_lshl_add_u64 v[142:143], v[252:253], 0, s[50:51]
	s_add_i32 m0, s2, 0x2000
	s_nop 0
	global_load_lds_dwordx4 v[142:143], off
	s_waitcnt vmcnt(6)
	s_barrier
	v_mfma_f32_16x16x32_bf16 v[52:55], v[226:229], v[174:177], v[52:55]
	v_mfma_f32_16x16x32_bf16 v[48:51], v[234:237], v[174:177], v[48:51]
	v_mfma_f32_16x16x32_bf16 v[36:39], v[226:229], v[182:185], v[36:39]
	v_mfma_f32_16x16x32_bf16 v[32:35], v[234:237], v[182:185], v[32:35]
	v_mfma_f32_16x16x32_bf16 v[20:23], v[226:229], v[206:209], v[20:23]
	v_mfma_f32_16x16x32_bf16 v[16:19], v[234:237], v[206:209], v[16:19]
	v_mfma_f32_16x16x32_bf16 v[4:7], v[226:229], v[218:221], v[4:7]
	v_mfma_f32_16x16x32_bf16 v[0:3], v[234:237], v[218:221], v[0:3]
	v_mfma_f32_16x16x32_bf16 v[52:55], v[230:233], v[178:181], v[52:55]
	v_mfma_f32_16x16x32_bf16 v[48:51], v[238:241], v[178:181], v[48:51]
	v_mfma_f32_16x16x32_bf16 v[36:39], v[230:233], v[186:189], v[36:39]
	v_mfma_f32_16x16x32_bf16 v[32:35], v[238:241], v[186:189], v[32:35]
	v_mfma_f32_16x16x32_bf16 v[20:23], v[230:233], v[214:217], v[20:23]
	v_mfma_f32_16x16x32_bf16 v[16:19], v[238:241], v[214:217], v[16:19]
	v_mfma_f32_16x16x32_bf16 v[4:7], v[230:233], v[222:225], v[4:7]
	v_mfma_f32_16x16x32_bf16 v[0:3], v[238:241], v[222:225], v[0:3]
	s_add_u32 s10, s10, 0x100
	s_addc_u32 s40, s40, 0
	s_add_u32 s6, s6, 0x100
	s_addc_u32 s7, s7, 0
	s_cmp_ge_i32 s41, s66
	s_mov_b32 s2, s41
	s_barrier
	s_cbranch_scc1 .Lpost_197
.LBB0_197:
	s_add_i32 s41, s2, 2
	s_add_u32 s21, s6, 0x80
	s_addc_u32 s3, s7, 0
	s_add_i32 s42, 0, 0x10000
	v_add_u32_e32 v140, s42, v154
	ds_read_b128 v[142:145], v140
	ds_read_b128 v[162:165], v140 offset:1024
	ds_read_b128 v[166:169], v140 offset:2048
	ds_read_b128 v[170:173], v140 offset:3072
	s_cmp_eq_u32 s9, s2
	s_cselect_b32 s2, s68, s21
	s_cselect_b32 s3, s69, s3
	s_cselect_b32 s39, s95, s40
	s_cselect_b32 s38, s94, s10
	v_lshl_add_u64 v[226:227], s[6:7], 0, v[138:139]
	s_add_i32 m0, s79, 0xc000
	ds_read_b128 v[174:177], v155
	ds_read_b128 v[178:181], v155 offset:1024
	ds_read_b128 v[182:185], v155 offset:2048
	ds_read_b128 v[186:189], v155 offset:3072
	ds_read_b128 v[206:209], v155 offset:4096
	ds_read_b128 v[214:217], v155 offset:5120
	ds_read_b128 v[218:221], v155 offset:6144
	ds_read_b128 v[222:225], v155 offset:7168
	global_load_lds_dwordx4 v[226:227], off
	v_lshl_add_u64 v[226:227], s[6:7], 0, v[136:137]
	s_add_i32 m0, s79, 0xe000
	s_nop 0
	global_load_lds_dwordx4 v[226:227], off
	s_waitcnt lgkmcnt(8)
	s_barrier
	s_waitcnt lgkmcnt(0)
	s_waitcnt lgkmcnt(0)
	v_mfma_f32_16x16x32_bf16 v[124:127], v[142:145], v[174:177], v[124:127]
	v_mfma_f32_16x16x32_bf16 v[120:123], v[166:169], v[174:177], v[120:123]
	v_mfma_f32_16x16x32_bf16 v[108:111], v[142:145], v[182:185], v[108:111]
	v_mfma_f32_16x16x32_bf16 v[104:107], v[166:169], v[182:185], v[104:107]
	v_mfma_f32_16x16x32_bf16 v[92:95], v[142:145], v[206:209], v[92:95]
	v_mfma_f32_16x16x32_bf16 v[88:91], v[166:169], v[206:209], v[88:91]
	v_mfma_f32_16x16x32_bf16 v[76:79], v[142:145], v[218:221], v[76:79]
	v_mfma_f32_16x16x32_bf16 v[72:75], v[166:169], v[218:221], v[72:75]
	v_mfma_f32_16x16x32_bf16 v[124:127], v[162:165], v[178:181], v[124:127]
	v_mfma_f32_16x16x32_bf16 v[120:123], v[170:173], v[178:181], v[120:123]
	v_mfma_f32_16x16x32_bf16 v[108:111], v[162:165], v[186:189], v[108:111]
	v_mfma_f32_16x16x32_bf16 v[104:107], v[170:173], v[186:189], v[104:107]
	v_mfma_f32_16x16x32_bf16 v[92:95], v[162:165], v[214:217], v[92:95]
	v_mfma_f32_16x16x32_bf16 v[88:91], v[170:173], v[214:217], v[88:91]
	v_mfma_f32_16x16x32_bf16 v[76:79], v[162:165], v[222:225], v[76:79]
	v_mfma_f32_16x16x32_bf16 v[72:75], v[170:173], v[222:225], v[72:75]
	s_barrier
	s_add_i32 s21, 0, 0x14000
	s_add_i32 s42, s42, s54
	v_add_u32_e32 v140, s21, v154
	v_lshl_add_u64 v[242:243], s[38:39], 0, v[130:131]
	s_mov_b32 m0, s42
	ds_read_b128 v[226:229], v140
	ds_read_b128 v[230:233], v140 offset:1024
	ds_read_b128 v[234:237], v140 offset:2048
	ds_read_b128 v[238:241], v140 offset:3072
	global_load_lds_dwordx4 v[242:243], off
	v_lshl_add_u64 v[244:245], s[38:39], 0, v[128:129]
	s_add_i32 m0, s42, 0x2000
	s_nop 0
	global_load_lds_dwordx4 v[244:245], off
	s_barrier
	s_waitcnt lgkmcnt(0)
	s_waitcnt lgkmcnt(0)
	v_mfma_f32_16x16x32_bf16 v[116:119], v[226:229], v[174:177], v[116:119]
	v_mfma_f32_16x16x32_bf16 v[112:115], v[234:237], v[174:177], v[112:115]
	v_mfma_f32_16x16x32_bf16 v[100:103], v[226:229], v[182:185], v[100:103]
	v_mfma_f32_16x16x32_bf16 v[96:99], v[234:237], v[182:185], v[96:99]
	v_mfma_f32_16x16x32_bf16 v[84:87], v[226:229], v[206:209], v[84:87]
	v_mfma_f32_16x16x32_bf16 v[80:83], v[234:237], v[206:209], v[80:83]
	v_mfma_f32_16x16x32_bf16 v[68:71], v[226:229], v[218:221], v[68:71]
	v_mfma_f32_16x16x32_bf16 v[64:67], v[234:237], v[218:221], v[64:67]
	v_mfma_f32_16x16x32_bf16 v[116:119], v[230:233], v[178:181], v[116:119]
	v_mfma_f32_16x16x32_bf16 v[112:115], v[238:241], v[178:181], v[112:115]
	v_mfma_f32_16x16x32_bf16 v[100:103], v[230:233], v[186:189], v[100:103]
	v_mfma_f32_16x16x32_bf16 v[96:99], v[238:241], v[186:189], v[96:99]
	v_mfma_f32_16x16x32_bf16 v[84:87], v[230:233], v[214:217], v[84:87]
	v_mfma_f32_16x16x32_bf16 v[80:83], v[238:241], v[214:217], v[80:83]
	v_mfma_f32_16x16x32_bf16 v[68:71], v[230:233], v[222:225], v[68:71]
	v_mfma_f32_16x16x32_bf16 v[64:67], v[238:241], v[222:225], v[64:67]
	s_mov_b32 m0, s79
	v_lshl_add_u64 v[246:247], s[2:3], 0, v[130:131]
	s_barrier
	ds_read_b128 v[174:177], v155 offset:16384
	ds_read_b128 v[178:181], v155 offset:17408
	ds_read_b128 v[182:185], v155 offset:18432
	ds_read_b128 v[186:189], v155 offset:19456
	ds_read_b128 v[206:209], v155 offset:20480
	ds_read_b128 v[214:217], v155 offset:21504
	ds_read_b128 v[218:221], v155 offset:22528
	ds_read_b128 v[222:225], v155 offset:23552
	global_load_lds_dwordx4 v[246:247], off
	v_lshl_add_u64 v[248:249], s[2:3], 0, v[128:129]
	s_mov_b32 m0, s34
	s_nop 0
	global_load_lds_dwordx4 v[248:249], off
	s_barrier
	s_waitcnt lgkmcnt(0)
	s_waitcnt lgkmcnt(0)
	v_mfma_f32_16x16x32_bf16 v[60:63], v[142:145], v[174:177], v[60:63]
	v_mfma_f32_16x16x32_bf16 v[56:59], v[166:169], v[174:177], v[56:59]
	v_mfma_f32_16x16x32_bf16 v[44:47], v[142:145], v[182:185], v[44:47]
	v_mfma_f32_16x16x32_bf16 v[40:43], v[166:169], v[182:185], v[40:43]
	v_mfma_f32_16x16x32_bf16 v[28:31], v[142:145], v[206:209], v[28:31]
	v_mfma_f32_16x16x32_bf16 v[24:27], v[166:169], v[206:209], v[24:27]
	v_mfma_f32_16x16x32_bf16 v[12:15], v[142:145], v[218:221], v[12:15]
	v_mfma_f32_16x16x32_bf16 v[8:11], v[166:169], v[218:221], v[8:11]
	v_mfma_f32_16x16x32_bf16 v[60:63], v[162:165], v[178:181], v[60:63]
	v_mfma_f32_16x16x32_bf16 v[56:59], v[170:173], v[178:181], v[56:59]
	v_mfma_f32_16x16x32_bf16 v[44:47], v[162:165], v[186:189], v[44:47]
	v_mfma_f32_16x16x32_bf16 v[40:43], v[170:173], v[186:189], v[40:43]
	v_mfma_f32_16x16x32_bf16 v[28:31], v[162:165], v[214:217], v[28:31]
	v_mfma_f32_16x16x32_bf16 v[24:27], v[170:173], v[214:217], v[24:27]
	v_mfma_f32_16x16x32_bf16 v[12:15], v[162:165], v[222:225], v[12:15]
	v_mfma_f32_16x16x32_bf16 v[8:11], v[170:173], v[222:225], v[8:11]
	s_barrier
	s_add_u32 s38, s38, s88
	s_addc_u32 s39, s39, s89
	s_add_i32 s21, s21, s54
	v_lshl_add_u64 v[250:251], s[38:39], 0, v[130:131]
	s_mov_b32 m0, s21
	v_lshl_add_u64 v[252:253], s[38:39], 0, v[128:129]
	global_load_lds_dwordx4 v[250:251], off
	s_add_i32 m0, s21, 0x2000
	s_nop 0
	global_load_lds_dwordx4 v[252:253], off
	s_waitcnt vmcnt(6)
	s_barrier
	v_mfma_f32_16x16x32_bf16 v[52:55], v[226:229], v[174:177], v[52:55]
	v_mfma_f32_16x16x32_bf16 v[48:51], v[234:237], v[174:177], v[48:51]
	v_mfma_f32_16x16x32_bf16 v[36:39], v[226:229], v[182:185], v[36:39]
	v_mfma_f32_16x16x32_bf16 v[32:35], v[234:237], v[182:185], v[32:35]
	v_mfma_f32_16x16x32_bf16 v[20:23], v[226:229], v[206:209], v[20:23]
	v_mfma_f32_16x16x32_bf16 v[16:19], v[234:237], v[206:209], v[16:19]
	v_mfma_f32_16x16x32_bf16 v[4:7], v[226:229], v[218:221], v[4:7]
	v_mfma_f32_16x16x32_bf16 v[0:3], v[234:237], v[218:221], v[0:3]
	v_mfma_f32_16x16x32_bf16 v[52:55], v[230:233], v[178:181], v[52:55]
	v_mfma_f32_16x16x32_bf16 v[48:51], v[238:241], v[178:181], v[48:51]
	v_mfma_f32_16x16x32_bf16 v[36:39], v[230:233], v[186:189], v[36:39]
	v_mfma_f32_16x16x32_bf16 v[32:35], v[238:241], v[186:189], v[32:35]
	v_mfma_f32_16x16x32_bf16 v[20:23], v[230:233], v[214:217], v[20:23]
	v_mfma_f32_16x16x32_bf16 v[16:19], v[238:241], v[214:217], v[16:19]
	v_mfma_f32_16x16x32_bf16 v[4:7], v[230:233], v[222:225], v[4:7]
	v_mfma_f32_16x16x32_bf16 v[0:3], v[238:241], v[222:225], v[0:3]
	s_add_i32 s21, 0, 0x18000
	v_add_u32_e32 v140, s21, v154
	s_barrier
	ds_read_b128 v[142:145], v140
	ds_read_b128 v[162:165], v140 offset:1024
	ds_read_b128 v[166:169], v140 offset:2048
	ds_read_b128 v[170:173], v140 offset:3072
	s_add_u32 s2, s2, s88
	s_addc_u32 s3, s3, s89
	s_mov_b32 m0, s35
	v_lshl_add_u64 v[226:227], s[2:3], 0, v[130:131]
	ds_read_b128 v[174:177], v155 offset:32768
	ds_read_b128 v[178:181], v155 offset:33792
	ds_read_b128 v[182:185], v155 offset:34816
	ds_read_b128 v[186:189], v155 offset:35840
	ds_read_b128 v[206:209], v155 offset:36864
	ds_read_b128 v[214:217], v155 offset:37888
	ds_read_b128 v[218:221], v155 offset:38912
	ds_read_b128 v[222:225], v155 offset:39936
	global_load_lds_dwordx4 v[226:227], off
	v_lshl_add_u64 v[226:227], s[2:3], 0, v[128:129]
	s_mov_b32 m0, s44
	s_nop 0
	global_load_lds_dwordx4 v[226:227], off
	s_waitcnt lgkmcnt(8)
	s_barrier
	s_waitcnt lgkmcnt(0)
	s_waitcnt lgkmcnt(0)
	v_mfma_f32_16x16x32_bf16 v[124:127], v[142:145], v[174:177], v[124:127]
	v_mfma_f32_16x16x32_bf16 v[120:123], v[166:169], v[174:177], v[120:123]
	v_mfma_f32_16x16x32_bf16 v[108:111], v[142:145], v[182:185], v[108:111]
	v_mfma_f32_16x16x32_bf16 v[104:107], v[166:169], v[182:185], v[104:107]
	v_mfma_f32_16x16x32_bf16 v[92:95], v[142:145], v[206:209], v[92:95]
	v_mfma_f32_16x16x32_bf16 v[88:91], v[166:169], v[206:209], v[88:91]
	v_mfma_f32_16x16x32_bf16 v[76:79], v[142:145], v[218:221], v[76:79]
	v_mfma_f32_16x16x32_bf16 v[72:75], v[166:169], v[218:221], v[72:75]
	v_mfma_f32_16x16x32_bf16 v[124:127], v[162:165], v[178:181], v[124:127]
	v_mfma_f32_16x16x32_bf16 v[120:123], v[170:173], v[178:181], v[120:123]
	v_mfma_f32_16x16x32_bf16 v[108:111], v[162:165], v[186:189], v[108:111]
	v_mfma_f32_16x16x32_bf16 v[104:107], v[170:173], v[186:189], v[104:107]
	v_mfma_f32_16x16x32_bf16 v[92:95], v[162:165], v[214:217], v[92:95]
	v_mfma_f32_16x16x32_bf16 v[88:91], v[170:173], v[214:217], v[88:91]
	v_mfma_f32_16x16x32_bf16 v[76:79], v[162:165], v[222:225], v[76:79]
	v_mfma_f32_16x16x32_bf16 v[72:75], v[170:173], v[222:225], v[72:75]
	s_barrier
	s_add_i32 s2, 0, 0x1c000
	s_add_i32 s3, s21, s54
	v_add_u32_e32 v140, s2, v154
	v_lshl_add_u64 v[242:243], v[242:243], 0, s[50:51]
	s_mov_b32 m0, s3
	ds_read_b128 v[226:229], v140
	ds_read_b128 v[230:233], v140 offset:1024
	ds_read_b128 v[234:237], v140 offset:2048
	ds_read_b128 v[238:241], v140 offset:3072
	global_load_lds_dwordx4 v[242:243], off
	v_lshl_add_u64 v[242:243], v[244:245], 0, s[50:51]
	s_add_i32 m0, s3, 0x2000
	s_nop 0
	global_load_lds_dwordx4 v[242:243], off
	s_barrier
	s_waitcnt lgkmcnt(0)
	s_waitcnt lgkmcnt(0)
	v_mfma_f32_16x16x32_bf16 v[116:119], v[226:229], v[174:177], v[116:119]
	v_mfma_f32_16x16x32_bf16 v[112:115], v[234:237], v[174:177], v[112:115]
	v_mfma_f32_16x16x32_bf16 v[100:103], v[226:229], v[182:185], v[100:103]
	v_mfma_f32_16x16x32_bf16 v[96:99], v[234:237], v[182:185], v[96:99]
	v_mfma_f32_16x16x32_bf16 v[84:87], v[226:229], v[206:209], v[84:87]
	v_mfma_f32_16x16x32_bf16 v[80:83], v[234:237], v[206:209], v[80:83]
	v_mfma_f32_16x16x32_bf16 v[68:71], v[226:229], v[218:221], v[68:71]
	v_mfma_f32_16x16x32_bf16 v[64:67], v[234:237], v[218:221], v[64:67]
	v_mfma_f32_16x16x32_bf16 v[116:119], v[230:233], v[178:181], v[116:119]
	v_mfma_f32_16x16x32_bf16 v[112:115], v[238:241], v[178:181], v[112:115]
	v_mfma_f32_16x16x32_bf16 v[100:103], v[230:233], v[186:189], v[100:103]
	v_mfma_f32_16x16x32_bf16 v[96:99], v[238:241], v[186:189], v[96:99]
	v_mfma_f32_16x16x32_bf16 v[84:87], v[230:233], v[214:217], v[84:87]
	v_mfma_f32_16x16x32_bf16 v[80:83], v[238:241], v[214:217], v[80:83]
	v_mfma_f32_16x16x32_bf16 v[68:71], v[230:233], v[222:225], v[68:71]
	v_mfma_f32_16x16x32_bf16 v[64:67], v[238:241], v[222:225], v[64:67]
	s_mov_b32 m0, s82
	v_lshl_add_u64 v[242:243], v[246:247], 0, s[50:51]
	s_barrier
	ds_read_b128 v[174:177], v155 offset:49152
	ds_read_b128 v[178:181], v155 offset:50176
	ds_read_b128 v[182:185], v155 offset:51200
	ds_read_b128 v[186:189], v155 offset:52224
	ds_read_b128 v[206:209], v155 offset:53248
	ds_read_b128 v[214:217], v155 offset:54272
	ds_read_b128 v[218:221], v155 offset:55296
	ds_read_b128 v[222:225], v155 offset:56320
	global_load_lds_dwordx4 v[242:243], off
	v_lshl_add_u64 v[242:243], v[248:249], 0, s[50:51]
	s_mov_b32 m0, s83
	s_nop 0
	global_load_lds_dwordx4 v[242:243], off
	s_barrier
	s_waitcnt lgkmcnt(0)
	s_waitcnt lgkmcnt(0)
	v_mfma_f32_16x16x32_bf16 v[60:63], v[142:145], v[174:177], v[60:63]
	v_mfma_f32_16x16x32_bf16 v[56:59], v[166:169], v[174:177], v[56:59]
	v_mfma_f32_16x16x32_bf16 v[44:47], v[142:145], v[182:185], v[44:47]
	v_mfma_f32_16x16x32_bf16 v[40:43], v[166:169], v[182:185], v[40:43]
	v_mfma_f32_16x16x32_bf16 v[28:31], v[142:145], v[206:209], v[28:31]
	v_mfma_f32_16x16x32_bf16 v[24:27], v[166:169], v[206:209], v[24:27]
	v_mfma_f32_16x16x32_bf16 v[12:15], v[142:145], v[218:221], v[12:15]
	v_mfma_f32_16x16x32_bf16 v[8:11], v[166:169], v[218:221], v[8:11]
	v_mfma_f32_16x16x32_bf16 v[60:63], v[162:165], v[178:181], v[60:63]
	v_mfma_f32_16x16x32_bf16 v[56:59], v[170:173], v[178:181], v[56:59]
	v_mfma_f32_16x16x32_bf16 v[44:47], v[162:165], v[186:189], v[44:47]
	v_mfma_f32_16x16x32_bf16 v[40:43], v[170:173], v[186:189], v[40:43]
	v_mfma_f32_16x16x32_bf16 v[28:31], v[162:165], v[214:217], v[28:31]
	v_mfma_f32_16x16x32_bf16 v[24:27], v[170:173], v[214:217], v[24:27]
	v_mfma_f32_16x16x32_bf16 v[12:15], v[162:165], v[222:225], v[12:15]
	v_mfma_f32_16x16x32_bf16 v[8:11], v[170:173], v[222:225], v[8:11]
	s_barrier
	s_add_i32 s2, s2, s54
	v_lshl_add_u64 v[142:143], v[250:251], 0, s[50:51]
	s_mov_b32 m0, s2
	s_nop 0
	global_load_lds_dwordx4 v[142:143], off
	v_lshl_add_u64 v[142:143], v[252:253], 0, s[50:51]
	s_add_i32 m0, s2, 0x2000
	s_nop 0
	global_load_lds_dwordx4 v[142:143], off
	s_waitcnt vmcnt(6)
	s_barrier
	v_mfma_f32_16x16x32_bf16 v[52:55], v[226:229], v[174:177], v[52:55]
	v_mfma_f32_16x16x32_bf16 v[48:51], v[234:237], v[174:177], v[48:51]
	v_mfma_f32_16x16x32_bf16 v[36:39], v[226:229], v[182:185], v[36:39]
	v_mfma_f32_16x16x32_bf16 v[32:35], v[234:237], v[182:185], v[32:35]
	v_mfma_f32_16x16x32_bf16 v[20:23], v[226:229], v[206:209], v[20:23]
	v_mfma_f32_16x16x32_bf16 v[16:19], v[234:237], v[206:209], v[16:19]
	v_mfma_f32_16x16x32_bf16 v[4:7], v[226:229], v[218:221], v[4:7]
	v_mfma_f32_16x16x32_bf16 v[0:3], v[234:237], v[218:221], v[0:3]
	v_mfma_f32_16x16x32_bf16 v[52:55], v[230:233], v[178:181], v[52:55]
	v_mfma_f32_16x16x32_bf16 v[48:51], v[238:241], v[178:181], v[48:51]
	v_mfma_f32_16x16x32_bf16 v[36:39], v[230:233], v[186:189], v[36:39]
	v_mfma_f32_16x16x32_bf16 v[32:35], v[238:241], v[186:189], v[32:35]
	v_mfma_f32_16x16x32_bf16 v[20:23], v[230:233], v[214:217], v[20:23]
	v_mfma_f32_16x16x32_bf16 v[16:19], v[238:241], v[214:217], v[16:19]
	v_mfma_f32_16x16x32_bf16 v[4:7], v[230:233], v[222:225], v[4:7]
	v_mfma_f32_16x16x32_bf16 v[0:3], v[238:241], v[222:225], v[0:3]
	s_add_u32 s10, s10, 0x100
	s_addc_u32 s40, s40, 0
	s_add_u32 s6, s6, 0x100
	s_addc_u32 s7, s7, 0
	s_cmp_ge_i32 s41, s66
	s_mov_b32 s2, s41
	s_barrier
	s_cbranch_scc0 .LBB0_197

.LBB0_270:
	v_lshl_add_u64 v[0:1], s[40:41], 0, v[156:157]
	v_mov_b32_e32 v129, v157
	v_lshl_add_u64 v[4:5], s[2:3], 0, v[156:157]
	v_lshl_add_u64 v[6:7], s[2:3], 0, v[128:129]
	s_lshl_b32 s2, s19, 5
	s_add_i32 m0, s25, 0x18000
	v_lshl_add_u64 v[0:1], v[0:1], 0, s[50:51]
	s_and_b32 s19, s2, 0x60
	s_waitcnt vmcnt(4)
	s_barrier
	global_load_lds_dwordx4 v[0:1], off
	s_add_i32 m0, s25, 0x1a000
	v_lshl_add_u64 v[2:3], s[40:41], 0, v[128:129]
	s_add_u32 s2, s26, 0x1a4a4080
	v_lshl_add_u64 v[0:1], v[2:3], 0, s[50:51]
	s_addc_u32 s3, s27, 0
	s_add_i32 s45, s25, 0x8000
	global_load_lds_dwordx4 v[0:1], off
	v_lshl_add_u64 v[0:1], s[2:3], 0, v[156:157]
	s_mov_b32 m0, s45
	s_add_i32 s48, s25, 0xa000
	global_load_lds_dwordx4 v[0:1], off
	v_lshl_add_u64 v[0:1], s[2:3], 0, v[128:129]
	s_mov_b32 m0, s48
	v_mov_b32_e32 v127, 0
	global_load_lds_dwordx4 v[0:1], off
	s_add_i32 m0, s25, 0x1c000
	v_lshl_add_u64 v[0:1], v[4:5], 0, s[50:51]
	global_load_lds_dwordx4 v[0:1], off
	v_lshl_add_u64 v[0:1], v[6:7], 0, s[50:51]
	s_add_i32 m0, s25, 0x1e000
	v_lshl_or_b32 v134, s42, 6, v149
	global_load_lds_dwordx4 v[0:1], off
	s_waitcnt vmcnt(6)
	s_cmp_lt_i32 s6, 64
	v_mov_b32_e32 v126, v127
	v_mov_b32_e32 v125, v127
	v_mov_b32_e32 v124, v127
	v_mov_b32_e32 v123, v127
	v_mov_b32_e32 v122, v127
	v_mov_b32_e32 v121, v127
	v_mov_b32_e32 v120, v127
	v_mov_b32_e32 v111, v127
	v_mov_b32_e32 v110, v127
	v_mov_b32_e32 v109, v127
	v_mov_b32_e32 v108, v127
	v_mov_b32_e32 v107, v127
	v_mov_b32_e32 v106, v127
	v_mov_b32_e32 v105, v127
	v_mov_b32_e32 v104, v127
	v_mov_b32_e32 v95, v127
	v_mov_b32_e32 v94, v127
	v_mov_b32_e32 v93, v127
	v_mov_b32_e32 v92, v127
	v_mov_b32_e32 v91, v127
	v_mov_b32_e32 v90, v127
	v_mov_b32_e32 v89, v127
	v_mov_b32_e32 v88, v127
	v_mov_b32_e32 v79, v127
	v_mov_b32_e32 v78, v127
	v_mov_b32_e32 v77, v127
	v_mov_b32_e32 v76, v127
	v_mov_b32_e32 v75, v127
	v_mov_b32_e32 v74, v127
	v_mov_b32_e32 v73, v127
	v_mov_b32_e32 v72, v127
	v_mov_b32_e32 v119, v127
	v_mov_b32_e32 v118, v127
	v_mov_b32_e32 v117, v127
	v_mov_b32_e32 v116, v127
	v_mov_b32_e32 v115, v127
	v_mov_b32_e32 v114, v127
	v_mov_b32_e32 v113, v127
	v_mov_b32_e32 v112, v127
	v_mov_b32_e32 v103, v127
	v_mov_b32_e32 v102, v127
	v_mov_b32_e32 v101, v127
	v_mov_b32_e32 v100, v127
	v_mov_b32_e32 v99, v127
	v_mov_b32_e32 v98, v127
	v_mov_b32_e32 v97, v127
	v_mov_b32_e32 v96, v127
	v_mov_b32_e32 v87, v127
	v_mov_b32_e32 v86, v127
	v_mov_b32_e32 v85, v127
	v_mov_b32_e32 v84, v127
	v_mov_b32_e32 v83, v127
	v_mov_b32_e32 v82, v127
	v_mov_b32_e32 v81, v127
	v_mov_b32_e32 v80, v127
	v_mov_b32_e32 v71, v127
	v_mov_b32_e32 v70, v127
	v_mov_b32_e32 v69, v127
	v_mov_b32_e32 v68, v127
	v_mov_b32_e32 v67, v127
	v_mov_b32_e32 v66, v127
	v_mov_b32_e32 v65, v127
	v_mov_b32_e32 v64, v127
	v_mov_b32_e32 v63, v127
	v_mov_b32_e32 v62, v127
	v_mov_b32_e32 v61, v127
	v_mov_b32_e32 v60, v127
	v_mov_b32_e32 v59, v127
	v_mov_b32_e32 v58, v127
	v_mov_b32_e32 v57, v127
	v_mov_b32_e32 v56, v127
	v_mov_b32_e32 v47, v127
	v_mov_b32_e32 v46, v127
	v_mov_b32_e32 v45, v127
	v_mov_b32_e32 v44, v127
	v_mov_b32_e32 v43, v127
	v_mov_b32_e32 v42, v127
	v_mov_b32_e32 v41, v127
	v_mov_b32_e32 v40, v127
	v_mov_b32_e32 v31, v127
	v_mov_b32_e32 v30, v127
	v_mov_b32_e32 v29, v127
	v_mov_b32_e32 v28, v127
	v_mov_b32_e32 v27, v127
	v_mov_b32_e32 v26, v127
	v_mov_b32_e32 v25, v127
	v_mov_b32_e32 v24, v127
	v_mov_b32_e32 v15, v127
	v_mov_b32_e32 v14, v127
	v_mov_b32_e32 v13, v127
	v_mov_b32_e32 v12, v127
	v_mov_b32_e32 v11, v127
	v_mov_b32_e32 v10, v127
	v_mov_b32_e32 v9, v127
	v_mov_b32_e32 v8, v127
	v_mov_b32_e32 v55, v127
	v_mov_b32_e32 v54, v127
	v_mov_b32_e32 v53, v127
	v_mov_b32_e32 v52, v127
	v_mov_b32_e32 v51, v127
	v_mov_b32_e32 v50, v127
	v_mov_b32_e32 v49, v127
	v_mov_b32_e32 v48, v127
	v_mov_b32_e32 v39, v127
	v_mov_b32_e32 v38, v127
	v_mov_b32_e32 v37, v127
	v_mov_b32_e32 v36, v127
	v_mov_b32_e32 v35, v127
	v_mov_b32_e32 v34, v127
	v_mov_b32_e32 v33, v127
	v_mov_b32_e32 v32, v127
	v_mov_b32_e32 v23, v127
	v_mov_b32_e32 v22, v127
	v_mov_b32_e32 v21, v127
	v_mov_b32_e32 v20, v127
	v_mov_b32_e32 v19, v127
	v_mov_b32_e32 v18, v127
	v_mov_b32_e32 v17, v127
	v_mov_b32_e32 v16, v127
	v_mov_b32_e32 v7, v127
	v_mov_b32_e32 v6, v127
	v_mov_b32_e32 v5, v127
	v_mov_b32_e32 v4, v127
	v_mov_b32_e32 v3, v127
	v_mov_b32_e32 v2, v127
	v_mov_b32_e32 v1, v127
	v_mov_b32_e32 v0, v127
	s_barrier
	s_cbranch_scc1 .LBB0_273
	s_lshr_b32 s2, s7, 26
	s_add_i32 s2, s6, s2
	s_ashr_i32 s49, s2, 6
	v_lshlrev_b32_e32 v0, 6, v134
	s_movk_i32 s2, 0x3c0
	v_lshlrev_b32_e32 v1, 2, v134
	s_add_i32 s53, s49, -2
	v_and_or_b32 v0, v0, s2, v147
	s_lshl_b32 s2, s42, 13
	v_and_b32_e32 v1, 32, v1
	v_bitop3_b32 v2, v0, s2, v1 bitop3:0xde
	s_add_u32 s2, s26, s36
	v_add_u32_e32 v0, v132, v133
	s_addc_u32 s3, s27, s37
	v_add_lshl_u32 v0, v0, v146, 1
	v_mov_b32_e32 v1, v157
	v_lshl_add_u64 v[132:133], s[2:3], 0, v[0:1]
	v_lshl_or_b32 v135, s19, 7, v148
	v_lshl_add_u64 v[130:131], s[2:3], 0, v[128:129]
	s_mov_b32 s2, 0
	s_mov_b64 s[6:7], 0x1a4a4080
	v_add_u32_e32 v136, 0, v2
	s_add_i32 s54, s2, 2
	s_add_u32 s3, s6, 0xe5b5c080
	s_addc_u32 s21, s7, -1
	s_cmp_lg_u32 s53, s2
	s_cselect_b32 s42, s3, 0
	s_cselect_b32 s21, s21, 0
	s_add_u32 s2, s38, s42
	s_addc_u32 s3, s39, s21
	s_add_i32 s55, 0, 0x10000
	v_add_u32_e32 v137, s55, v135
	ds_read_b128 v[142:145], v137
	ds_read_b128 v[146:149], v137 offset:1024
	ds_read_b128 v[150:153], v137 offset:2048
	ds_read_b128 v[162:165], v137 offset:3072
	s_add_u32 s42, s40, s42
	s_addc_u32 s43, s41, s21
	v_lshl_add_u64 v[138:139], v[132:133], 0, s[6:7]
	s_add_i32 m0, s25, 0xc000
	ds_read_b128 v[166:169], v136
	ds_read_b128 v[170:173], v136 offset:1024
	ds_read_b128 v[174:177], v136 offset:2048
	ds_read_b128 v[178:181], v136 offset:3072
	ds_read_b128 v[182:185], v136 offset:4096
	ds_read_b128 v[186:189], v136 offset:5120
	ds_read_b128 v[206:209], v136 offset:6144
	ds_read_b128 v[214:217], v136 offset:7168
	global_load_lds_dwordx4 v[138:139], off
	v_lshl_add_u64 v[138:139], v[130:131], 0, s[6:7]
	s_add_i32 m0, s25, 0xe000
	s_nop 0
	global_load_lds_dwordx4 v[138:139], off
	s_waitcnt lgkmcnt(8)
	s_barrier
	s_waitcnt lgkmcnt(0)
	s_waitcnt lgkmcnt(0)
	v_mfma_f32_16x16x32_bf16 v[124:127], v[142:145], v[166:169], 0
	v_mfma_f32_16x16x32_bf16 v[120:123], v[150:153], v[166:169], 0
	v_mfma_f32_16x16x32_bf16 v[108:111], v[142:145], v[174:177], 0
	v_mfma_f32_16x16x32_bf16 v[104:107], v[150:153], v[174:177], 0
	v_mfma_f32_16x16x32_bf16 v[92:95], v[142:145], v[182:185], 0
	v_mfma_f32_16x16x32_bf16 v[88:91], v[150:153], v[182:185], 0
	v_mfma_f32_16x16x32_bf16 v[76:79], v[142:145], v[206:209], 0
	v_mfma_f32_16x16x32_bf16 v[72:75], v[150:153], v[206:209], 0
	v_mfma_f32_16x16x32_bf16 v[124:127], v[146:149], v[170:173], v[124:127]
	v_mfma_f32_16x16x32_bf16 v[120:123], v[162:165], v[170:173], v[120:123]
	v_mfma_f32_16x16x32_bf16 v[108:111], v[146:149], v[178:181], v[108:111]
	v_mfma_f32_16x16x32_bf16 v[104:107], v[162:165], v[178:181], v[104:107]
	v_mfma_f32_16x16x32_bf16 v[92:95], v[146:149], v[186:189], v[92:95]
	v_mfma_f32_16x16x32_bf16 v[88:91], v[162:165], v[186:189], v[88:91]
	v_mfma_f32_16x16x32_bf16 v[76:79], v[146:149], v[214:217], v[76:79]
	v_mfma_f32_16x16x32_bf16 v[72:75], v[162:165], v[214:217], v[72:75]
	s_barrier
	s_add_i32 s21, 0, 0x14000
	s_add_i32 s55, s55, s24
	v_add_u32_e32 v137, s21, v135
	v_lshl_add_u64 v[138:139], s[42:43], 0, v[156:157]
	s_mov_b32 m0, s55
	ds_read_b128 v[218:221], v137
	ds_read_b128 v[222:225], v137 offset:1024
	ds_read_b128 v[226:229], v137 offset:2048
	ds_read_b128 v[230:233], v137 offset:3072
	global_load_lds_dwordx4 v[138:139], off
	v_lshl_add_u64 v[154:155], s[42:43], 0, v[128:129]
	s_add_i32 m0, s55, 0x2000
	s_nop 0
	global_load_lds_dwordx4 v[154:155], off
	s_barrier
	s_waitcnt lgkmcnt(0)
	s_waitcnt lgkmcnt(0)
	v_mfma_f32_16x16x32_bf16 v[116:119], v[218:221], v[166:169], 0
	v_mfma_f32_16x16x32_bf16 v[112:115], v[226:229], v[166:169], 0
	v_mfma_f32_16x16x32_bf16 v[100:103], v[218:221], v[174:177], 0
	v_mfma_f32_16x16x32_bf16 v[96:99], v[226:229], v[174:177], 0
	v_mfma_f32_16x16x32_bf16 v[84:87], v[218:221], v[182:185], 0
	v_mfma_f32_16x16x32_bf16 v[80:83], v[226:229], v[182:185], 0
	v_mfma_f32_16x16x32_bf16 v[68:71], v[218:221], v[206:209], 0
	v_mfma_f32_16x16x32_bf16 v[64:67], v[226:229], v[206:209], 0
	v_mfma_f32_16x16x32_bf16 v[116:119], v[222:225], v[170:173], v[116:119]
	v_mfma_f32_16x16x32_bf16 v[112:115], v[230:233], v[170:173], v[112:115]
	v_mfma_f32_16x16x32_bf16 v[100:103], v[222:225], v[178:181], v[100:103]
	v_mfma_f32_16x16x32_bf16 v[96:99], v[230:233], v[178:181], v[96:99]
	v_mfma_f32_16x16x32_bf16 v[84:87], v[222:225], v[186:189], v[84:87]
	v_mfma_f32_16x16x32_bf16 v[80:83], v[230:233], v[186:189], v[80:83]
	v_mfma_f32_16x16x32_bf16 v[68:71], v[222:225], v[214:217], v[68:71]
	v_mfma_f32_16x16x32_bf16 v[64:67], v[230:233], v[214:217], v[64:67]
	s_mov_b32 m0, s25
	v_lshl_add_u64 v[234:235], s[2:3], 0, v[156:157]
	s_barrier
	ds_read_b128 v[166:169], v136 offset:16384
	ds_read_b128 v[170:173], v136 offset:17408
	ds_read_b128 v[174:177], v136 offset:18432
	ds_read_b128 v[178:181], v136 offset:19456
	ds_read_b128 v[182:185], v136 offset:20480
	ds_read_b128 v[186:189], v136 offset:21504
	ds_read_b128 v[206:209], v136 offset:22528
	ds_read_b128 v[214:217], v136 offset:23552
	global_load_lds_dwordx4 v[234:235], off
	v_lshl_add_u64 v[236:237], s[2:3], 0, v[128:129]
	s_mov_b32 m0, s34
	s_nop 0
	global_load_lds_dwordx4 v[236:237], off
	s_barrier
	s_waitcnt lgkmcnt(0)
	s_waitcnt lgkmcnt(0)
	v_mfma_f32_16x16x32_bf16 v[60:63], v[142:145], v[166:169], 0
	v_mfma_f32_16x16x32_bf16 v[56:59], v[150:153], v[166:169], 0
	v_mfma_f32_16x16x32_bf16 v[44:47], v[142:145], v[174:177], 0
	v_mfma_f32_16x16x32_bf16 v[40:43], v[150:153], v[174:177], 0
	v_mfma_f32_16x16x32_bf16 v[28:31], v[142:145], v[182:185], 0
	v_mfma_f32_16x16x32_bf16 v[24:27], v[150:153], v[182:185], 0
	v_mfma_f32_16x16x32_bf16 v[12:15], v[142:145], v[206:209], 0
	v_mfma_f32_16x16x32_bf16 v[8:11], v[150:153], v[206:209], 0
	v_mfma_f32_16x16x32_bf16 v[60:63], v[146:149], v[170:173], v[60:63]
	v_mfma_f32_16x16x32_bf16 v[56:59], v[162:165], v[170:173], v[56:59]
	v_mfma_f32_16x16x32_bf16 v[44:47], v[146:149], v[178:181], v[44:47]
	v_mfma_f32_16x16x32_bf16 v[40:43], v[162:165], v[178:181], v[40:43]
	v_mfma_f32_16x16x32_bf16 v[28:31], v[146:149], v[186:189], v[28:31]
	v_mfma_f32_16x16x32_bf16 v[24:27], v[162:165], v[186:189], v[24:27]
	v_mfma_f32_16x16x32_bf16 v[12:15], v[146:149], v[214:217], v[12:15]
	v_mfma_f32_16x16x32_bf16 v[8:11], v[162:165], v[214:217], v[8:11]
	s_barrier
	s_add_u32 s42, s42, s36
	s_addc_u32 s43, s43, s37
	s_add_i32 s21, s21, s24
	v_lshl_add_u64 v[238:239], s[42:43], 0, v[156:157]
	s_mov_b32 m0, s21
	v_lshl_add_u64 v[240:241], s[42:43], 0, v[128:129]
	global_load_lds_dwordx4 v[238:239], off
	s_add_i32 m0, s21, 0x2000
	s_nop 0
	global_load_lds_dwordx4 v[240:241], off
	s_waitcnt vmcnt(6)
	s_barrier
	v_mfma_f32_16x16x32_bf16 v[52:55], v[218:221], v[166:169], 0
	v_mfma_f32_16x16x32_bf16 v[48:51], v[226:229], v[166:169], 0
	v_mfma_f32_16x16x32_bf16 v[36:39], v[218:221], v[174:177], 0
	v_mfma_f32_16x16x32_bf16 v[32:35], v[226:229], v[174:177], 0
	v_mfma_f32_16x16x32_bf16 v[20:23], v[218:221], v[182:185], 0
	v_mfma_f32_16x16x32_bf16 v[16:19], v[226:229], v[182:185], 0
	v_mfma_f32_16x16x32_bf16 v[4:7], v[218:221], v[206:209], 0
	v_mfma_f32_16x16x32_bf16 v[0:3], v[226:229], v[206:209], 0
	v_mfma_f32_16x16x32_bf16 v[52:55], v[222:225], v[170:173], v[52:55]
	v_mfma_f32_16x16x32_bf16 v[48:51], v[230:233], v[170:173], v[48:51]
	v_mfma_f32_16x16x32_bf16 v[36:39], v[222:225], v[178:181], v[36:39]
	v_mfma_f32_16x16x32_bf16 v[32:35], v[230:233], v[178:181], v[32:35]
	v_mfma_f32_16x16x32_bf16 v[20:23], v[222:225], v[186:189], v[20:23]
	v_mfma_f32_16x16x32_bf16 v[16:19], v[230:233], v[186:189], v[16:19]
	v_mfma_f32_16x16x32_bf16 v[4:7], v[222:225], v[214:217], v[4:7]
	v_mfma_f32_16x16x32_bf16 v[0:3], v[230:233], v[214:217], v[0:3]
	s_add_i32 s21, 0, 0x18000
	v_add_u32_e32 v137, s21, v135
	s_barrier
	ds_read_b128 v[142:145], v137
	ds_read_b128 v[146:149], v137 offset:1024
	ds_read_b128 v[150:153], v137 offset:2048
	ds_read_b128 v[162:165], v137 offset:3072
	s_add_u32 s2, s2, s36
	s_addc_u32 s3, s3, s37
	s_mov_b32 m0, s35
	v_lshl_add_u64 v[218:219], s[2:3], 0, v[156:157]
	ds_read_b128 v[166:169], v136 offset:32768
	ds_read_b128 v[170:173], v136 offset:33792
	ds_read_b128 v[174:177], v136 offset:34816
	ds_read_b128 v[178:181], v136 offset:35840
	ds_read_b128 v[182:185], v136 offset:36864
	ds_read_b128 v[186:189], v136 offset:37888
	ds_read_b128 v[206:209], v136 offset:38912
	ds_read_b128 v[214:217], v136 offset:39936
	global_load_lds_dwordx4 v[218:219], off
	v_lshl_add_u64 v[218:219], s[2:3], 0, v[128:129]
	s_mov_b32 m0, s44
	s_nop 0
	global_load_lds_dwordx4 v[218:219], off
	s_waitcnt lgkmcnt(8)
	s_barrier
	s_waitcnt lgkmcnt(0)
	s_waitcnt lgkmcnt(0)
	v_mfma_f32_16x16x32_bf16 v[124:127], v[142:145], v[166:169], v[124:127]
	v_mfma_f32_16x16x32_bf16 v[120:123], v[150:153], v[166:169], v[120:123]
	v_mfma_f32_16x16x32_bf16 v[108:111], v[142:145], v[174:177], v[108:111]
	v_mfma_f32_16x16x32_bf16 v[104:107], v[150:153], v[174:177], v[104:107]
	v_mfma_f32_16x16x32_bf16 v[92:95], v[142:145], v[182:185], v[92:95]
	v_mfma_f32_16x16x32_bf16 v[88:91], v[150:153], v[182:185], v[88:91]
	v_mfma_f32_16x16x32_bf16 v[76:79], v[142:145], v[206:209], v[76:79]
	v_mfma_f32_16x16x32_bf16 v[72:75], v[150:153], v[206:209], v[72:75]
	v_mfma_f32_16x16x32_bf16 v[124:127], v[146:149], v[170:173], v[124:127]
	v_mfma_f32_16x16x32_bf16 v[120:123], v[162:165], v[170:173], v[120:123]
	v_mfma_f32_16x16x32_bf16 v[108:111], v[146:149], v[178:181], v[108:111]
	v_mfma_f32_16x16x32_bf16 v[104:107], v[162:165], v[178:181], v[104:107]
	v_mfma_f32_16x16x32_bf16 v[92:95], v[146:149], v[186:189], v[92:95]
	v_mfma_f32_16x16x32_bf16 v[88:91], v[162:165], v[186:189], v[88:91]
	v_mfma_f32_16x16x32_bf16 v[76:79], v[146:149], v[214:217], v[76:79]
	v_mfma_f32_16x16x32_bf16 v[72:75], v[162:165], v[214:217], v[72:75]
	s_barrier
	s_add_i32 s2, 0, 0x1c000
	s_add_i32 s3, s21, s24
	v_add_u32_e32 v137, s2, v135
	v_lshl_add_u64 v[138:139], v[138:139], 0, s[50:51]
	s_mov_b32 m0, s3
	ds_read_b128 v[218:221], v137
	ds_read_b128 v[222:225], v137 offset:1024
	ds_read_b128 v[226:229], v137 offset:2048
	ds_read_b128 v[230:233], v137 offset:3072
	global_load_lds_dwordx4 v[138:139], off
	v_lshl_add_u64 v[138:139], v[154:155], 0, s[50:51]
	s_add_i32 m0, s3, 0x2000
	s_nop 0
	global_load_lds_dwordx4 v[138:139], off
	s_barrier
	s_waitcnt lgkmcnt(0)
	s_waitcnt lgkmcnt(0)
	v_mfma_f32_16x16x32_bf16 v[116:119], v[218:221], v[166:169], v[116:119]
	v_mfma_f32_16x16x32_bf16 v[112:115], v[226:229], v[166:169], v[112:115]
	v_mfma_f32_16x16x32_bf16 v[100:103], v[218:221], v[174:177], v[100:103]
	v_mfma_f32_16x16x32_bf16 v[96:99], v[226:229], v[174:177], v[96:99]
	v_mfma_f32_16x16x32_bf16 v[84:87], v[218:221], v[182:185], v[84:87]
	v_mfma_f32_16x16x32_bf16 v[80:83], v[226:229], v[182:185], v[80:83]
	v_mfma_f32_16x16x32_bf16 v[68:71], v[218:221], v[206:209], v[68:71]
	v_mfma_f32_16x16x32_bf16 v[64:67], v[226:229], v[206:209], v[64:67]
	v_mfma_f32_16x16x32_bf16 v[116:119], v[222:225], v[170:173], v[116:119]
	v_mfma_f32_16x16x32_bf16 v[112:115], v[230:233], v[170:173], v[112:115]
	v_mfma_f32_16x16x32_bf16 v[100:103], v[222:225], v[178:181], v[100:103]
	v_mfma_f32_16x16x32_bf16 v[96:99], v[230:233], v[178:181], v[96:99]
	v_mfma_f32_16x16x32_bf16 v[84:87], v[222:225], v[186:189], v[84:87]
	v_mfma_f32_16x16x32_bf16 v[80:83], v[230:233], v[186:189], v[80:83]
	v_mfma_f32_16x16x32_bf16 v[68:71], v[222:225], v[214:217], v[68:71]
	v_mfma_f32_16x16x32_bf16 v[64:67], v[230:233], v[214:217], v[64:67]
	s_mov_b32 m0, s45
	v_lshl_add_u64 v[138:139], v[234:235], 0, s[50:51]
	s_barrier
	ds_read_b128 v[166:169], v136 offset:49152
	ds_read_b128 v[170:173], v136 offset:50176
	ds_read_b128 v[174:177], v136 offset:51200
	ds_read_b128 v[178:181], v136 offset:52224
	ds_read_b128 v[182:185], v136 offset:53248
	ds_read_b128 v[186:189], v136 offset:54272
	ds_read_b128 v[206:209], v136 offset:55296
	ds_read_b128 v[214:217], v136 offset:56320
	global_load_lds_dwordx4 v[138:139], off
	v_lshl_add_u64 v[138:139], v[236:237], 0, s[50:51]
	s_mov_b32 m0, s48
	s_nop 0
	global_load_lds_dwordx4 v[138:139], off
	s_barrier
	s_waitcnt lgkmcnt(0)
	s_waitcnt lgkmcnt(0)
	v_mfma_f32_16x16x32_bf16 v[60:63], v[142:145], v[166:169], v[60:63]
	v_mfma_f32_16x16x32_bf16 v[56:59], v[150:153], v[166:169], v[56:59]
	v_mfma_f32_16x16x32_bf16 v[44:47], v[142:145], v[174:177], v[44:47]
	v_mfma_f32_16x16x32_bf16 v[40:43], v[150:153], v[174:177], v[40:43]
	v_mfma_f32_16x16x32_bf16 v[28:31], v[142:145], v[182:185], v[28:31]
	v_mfma_f32_16x16x32_bf16 v[24:27], v[150:153], v[182:185], v[24:27]
	v_mfma_f32_16x16x32_bf16 v[12:15], v[142:145], v[206:209], v[12:15]
	v_mfma_f32_16x16x32_bf16 v[8:11], v[150:153], v[206:209], v[8:11]
	v_mfma_f32_16x16x32_bf16 v[60:63], v[146:149], v[170:173], v[60:63]
	v_mfma_f32_16x16x32_bf16 v[56:59], v[162:165], v[170:173], v[56:59]
	v_mfma_f32_16x16x32_bf16 v[44:47], v[146:149], v[178:181], v[44:47]
	v_mfma_f32_16x16x32_bf16 v[40:43], v[162:165], v[178:181], v[40:43]
	v_mfma_f32_16x16x32_bf16 v[28:31], v[146:149], v[186:189], v[28:31]
	v_mfma_f32_16x16x32_bf16 v[24:27], v[162:165], v[186:189], v[24:27]
	v_mfma_f32_16x16x32_bf16 v[12:15], v[146:149], v[214:217], v[12:15]
	v_mfma_f32_16x16x32_bf16 v[8:11], v[162:165], v[214:217], v[8:11]
	s_barrier
	s_add_i32 s2, s2, s24
	v_lshl_add_u64 v[138:139], v[238:239], 0, s[50:51]
	s_mov_b32 m0, s2
	s_nop 0
	global_load_lds_dwordx4 v[138:139], off
	v_lshl_add_u64 v[138:139], v[240:241], 0, s[50:51]
	s_add_i32 m0, s2, 0x2000
	s_nop 0
	global_load_lds_dwordx4 v[138:139], off
	s_waitcnt vmcnt(6)
	s_barrier
	v_mfma_f32_16x16x32_bf16 v[52:55], v[218:221], v[166:169], v[52:55]
	v_mfma_f32_16x16x32_bf16 v[48:51], v[226:229], v[166:169], v[48:51]
	v_mfma_f32_16x16x32_bf16 v[36:39], v[218:221], v[174:177], v[36:39]
	v_mfma_f32_16x16x32_bf16 v[32:35], v[226:229], v[174:177], v[32:35]
	v_mfma_f32_16x16x32_bf16 v[20:23], v[218:221], v[182:185], v[20:23]
	v_mfma_f32_16x16x32_bf16 v[16:19], v[226:229], v[182:185], v[16:19]
	v_mfma_f32_16x16x32_bf16 v[4:7], v[218:221], v[206:209], v[4:7]
	v_mfma_f32_16x16x32_bf16 v[0:3], v[226:229], v[206:209], v[0:3]
	v_mfma_f32_16x16x32_bf16 v[52:55], v[222:225], v[170:173], v[52:55]
	v_mfma_f32_16x16x32_bf16 v[48:51], v[230:233], v[170:173], v[48:51]
	v_mfma_f32_16x16x32_bf16 v[36:39], v[222:225], v[178:181], v[36:39]
	v_mfma_f32_16x16x32_bf16 v[32:35], v[230:233], v[178:181], v[32:35]
	v_mfma_f32_16x16x32_bf16 v[20:23], v[222:225], v[186:189], v[20:23]
	v_mfma_f32_16x16x32_bf16 v[16:19], v[230:233], v[186:189], v[16:19]
	v_mfma_f32_16x16x32_bf16 v[4:7], v[222:225], v[214:217], v[4:7]
	v_mfma_f32_16x16x32_bf16 v[0:3], v[230:233], v[214:217], v[0:3]
	s_add_u32 s6, s6, 0x100
	s_addc_u32 s7, s7, 0
	s_cmp_ge_i32 s54, s49
	s_mov_b32 s2, s54
	s_barrier
	s_cbranch_scc1 .Lpost_272
.LBB0_272:
	s_add_i32 s54, s2, 2
	s_add_u32 s3, s6, 0xe5b5c080
	s_addc_u32 s21, s7, -1
	s_cmp_lg_u32 s53, s2
	s_cselect_b32 s42, s3, 0
	s_cselect_b32 s21, s21, 0
	s_add_u32 s2, s38, s42
	s_addc_u32 s3, s39, s21
	s_add_i32 s55, 0, 0x10000
	v_add_u32_e32 v137, s55, v135
	ds_read_b128 v[142:145], v137
	ds_read_b128 v[146:149], v137 offset:1024
	ds_read_b128 v[150:153], v137 offset:2048
	ds_read_b128 v[162:165], v137 offset:3072
	s_add_u32 s42, s40, s42
	s_addc_u32 s43, s41, s21
	v_lshl_add_u64 v[138:139], v[132:133], 0, s[6:7]
	s_add_i32 m0, s25, 0xc000
	ds_read_b128 v[166:169], v136
	ds_read_b128 v[170:173], v136 offset:1024
	ds_read_b128 v[174:177], v136 offset:2048
	ds_read_b128 v[178:181], v136 offset:3072
	ds_read_b128 v[182:185], v136 offset:4096
	ds_read_b128 v[186:189], v136 offset:5120
	ds_read_b128 v[206:209], v136 offset:6144
	ds_read_b128 v[214:217], v136 offset:7168
	global_load_lds_dwordx4 v[138:139], off
	v_lshl_add_u64 v[138:139], v[130:131], 0, s[6:7]
	s_add_i32 m0, s25, 0xe000
	s_nop 0
	global_load_lds_dwordx4 v[138:139], off
	s_waitcnt lgkmcnt(8)
	s_barrier
	s_waitcnt lgkmcnt(0)
	s_waitcnt lgkmcnt(0)
	v_mfma_f32_16x16x32_bf16 v[124:127], v[142:145], v[166:169], v[124:127]
	v_mfma_f32_16x16x32_bf16 v[120:123], v[150:153], v[166:169], v[120:123]
	v_mfma_f32_16x16x32_bf16 v[108:111], v[142:145], v[174:177], v[108:111]
	v_mfma_f32_16x16x32_bf16 v[104:107], v[150:153], v[174:177], v[104:107]
	v_mfma_f32_16x16x32_bf16 v[92:95], v[142:145], v[182:185], v[92:95]
	v_mfma_f32_16x16x32_bf16 v[88:91], v[150:153], v[182:185], v[88:91]
	v_mfma_f32_16x16x32_bf16 v[76:79], v[142:145], v[206:209], v[76:79]
	v_mfma_f32_16x16x32_bf16 v[72:75], v[150:153], v[206:209], v[72:75]
	v_mfma_f32_16x16x32_bf16 v[124:127], v[146:149], v[170:173], v[124:127]
	v_mfma_f32_16x16x32_bf16 v[120:123], v[162:165], v[170:173], v[120:123]
	v_mfma_f32_16x16x32_bf16 v[108:111], v[146:149], v[178:181], v[108:111]
	v_mfma_f32_16x16x32_bf16 v[104:107], v[162:165], v[178:181], v[104:107]
	v_mfma_f32_16x16x32_bf16 v[92:95], v[146:149], v[186:189], v[92:95]
	v_mfma_f32_16x16x32_bf16 v[88:91], v[162:165], v[186:189], v[88:91]
	v_mfma_f32_16x16x32_bf16 v[76:79], v[146:149], v[214:217], v[76:79]
	v_mfma_f32_16x16x32_bf16 v[72:75], v[162:165], v[214:217], v[72:75]
	s_barrier
	s_add_i32 s21, 0, 0x14000
	s_add_i32 s55, s55, s24
	v_add_u32_e32 v137, s21, v135
	v_lshl_add_u64 v[138:139], s[42:43], 0, v[156:157]
	s_mov_b32 m0, s55
	ds_read_b128 v[218:221], v137
	ds_read_b128 v[222:225], v137 offset:1024
	ds_read_b128 v[226:229], v137 offset:2048
	ds_read_b128 v[230:233], v137 offset:3072
	global_load_lds_dwordx4 v[138:139], off
	v_lshl_add_u64 v[154:155], s[42:43], 0, v[128:129]
	s_add_i32 m0, s55, 0x2000
	s_nop 0
	global_load_lds_dwordx4 v[154:155], off
	s_barrier
	s_waitcnt lgkmcnt(0)
	s_waitcnt lgkmcnt(0)
	v_mfma_f32_16x16x32_bf16 v[116:119], v[218:221], v[166:169], v[116:119]
	v_mfma_f32_16x16x32_bf16 v[112:115], v[226:229], v[166:169], v[112:115]
	v_mfma_f32_16x16x32_bf16 v[100:103], v[218:221], v[174:177], v[100:103]
	v_mfma_f32_16x16x32_bf16 v[96:99], v[226:229], v[174:177], v[96:99]
	v_mfma_f32_16x16x32_bf16 v[84:87], v[218:221], v[182:185], v[84:87]
	v_mfma_f32_16x16x32_bf16 v[80:83], v[226:229], v[182:185], v[80:83]
	v_mfma_f32_16x16x32_bf16 v[68:71], v[218:221], v[206:209], v[68:71]
	v_mfma_f32_16x16x32_bf16 v[64:67], v[226:229], v[206:209], v[64:67]
	v_mfma_f32_16x16x32_bf16 v[116:119], v[222:225], v[170:173], v[116:119]
	v_mfma_f32_16x16x32_bf16 v[112:115], v[230:233], v[170:173], v[112:115]
	v_mfma_f32_16x16x32_bf16 v[100:103], v[222:225], v[178:181], v[100:103]
	v_mfma_f32_16x16x32_bf16 v[96:99], v[230:233], v[178:181], v[96:99]
	v_mfma_f32_16x16x32_bf16 v[84:87], v[222:225], v[186:189], v[84:87]
	v_mfma_f32_16x16x32_bf16 v[80:83], v[230:233], v[186:189], v[80:83]
	v_mfma_f32_16x16x32_bf16 v[68:71], v[222:225], v[214:217], v[68:71]
	v_mfma_f32_16x16x32_bf16 v[64:67], v[230:233], v[214:217], v[64:67]
	s_mov_b32 m0, s25
	v_lshl_add_u64 v[234:235], s[2:3], 0, v[156:157]
	s_barrier
	ds_read_b128 v[166:169], v136 offset:16384
	ds_read_b128 v[170:173], v136 offset:17408
	ds_read_b128 v[174:177], v136 offset:18432
	ds_read_b128 v[178:181], v136 offset:19456
	ds_read_b128 v[182:185], v136 offset:20480
	ds_read_b128 v[186:189], v136 offset:21504
	ds_read_b128 v[206:209], v136 offset:22528
	ds_read_b128 v[214:217], v136 offset:23552
	global_load_lds_dwordx4 v[234:235], off
	v_lshl_add_u64 v[236:237], s[2:3], 0, v[128:129]
	s_mov_b32 m0, s34
	s_nop 0
	global_load_lds_dwordx4 v[236:237], off
	s_barrier
	s_waitcnt lgkmcnt(0)
	s_waitcnt lgkmcnt(0)
	v_mfma_f32_16x16x32_bf16 v[60:63], v[142:145], v[166:169], v[60:63]
	v_mfma_f32_16x16x32_bf16 v[56:59], v[150:153], v[166:169], v[56:59]
	v_mfma_f32_16x16x32_bf16 v[44:47], v[142:145], v[174:177], v[44:47]
	v_mfma_f32_16x16x32_bf16 v[40:43], v[150:153], v[174:177], v[40:43]
	v_mfma_f32_16x16x32_bf16 v[28:31], v[142:145], v[182:185], v[28:31]
	v_mfma_f32_16x16x32_bf16 v[24:27], v[150:153], v[182:185], v[24:27]
	v_mfma_f32_16x16x32_bf16 v[12:15], v[142:145], v[206:209], v[12:15]
	v_mfma_f32_16x16x32_bf16 v[8:11], v[150:153], v[206:209], v[8:11]
	v_mfma_f32_16x16x32_bf16 v[60:63], v[146:149], v[170:173], v[60:63]
	v_mfma_f32_16x16x32_bf16 v[56:59], v[162:165], v[170:173], v[56:59]
	v_mfma_f32_16x16x32_bf16 v[44:47], v[146:149], v[178:181], v[44:47]
	v_mfma_f32_16x16x32_bf16 v[40:43], v[162:165], v[178:181], v[40:43]
	v_mfma_f32_16x16x32_bf16 v[28:31], v[146:149], v[186:189], v[28:31]
	v_mfma_f32_16x16x32_bf16 v[24:27], v[162:165], v[186:189], v[24:27]
	v_mfma_f32_16x16x32_bf16 v[12:15], v[146:149], v[214:217], v[12:15]
	v_mfma_f32_16x16x32_bf16 v[8:11], v[162:165], v[214:217], v[8:11]
	s_barrier
	s_add_u32 s42, s42, s36
	s_addc_u32 s43, s43, s37
	s_add_i32 s21, s21, s24
	v_lshl_add_u64 v[238:239], s[42:43], 0, v[156:157]
	s_mov_b32 m0, s21
	v_lshl_add_u64 v[240:241], s[42:43], 0, v[128:129]
	global_load_lds_dwordx4 v[238:239], off
	s_add_i32 m0, s21, 0x2000
	s_nop 0
	global_load_lds_dwordx4 v[240:241], off
	s_waitcnt vmcnt(6)
	s_barrier
	v_mfma_f32_16x16x32_bf16 v[52:55], v[218:221], v[166:169], v[52:55]
	v_mfma_f32_16x16x32_bf16 v[48:51], v[226:229], v[166:169], v[48:51]
	v_mfma_f32_16x16x32_bf16 v[36:39], v[218:221], v[174:177], v[36:39]
	v_mfma_f32_16x16x32_bf16 v[32:35], v[226:229], v[174:177], v[32:35]
	v_mfma_f32_16x16x32_bf16 v[20:23], v[218:221], v[182:185], v[20:23]
	v_mfma_f32_16x16x32_bf16 v[16:19], v[226:229], v[182:185], v[16:19]
	v_mfma_f32_16x16x32_bf16 v[4:7], v[218:221], v[206:209], v[4:7]
	v_mfma_f32_16x16x32_bf16 v[0:3], v[226:229], v[206:209], v[0:3]
	v_mfma_f32_16x16x32_bf16 v[52:55], v[222:225], v[170:173], v[52:55]
	v_mfma_f32_16x16x32_bf16 v[48:51], v[230:233], v[170:173], v[48:51]
	v_mfma_f32_16x16x32_bf16 v[36:39], v[222:225], v[178:181], v[36:39]
	v_mfma_f32_16x16x32_bf16 v[32:35], v[230:233], v[178:181], v[32:35]
	v_mfma_f32_16x16x32_bf16 v[20:23], v[222:225], v[186:189], v[20:23]
	v_mfma_f32_16x16x32_bf16 v[16:19], v[230:233], v[186:189], v[16:19]
	v_mfma_f32_16x16x32_bf16 v[4:7], v[222:225], v[214:217], v[4:7]
	v_mfma_f32_16x16x32_bf16 v[0:3], v[230:233], v[214:217], v[0:3]
	s_add_i32 s21, 0, 0x18000
	v_add_u32_e32 v137, s21, v135
	s_barrier
	ds_read_b128 v[142:145], v137
	ds_read_b128 v[146:149], v137 offset:1024
	ds_read_b128 v[150:153], v137 offset:2048
	ds_read_b128 v[162:165], v137 offset:3072
	s_add_u32 s2, s2, s36
	s_addc_u32 s3, s3, s37
	s_mov_b32 m0, s35
	v_lshl_add_u64 v[218:219], s[2:3], 0, v[156:157]
	ds_read_b128 v[166:169], v136 offset:32768
	ds_read_b128 v[170:173], v136 offset:33792
	ds_read_b128 v[174:177], v136 offset:34816
	ds_read_b128 v[178:181], v136 offset:35840
	ds_read_b128 v[182:185], v136 offset:36864
	ds_read_b128 v[186:189], v136 offset:37888
	ds_read_b128 v[206:209], v136 offset:38912
	ds_read_b128 v[214:217], v136 offset:39936
	global_load_lds_dwordx4 v[218:219], off
	v_lshl_add_u64 v[218:219], s[2:3], 0, v[128:129]
	s_mov_b32 m0, s44
	s_nop 0
	global_load_lds_dwordx4 v[218:219], off
	s_waitcnt lgkmcnt(8)
	s_barrier
	s_waitcnt lgkmcnt(0)
	s_waitcnt lgkmcnt(0)
	v_mfma_f32_16x16x32_bf16 v[124:127], v[142:145], v[166:169], v[124:127]
	v_mfma_f32_16x16x32_bf16 v[120:123], v[150:153], v[166:169], v[120:123]
	v_mfma_f32_16x16x32_bf16 v[108:111], v[142:145], v[174:177], v[108:111]
	v_mfma_f32_16x16x32_bf16 v[104:107], v[150:153], v[174:177], v[104:107]
	v_mfma_f32_16x16x32_bf16 v[92:95], v[142:145], v[182:185], v[92:95]
	v_mfma_f32_16x16x32_bf16 v[88:91], v[150:153], v[182:185], v[88:91]
	v_mfma_f32_16x16x32_bf16 v[76:79], v[142:145], v[206:209], v[76:79]
	v_mfma_f32_16x16x32_bf16 v[72:75], v[150:153], v[206:209], v[72:75]
	v_mfma_f32_16x16x32_bf16 v[124:127], v[146:149], v[170:173], v[124:127]
	v_mfma_f32_16x16x32_bf16 v[120:123], v[162:165], v[170:173], v[120:123]
	v_mfma_f32_16x16x32_bf16 v[108:111], v[146:149], v[178:181], v[108:111]
	v_mfma_f32_16x16x32_bf16 v[104:107], v[162:165], v[178:181], v[104:107]
	v_mfma_f32_16x16x32_bf16 v[92:95], v[146:149], v[186:189], v[92:95]
	v_mfma_f32_16x16x32_bf16 v[88:91], v[162:165], v[186:189], v[88:91]
	v_mfma_f32_16x16x32_bf16 v[76:79], v[146:149], v[214:217], v[76:79]
	v_mfma_f32_16x16x32_bf16 v[72:75], v[162:165], v[214:217], v[72:75]
	s_barrier
	s_add_i32 s2, 0, 0x1c000
	s_add_i32 s3, s21, s24
	v_add_u32_e32 v137, s2, v135
	v_lshl_add_u64 v[138:139], v[138:139], 0, s[50:51]
	s_mov_b32 m0, s3
	ds_read_b128 v[218:221], v137
	ds_read_b128 v[222:225], v137 offset:1024
	ds_read_b128 v[226:229], v137 offset:2048
	ds_read_b128 v[230:233], v137 offset:3072
	global_load_lds_dwordx4 v[138:139], off
	v_lshl_add_u64 v[138:139], v[154:155], 0, s[50:51]
	s_add_i32 m0, s3, 0x2000
	s_nop 0
	global_load_lds_dwordx4 v[138:139], off
	s_barrier
	s_waitcnt lgkmcnt(0)
	s_waitcnt lgkmcnt(0)
	v_mfma_f32_16x16x32_bf16 v[116:119], v[218:221], v[166:169], v[116:119]
	v_mfma_f32_16x16x32_bf16 v[112:115], v[226:229], v[166:169], v[112:115]
	v_mfma_f32_16x16x32_bf16 v[100:103], v[218:221], v[174:177], v[100:103]
	v_mfma_f32_16x16x32_bf16 v[96:99], v[226:229], v[174:177], v[96:99]
	v_mfma_f32_16x16x32_bf16 v[84:87], v[218:221], v[182:185], v[84:87]
	v_mfma_f32_16x16x32_bf16 v[80:83], v[226:229], v[182:185], v[80:83]
	v_mfma_f32_16x16x32_bf16 v[68:71], v[218:221], v[206:209], v[68:71]
	v_mfma_f32_16x16x32_bf16 v[64:67], v[226:229], v[206:209], v[64:67]
	v_mfma_f32_16x16x32_bf16 v[116:119], v[222:225], v[170:173], v[116:119]
	v_mfma_f32_16x16x32_bf16 v[112:115], v[230:233], v[170:173], v[112:115]
	v_mfma_f32_16x16x32_bf16 v[100:103], v[222:225], v[178:181], v[100:103]
	v_mfma_f32_16x16x32_bf16 v[96:99], v[230:233], v[178:181], v[96:99]
	v_mfma_f32_16x16x32_bf16 v[84:87], v[222:225], v[186:189], v[84:87]
	v_mfma_f32_16x16x32_bf16 v[80:83], v[230:233], v[186:189], v[80:83]
	v_mfma_f32_16x16x32_bf16 v[68:71], v[222:225], v[214:217], v[68:71]
	v_mfma_f32_16x16x32_bf16 v[64:67], v[230:233], v[214:217], v[64:67]
	s_mov_b32 m0, s45
	v_lshl_add_u64 v[138:139], v[234:235], 0, s[50:51]
	s_barrier
	ds_read_b128 v[166:169], v136 offset:49152
	ds_read_b128 v[170:173], v136 offset:50176
	ds_read_b128 v[174:177], v136 offset:51200
	ds_read_b128 v[178:181], v136 offset:52224
	ds_read_b128 v[182:185], v136 offset:53248
	ds_read_b128 v[186:189], v136 offset:54272
	ds_read_b128 v[206:209], v136 offset:55296
	ds_read_b128 v[214:217], v136 offset:56320
	global_load_lds_dwordx4 v[138:139], off
	v_lshl_add_u64 v[138:139], v[236:237], 0, s[50:51]
	s_mov_b32 m0, s48
	s_nop 0
	global_load_lds_dwordx4 v[138:139], off
	s_barrier
	s_waitcnt lgkmcnt(0)
	s_waitcnt lgkmcnt(0)
	v_mfma_f32_16x16x32_bf16 v[60:63], v[142:145], v[166:169], v[60:63]
	v_mfma_f32_16x16x32_bf16 v[56:59], v[150:153], v[166:169], v[56:59]
	v_mfma_f32_16x16x32_bf16 v[44:47], v[142:145], v[174:177], v[44:47]
	v_mfma_f32_16x16x32_bf16 v[40:43], v[150:153], v[174:177], v[40:43]
	v_mfma_f32_16x16x32_bf16 v[28:31], v[142:145], v[182:185], v[28:31]
	v_mfma_f32_16x16x32_bf16 v[24:27], v[150:153], v[182:185], v[24:27]
	v_mfma_f32_16x16x32_bf16 v[12:15], v[142:145], v[206:209], v[12:15]
	v_mfma_f32_16x16x32_bf16 v[8:11], v[150:153], v[206:209], v[8:11]
	v_mfma_f32_16x16x32_bf16 v[60:63], v[146:149], v[170:173], v[60:63]
	v_mfma_f32_16x16x32_bf16 v[56:59], v[162:165], v[170:173], v[56:59]
	v_mfma_f32_16x16x32_bf16 v[44:47], v[146:149], v[178:181], v[44:47]
	v_mfma_f32_16x16x32_bf16 v[40:43], v[162:165], v[178:181], v[40:43]
	v_mfma_f32_16x16x32_bf16 v[28:31], v[146:149], v[186:189], v[28:31]
	v_mfma_f32_16x16x32_bf16 v[24:27], v[162:165], v[186:189], v[24:27]
	v_mfma_f32_16x16x32_bf16 v[12:15], v[146:149], v[214:217], v[12:15]
	v_mfma_f32_16x16x32_bf16 v[8:11], v[162:165], v[214:217], v[8:11]
	s_barrier
	s_add_i32 s2, s2, s24
	v_lshl_add_u64 v[138:139], v[238:239], 0, s[50:51]
	s_mov_b32 m0, s2
	s_nop 0
	global_load_lds_dwordx4 v[138:139], off
	v_lshl_add_u64 v[138:139], v[240:241], 0, s[50:51]
	s_add_i32 m0, s2, 0x2000
	s_nop 0
	global_load_lds_dwordx4 v[138:139], off
	s_waitcnt vmcnt(6)
	s_barrier
	v_mfma_f32_16x16x32_bf16 v[52:55], v[218:221], v[166:169], v[52:55]
	v_mfma_f32_16x16x32_bf16 v[48:51], v[226:229], v[166:169], v[48:51]
	v_mfma_f32_16x16x32_bf16 v[36:39], v[218:221], v[174:177], v[36:39]
	v_mfma_f32_16x16x32_bf16 v[32:35], v[226:229], v[174:177], v[32:35]
	v_mfma_f32_16x16x32_bf16 v[20:23], v[218:221], v[182:185], v[20:23]
	v_mfma_f32_16x16x32_bf16 v[16:19], v[226:229], v[182:185], v[16:19]
	v_mfma_f32_16x16x32_bf16 v[4:7], v[218:221], v[206:209], v[4:7]
	v_mfma_f32_16x16x32_bf16 v[0:3], v[226:229], v[206:209], v[0:3]
	v_mfma_f32_16x16x32_bf16 v[52:55], v[222:225], v[170:173], v[52:55]
	v_mfma_f32_16x16x32_bf16 v[48:51], v[230:233], v[170:173], v[48:51]
	v_mfma_f32_16x16x32_bf16 v[36:39], v[222:225], v[178:181], v[36:39]
	v_mfma_f32_16x16x32_bf16 v[32:35], v[230:233], v[178:181], v[32:35]
	v_mfma_f32_16x16x32_bf16 v[20:23], v[222:225], v[186:189], v[20:23]
	v_mfma_f32_16x16x32_bf16 v[16:19], v[230:233], v[186:189], v[16:19]
	v_mfma_f32_16x16x32_bf16 v[4:7], v[222:225], v[214:217], v[4:7]
	v_mfma_f32_16x16x32_bf16 v[0:3], v[230:233], v[214:217], v[0:3]
	s_add_u32 s6, s6, 0x100
	s_addc_u32 s7, s7, 0
	s_cmp_ge_i32 s54, s49
	s_mov_b32 s2, s54
	s_barrier
	s_cbranch_scc0 .LBB0_272

.LBB0_285:
	v_bfe_u32 v14, v160, 4, 2
	v_and_b32_e32 v131, 15, v160
	v_lshlrev_b32_e32 v130, 4, v14
	v_lshlrev_b32_e32 v15, 2, v160
	v_lshl_or_b32 v14, v131, 6, v130
	s_lshl_b32 s21, s44, 13
	v_and_b32_e32 v15, 32, v15
	v_bitop3_b32 v16, v14, s21, v15 bitop3:0xde
	s_lshl_b32 s21, s45, 5
	s_lshl_b32 s35, s44, 6
	s_and_b32 s44, s21, 0x60
	s_add_i32 m0, s19, 0x18000
	v_lshl_add_u64 v[6:7], v[6:7], 0, s[50:51]
	s_lshl_b32 s21, s44, 7
	s_waitcnt vmcnt(4)
	s_barrier
	global_load_lds_dwordx4 v[6:7], off
	v_lshl_add_u64 v[4:5], v[4:5], 0, s[50:51]
	s_add_i32 m0, s19, 0x1a000
	s_add_i32 s45, s19, 0x8000
	s_add_i32 s53, s19, 0xa000
	global_load_lds_dwordx4 v[4:5], off
	v_lshl_add_u64 v[2:3], v[2:3], 0, s[50:51]
	s_mov_b32 m0, s45
	s_add_u32 s54, s42, 0x80080
	global_load_lds_dwordx4 v[2:3], off
	v_lshl_add_u64 v[0:1], v[0:1], 0, s[50:51]
	s_mov_b32 m0, s53
	s_addc_u32 s55, s43, 0
	global_load_lds_dwordx4 v[0:1], off
	s_add_i32 m0, s19, 0x1c000
	v_lshl_add_u64 v[0:1], s[54:55], 0, v[156:157]
	global_load_lds_dwordx4 v[0:1], off
	v_lshl_add_u64 v[0:1], s[54:55], 0, v[128:129]
	s_add_i32 m0, s19, 0x1e000
	s_add_u32 s2, s6, s2
	global_load_lds_dwordx4 v[0:1], off
	s_addc_u32 s3, s7, s3
	v_lshlrev_b32_e32 v0, 15, v11
	v_and_b32_e32 v0, 0xffff0000, v0
	s_add_u32 s2, s26, s2
	v_lshl_add_u32 v0, v12, 12, v0
	v_and_b32_e32 v1, 1, v11
	s_addc_u32 s3, s27, s3
	v_lshl_or_b32 v0, v1, 6, v0
	s_add_u32 s2, s2, 0x19524080
	v_lshl_add_u32 v0, v13, 1, v0
	v_mov_b32_e32 v1, v157
	s_addc_u32 s3, s3, 0
	v_lshl_add_u64 v[132:133], s[2:3], 0, v[0:1]
	v_lshlrev_b32_e32 v0, 15, v8
	v_and_b32_e32 v0, 0xffff0000, v0
	v_lshl_add_u32 v0, v9, 12, v0
	v_and_b32_e32 v1, 1, v8
	v_lshl_or_b32 v0, v1, 6, v0
	s_waitcnt vmcnt(6)
	v_lshl_add_u32 v0, v10, 1, v0
	v_mov_b32_e32 v1, v157
	v_lshl_add_u64 v[134:135], s[2:3], 0, v[0:1]
	v_bitop3_b32 v136, s21, v14, v15 bitop3:0xf6
	s_mov_b32 s54, -2
	s_mov_b64 s[6:7], 0
	v_add_u32_e32 v137, 0, v16
	s_barrier
	s_add_u32 s60, s6, 0x100
	s_addc_u32 s61, s7, 0
	s_cmp_lg_u32 s54, 28
	s_cselect_b32 s55, s60, 0
	s_cselect_b32 s21, s61, 0
	s_add_u32 s2, s48, s55
	s_addc_u32 s3, s49, s21
	s_add_i32 s66, 0, 0x10000
	v_add_u32_e32 v150, s66, v136
	ds_read_b128 v[138:141], v150
	ds_read_b128 v[142:145], v150 offset:1024
	ds_read_b128 v[146:149], v150 offset:2048
	ds_read_b128 v[150:153], v150 offset:3072
	s_add_u32 s62, s42, s55
	s_addc_u32 s63, s43, s21
	v_lshl_add_u64 v[154:155], v[134:135], 0, s[6:7]
	s_add_i32 m0, s19, 0xc000
	ds_read_b128 v[162:165], v137
	ds_read_b128 v[166:169], v137 offset:1024
	ds_read_b128 v[170:173], v137 offset:2048
	ds_read_b128 v[174:177], v137 offset:3072
	ds_read_b128 v[178:181], v137 offset:4096
	ds_read_b128 v[182:185], v137 offset:5120
	ds_read_b128 v[186:189], v137 offset:6144
	ds_read_b128 v[206:209], v137 offset:7168
	global_load_lds_dwordx4 v[154:155], off
	v_lshl_add_u64 v[154:155], v[132:133], 0, s[6:7]
	s_add_i32 m0, s19, 0xe000
	s_nop 0
	global_load_lds_dwordx4 v[154:155], off
	s_waitcnt lgkmcnt(8)
	s_barrier
	s_waitcnt lgkmcnt(0)
	s_waitcnt lgkmcnt(0)
	v_mfma_f32_16x16x32_bf16 v[124:127], v[138:141], v[162:165], 0
	v_mfma_f32_16x16x32_bf16 v[120:123], v[146:149], v[162:165], 0
	v_mfma_f32_16x16x32_bf16 v[116:119], v[138:141], v[170:173], 0
	v_mfma_f32_16x16x32_bf16 v[112:115], v[146:149], v[170:173], 0
	v_mfma_f32_16x16x32_bf16 v[108:111], v[138:141], v[178:181], 0
	v_mfma_f32_16x16x32_bf16 v[100:103], v[146:149], v[178:181], 0
	v_mfma_f32_16x16x32_bf16 v[92:95], v[138:141], v[186:189], 0
	v_mfma_f32_16x16x32_bf16 v[84:87], v[146:149], v[186:189], 0
	v_mfma_f32_16x16x32_bf16 v[124:127], v[142:145], v[166:169], v[124:127]
	v_mfma_f32_16x16x32_bf16 v[120:123], v[150:153], v[166:169], v[120:123]
	v_mfma_f32_16x16x32_bf16 v[116:119], v[142:145], v[174:177], v[116:119]
	v_mfma_f32_16x16x32_bf16 v[112:115], v[150:153], v[174:177], v[112:115]
	v_mfma_f32_16x16x32_bf16 v[108:111], v[142:145], v[182:185], v[108:111]
	v_mfma_f32_16x16x32_bf16 v[100:103], v[150:153], v[182:185], v[100:103]
	v_mfma_f32_16x16x32_bf16 v[92:95], v[142:145], v[206:209], v[92:95]
	v_mfma_f32_16x16x32_bf16 v[84:87], v[150:153], v[206:209], v[84:87]
	s_barrier
	s_add_i32 s21, 0, 0x14000
	v_add_u32_e32 v154, s21, v136
	s_add_i32 s6, s66, s10
	ds_read_b128 v[214:217], v154
	ds_read_b128 v[218:221], v154 offset:1024
	ds_read_b128 v[222:225], v154 offset:2048
	ds_read_b128 v[226:229], v154 offset:3072
	v_lshl_add_u64 v[154:155], s[62:63], 0, v[156:157]
	s_mov_b32 m0, s6
	v_lshl_add_u64 v[230:231], s[62:63], 0, v[128:129]
	global_load_lds_dwordx4 v[154:155], off
	s_add_i32 m0, s6, 0x2000
	s_nop 0
	global_load_lds_dwordx4 v[230:231], off
	s_barrier
	s_waitcnt lgkmcnt(0)
	s_waitcnt lgkmcnt(0)
	v_mfma_f32_16x16x32_bf16 v[104:107], v[214:217], v[162:165], 0
	v_mfma_f32_16x16x32_bf16 v[96:99], v[222:225], v[162:165], 0
	v_mfma_f32_16x16x32_bf16 v[88:91], v[214:217], v[170:173], 0
	v_mfma_f32_16x16x32_bf16 v[80:83], v[222:225], v[170:173], 0
	v_mfma_f32_16x16x32_bf16 v[76:79], v[214:217], v[178:181], 0
	v_mfma_f32_16x16x32_bf16 v[72:75], v[222:225], v[178:181], 0
	v_mfma_f32_16x16x32_bf16 v[68:71], v[214:217], v[186:189], 0
	v_mfma_f32_16x16x32_bf16 v[64:67], v[222:225], v[186:189], 0
	v_mfma_f32_16x16x32_bf16 v[104:107], v[218:221], v[166:169], v[104:107]
	v_mfma_f32_16x16x32_bf16 v[96:99], v[226:229], v[166:169], v[96:99]
	v_mfma_f32_16x16x32_bf16 v[88:91], v[218:221], v[174:177], v[88:91]
	v_mfma_f32_16x16x32_bf16 v[80:83], v[226:229], v[174:177], v[80:83]
	v_mfma_f32_16x16x32_bf16 v[76:79], v[218:221], v[182:185], v[76:79]
	v_mfma_f32_16x16x32_bf16 v[72:75], v[226:229], v[182:185], v[72:75]
	v_mfma_f32_16x16x32_bf16 v[68:71], v[218:221], v[206:209], v[68:71]
	v_mfma_f32_16x16x32_bf16 v[64:67], v[226:229], v[206:209], v[64:67]
	s_mov_b32 m0, s19
	v_lshl_add_u64 v[232:233], s[2:3], 0, v[156:157]
	s_barrier
	ds_read_b128 v[162:165], v137 offset:16384
	ds_read_b128 v[166:169], v137 offset:17408
	ds_read_b128 v[170:173], v137 offset:18432
	ds_read_b128 v[174:177], v137 offset:19456
	ds_read_b128 v[178:181], v137 offset:20480
	ds_read_b128 v[182:185], v137 offset:21504
	ds_read_b128 v[186:189], v137 offset:22528
	ds_read_b128 v[206:209], v137 offset:23552
	global_load_lds_dwordx4 v[232:233], off
	v_lshl_add_u64 v[234:235], s[2:3], 0, v[128:129]
	s_mov_b32 m0, s24
	s_nop 0
	global_load_lds_dwordx4 v[234:235], off
	s_barrier
	s_waitcnt lgkmcnt(0)
	s_waitcnt lgkmcnt(0)
	v_mfma_f32_16x16x32_bf16 v[60:63], v[138:141], v[162:165], 0
	v_mfma_f32_16x16x32_bf16 v[56:59], v[146:149], v[162:165], 0
	v_mfma_f32_16x16x32_bf16 v[52:55], v[138:141], v[170:173], 0
	v_mfma_f32_16x16x32_bf16 v[48:51], v[146:149], v[170:173], 0
	v_mfma_f32_16x16x32_bf16 v[40:43], v[138:141], v[178:181], 0
	v_mfma_f32_16x16x32_bf16 v[32:35], v[146:149], v[178:181], 0
	v_mfma_f32_16x16x32_bf16 v[24:27], v[138:141], v[186:189], 0
	v_mfma_f32_16x16x32_bf16 v[16:19], v[146:149], v[186:189], 0
	v_mfma_f32_16x16x32_bf16 v[60:63], v[142:145], v[166:169], v[60:63]
	v_mfma_f32_16x16x32_bf16 v[56:59], v[150:153], v[166:169], v[56:59]
	v_mfma_f32_16x16x32_bf16 v[52:55], v[142:145], v[174:177], v[52:55]
	v_mfma_f32_16x16x32_bf16 v[48:51], v[150:153], v[174:177], v[48:51]
	v_mfma_f32_16x16x32_bf16 v[40:43], v[142:145], v[182:185], v[40:43]
	v_mfma_f32_16x16x32_bf16 v[32:35], v[150:153], v[182:185], v[32:35]
	v_mfma_f32_16x16x32_bf16 v[24:27], v[142:145], v[206:209], v[24:27]
	v_mfma_f32_16x16x32_bf16 v[16:19], v[150:153], v[206:209], v[16:19]
	s_barrier
	s_add_u32 s6, s62, 0x80000
	s_addc_u32 s7, s63, 0
	s_add_i32 s21, s21, s10
	v_lshl_add_u64 v[138:139], s[6:7], 0, v[156:157]
	s_mov_b32 m0, s21
	s_nop 0
	global_load_lds_dwordx4 v[138:139], off
	v_lshl_add_u64 v[138:139], s[6:7], 0, v[128:129]
	s_add_i32 m0, s21, 0x2000
	s_nop 0
	global_load_lds_dwordx4 v[138:139], off
	s_waitcnt vmcnt(6)
	s_barrier
	v_mfma_f32_16x16x32_bf16 v[44:47], v[214:217], v[162:165], 0
	v_mfma_f32_16x16x32_bf16 v[36:39], v[222:225], v[162:165], 0
	v_mfma_f32_16x16x32_bf16 v[28:31], v[214:217], v[170:173], 0
	v_mfma_f32_16x16x32_bf16 v[20:23], v[222:225], v[170:173], 0
	v_mfma_f32_16x16x32_bf16 v[12:15], v[214:217], v[178:181], 0
	v_mfma_f32_16x16x32_bf16 v[8:11], v[222:225], v[178:181], 0
	v_mfma_f32_16x16x32_bf16 v[4:7], v[214:217], v[186:189], 0
	v_mfma_f32_16x16x32_bf16 v[0:3], v[222:225], v[186:189], 0
	v_mfma_f32_16x16x32_bf16 v[44:47], v[218:221], v[166:169], v[44:47]
	v_mfma_f32_16x16x32_bf16 v[36:39], v[226:229], v[166:169], v[36:39]
	v_mfma_f32_16x16x32_bf16 v[28:31], v[218:221], v[174:177], v[28:31]
	v_mfma_f32_16x16x32_bf16 v[20:23], v[226:229], v[174:177], v[20:23]
	v_mfma_f32_16x16x32_bf16 v[12:15], v[218:221], v[182:185], v[12:15]
	v_mfma_f32_16x16x32_bf16 v[8:11], v[226:229], v[182:185], v[8:11]
	v_mfma_f32_16x16x32_bf16 v[4:7], v[218:221], v[206:209], v[4:7]
	v_mfma_f32_16x16x32_bf16 v[0:3], v[226:229], v[206:209], v[0:3]
	s_add_i32 s6, 0, 0x18000
	v_add_u32_e32 v150, s6, v136
	s_barrier
	ds_read_b128 v[138:141], v150
	ds_read_b128 v[142:145], v150 offset:1024
	ds_read_b128 v[146:149], v150 offset:2048
	ds_read_b128 v[150:153], v150 offset:3072
	s_add_u32 s2, s2, 0x80000
	s_addc_u32 s3, s3, 0
	s_mov_b32 m0, s25
	v_lshl_add_u64 v[214:215], s[2:3], 0, v[156:157]
	ds_read_b128 v[162:165], v137 offset:32768
	ds_read_b128 v[166:169], v137 offset:33792
	ds_read_b128 v[170:173], v137 offset:34816
	ds_read_b128 v[174:177], v137 offset:35840
	ds_read_b128 v[178:181], v137 offset:36864
	ds_read_b128 v[182:185], v137 offset:37888
	ds_read_b128 v[186:189], v137 offset:38912
	ds_read_b128 v[206:209], v137 offset:39936
	global_load_lds_dwordx4 v[214:215], off
	v_lshl_add_u64 v[214:215], s[2:3], 0, v[128:129]
	s_mov_b32 m0, s34
	s_nop 0
	global_load_lds_dwordx4 v[214:215], off
	s_waitcnt lgkmcnt(8)
	s_barrier
	s_waitcnt lgkmcnt(0)
	s_waitcnt lgkmcnt(0)
	v_mfma_f32_16x16x32_bf16 v[124:127], v[138:141], v[162:165], v[124:127]
	v_mfma_f32_16x16x32_bf16 v[120:123], v[146:149], v[162:165], v[120:123]
	v_mfma_f32_16x16x32_bf16 v[116:119], v[138:141], v[170:173], v[116:119]
	v_mfma_f32_16x16x32_bf16 v[112:115], v[146:149], v[170:173], v[112:115]
	v_mfma_f32_16x16x32_bf16 v[108:111], v[138:141], v[178:181], v[108:111]
	v_mfma_f32_16x16x32_bf16 v[100:103], v[146:149], v[178:181], v[100:103]
	v_mfma_f32_16x16x32_bf16 v[92:95], v[138:141], v[186:189], v[92:95]
	v_mfma_f32_16x16x32_bf16 v[84:87], v[146:149], v[186:189], v[84:87]
	v_mfma_f32_16x16x32_bf16 v[124:127], v[142:145], v[166:169], v[124:127]
	v_mfma_f32_16x16x32_bf16 v[120:123], v[150:153], v[166:169], v[120:123]
	v_mfma_f32_16x16x32_bf16 v[116:119], v[142:145], v[174:177], v[116:119]
	v_mfma_f32_16x16x32_bf16 v[112:115], v[150:153], v[174:177], v[112:115]
	v_mfma_f32_16x16x32_bf16 v[108:111], v[142:145], v[182:185], v[108:111]
	v_mfma_f32_16x16x32_bf16 v[100:103], v[150:153], v[182:185], v[100:103]
	v_mfma_f32_16x16x32_bf16 v[92:95], v[142:145], v[206:209], v[92:95]
	v_mfma_f32_16x16x32_bf16 v[84:87], v[150:153], v[206:209], v[84:87]
	s_barrier
	s_add_i32 s7, 0, 0x1c000
	s_add_i32 s2, s6, s10
	v_add_u32_e32 v161, s7, v136
	v_lshl_add_u64 v[154:155], v[154:155], 0, s[50:51]
	s_mov_b32 m0, s2
	ds_read_b128 v[214:217], v161
	ds_read_b128 v[218:221], v161 offset:1024
	ds_read_b128 v[222:225], v161 offset:2048
	ds_read_b128 v[226:229], v161 offset:3072
	global_load_lds_dwordx4 v[154:155], off
	v_lshl_add_u64 v[154:155], v[230:231], 0, s[50:51]
	s_add_i32 m0, s2, 0x2000
	s_nop 0
	global_load_lds_dwordx4 v[154:155], off
	s_barrier
	s_waitcnt lgkmcnt(0)
	s_waitcnt lgkmcnt(0)
	v_mfma_f32_16x16x32_bf16 v[104:107], v[214:217], v[162:165], v[104:107]
	v_mfma_f32_16x16x32_bf16 v[96:99], v[222:225], v[162:165], v[96:99]
	v_mfma_f32_16x16x32_bf16 v[88:91], v[214:217], v[170:173], v[88:91]
	v_mfma_f32_16x16x32_bf16 v[80:83], v[222:225], v[170:173], v[80:83]
	v_mfma_f32_16x16x32_bf16 v[76:79], v[214:217], v[178:181], v[76:79]
	v_mfma_f32_16x16x32_bf16 v[72:75], v[222:225], v[178:181], v[72:75]
	v_mfma_f32_16x16x32_bf16 v[68:71], v[214:217], v[186:189], v[68:71]
	v_mfma_f32_16x16x32_bf16 v[64:67], v[222:225], v[186:189], v[64:67]
	v_mfma_f32_16x16x32_bf16 v[104:107], v[218:221], v[166:169], v[104:107]
	v_mfma_f32_16x16x32_bf16 v[96:99], v[226:229], v[166:169], v[96:99]
	v_mfma_f32_16x16x32_bf16 v[88:91], v[218:221], v[174:177], v[88:91]
	v_mfma_f32_16x16x32_bf16 v[80:83], v[226:229], v[174:177], v[80:83]
	v_mfma_f32_16x16x32_bf16 v[76:79], v[218:221], v[182:185], v[76:79]
	v_mfma_f32_16x16x32_bf16 v[72:75], v[226:229], v[182:185], v[72:75]
	v_mfma_f32_16x16x32_bf16 v[68:71], v[218:221], v[206:209], v[68:71]
	v_mfma_f32_16x16x32_bf16 v[64:67], v[226:229], v[206:209], v[64:67]
	s_mov_b32 m0, s45
	v_lshl_add_u64 v[154:155], v[232:233], 0, s[50:51]
	s_barrier
	ds_read_b128 v[162:165], v137 offset:49152
	ds_read_b128 v[166:169], v137 offset:50176
	ds_read_b128 v[170:173], v137 offset:51200
	ds_read_b128 v[174:177], v137 offset:52224
	ds_read_b128 v[178:181], v137 offset:53248
	ds_read_b128 v[182:185], v137 offset:54272
	ds_read_b128 v[186:189], v137 offset:55296
	ds_read_b128 v[206:209], v137 offset:56320
	global_load_lds_dwordx4 v[154:155], off
	v_lshl_add_u64 v[154:155], v[234:235], 0, s[50:51]
	s_mov_b32 m0, s53
	s_nop 0
	global_load_lds_dwordx4 v[154:155], off
	s_barrier
	s_waitcnt lgkmcnt(0)
	s_waitcnt lgkmcnt(0)
	v_mfma_f32_16x16x32_bf16 v[60:63], v[138:141], v[162:165], v[60:63]
	v_mfma_f32_16x16x32_bf16 v[56:59], v[146:149], v[162:165], v[56:59]
	v_mfma_f32_16x16x32_bf16 v[52:55], v[138:141], v[170:173], v[52:55]
	v_mfma_f32_16x16x32_bf16 v[48:51], v[146:149], v[170:173], v[48:51]
	v_mfma_f32_16x16x32_bf16 v[40:43], v[138:141], v[178:181], v[40:43]
	v_mfma_f32_16x16x32_bf16 v[32:35], v[146:149], v[178:181], v[32:35]
	v_mfma_f32_16x16x32_bf16 v[24:27], v[138:141], v[186:189], v[24:27]
	v_mfma_f32_16x16x32_bf16 v[16:19], v[146:149], v[186:189], v[16:19]
	v_mfma_f32_16x16x32_bf16 v[60:63], v[142:145], v[166:169], v[60:63]
	v_mfma_f32_16x16x32_bf16 v[56:59], v[150:153], v[166:169], v[56:59]
	v_mfma_f32_16x16x32_bf16 v[52:55], v[142:145], v[174:177], v[52:55]
	v_mfma_f32_16x16x32_bf16 v[48:51], v[150:153], v[174:177], v[48:51]
	v_mfma_f32_16x16x32_bf16 v[40:43], v[142:145], v[182:185], v[40:43]
	v_mfma_f32_16x16x32_bf16 v[32:35], v[150:153], v[182:185], v[32:35]
	v_mfma_f32_16x16x32_bf16 v[24:27], v[142:145], v[206:209], v[24:27]
	v_mfma_f32_16x16x32_bf16 v[16:19], v[150:153], v[206:209], v[16:19]
	s_barrier
	s_add_u32 s2, s62, 0x80080
	s_addc_u32 s3, s63, 0
	s_add_i32 s6, s7, s10
	v_lshl_add_u64 v[138:139], s[2:3], 0, v[156:157]
	s_mov_b32 m0, s6
	s_nop 0
	global_load_lds_dwordx4 v[138:139], off
	v_lshl_add_u64 v[138:139], s[2:3], 0, v[128:129]
	s_add_i32 m0, s6, 0x2000
	s_nop 0
	global_load_lds_dwordx4 v[138:139], off
	s_waitcnt vmcnt(6)
	s_barrier
	v_mfma_f32_16x16x32_bf16 v[44:47], v[214:217], v[162:165], v[44:47]
	v_mfma_f32_16x16x32_bf16 v[36:39], v[222:225], v[162:165], v[36:39]
	v_mfma_f32_16x16x32_bf16 v[28:31], v[214:217], v[170:173], v[28:31]
	v_mfma_f32_16x16x32_bf16 v[20:23], v[222:225], v[170:173], v[20:23]
	v_mfma_f32_16x16x32_bf16 v[12:15], v[214:217], v[178:181], v[12:15]
	v_mfma_f32_16x16x32_bf16 v[8:11], v[222:225], v[178:181], v[8:11]
	v_mfma_f32_16x16x32_bf16 v[4:7], v[214:217], v[186:189], v[4:7]
	v_mfma_f32_16x16x32_bf16 v[0:3], v[222:225], v[186:189], v[0:3]
	v_mfma_f32_16x16x32_bf16 v[44:47], v[218:221], v[166:169], v[44:47]
	v_mfma_f32_16x16x32_bf16 v[36:39], v[226:229], v[166:169], v[36:39]
	v_mfma_f32_16x16x32_bf16 v[28:31], v[218:221], v[174:177], v[28:31]
	v_mfma_f32_16x16x32_bf16 v[20:23], v[226:229], v[174:177], v[20:23]
	v_mfma_f32_16x16x32_bf16 v[12:15], v[218:221], v[182:185], v[12:15]
	v_mfma_f32_16x16x32_bf16 v[8:11], v[226:229], v[182:185], v[8:11]
	v_mfma_f32_16x16x32_bf16 v[4:7], v[218:221], v[206:209], v[4:7]
	v_mfma_f32_16x16x32_bf16 v[0:3], v[226:229], v[206:209], v[0:3]
	s_add_i32 s54, s54, 2
	s_cmp_gt_u32 s54, 29
	s_mov_b64 s[6:7], s[60:61]
	s_barrier
	s_cbranch_scc1 .Lpost_286
.LBB0_286:
	s_add_u32 s60, s6, 0x100
	s_addc_u32 s61, s7, 0
	s_cmp_lg_u32 s54, 28
	s_cselect_b32 s55, s60, 0
	s_cselect_b32 s21, s61, 0
	s_add_u32 s2, s48, s55
	s_addc_u32 s3, s49, s21
	s_add_i32 s66, 0, 0x10000
	v_add_u32_e32 v150, s66, v136
	ds_read_b128 v[138:141], v150
	ds_read_b128 v[142:145], v150 offset:1024
	ds_read_b128 v[146:149], v150 offset:2048
	ds_read_b128 v[150:153], v150 offset:3072
	s_add_u32 s62, s42, s55
	s_addc_u32 s63, s43, s21
	v_lshl_add_u64 v[154:155], v[134:135], 0, s[6:7]
	s_add_i32 m0, s19, 0xc000
	ds_read_b128 v[162:165], v137
	ds_read_b128 v[166:169], v137 offset:1024
	ds_read_b128 v[170:173], v137 offset:2048
	ds_read_b128 v[174:177], v137 offset:3072
	ds_read_b128 v[178:181], v137 offset:4096
	ds_read_b128 v[182:185], v137 offset:5120
	ds_read_b128 v[186:189], v137 offset:6144
	ds_read_b128 v[206:209], v137 offset:7168
	global_load_lds_dwordx4 v[154:155], off
	v_lshl_add_u64 v[154:155], v[132:133], 0, s[6:7]
	s_add_i32 m0, s19, 0xe000
	s_nop 0
	global_load_lds_dwordx4 v[154:155], off
	s_waitcnt lgkmcnt(8)
	s_barrier
	s_waitcnt lgkmcnt(0)
	s_waitcnt lgkmcnt(0)
	v_mfma_f32_16x16x32_bf16 v[124:127], v[138:141], v[162:165], v[124:127]
	v_mfma_f32_16x16x32_bf16 v[120:123], v[146:149], v[162:165], v[120:123]
	v_mfma_f32_16x16x32_bf16 v[116:119], v[138:141], v[170:173], v[116:119]
	v_mfma_f32_16x16x32_bf16 v[112:115], v[146:149], v[170:173], v[112:115]
	v_mfma_f32_16x16x32_bf16 v[108:111], v[138:141], v[178:181], v[108:111]
	v_mfma_f32_16x16x32_bf16 v[100:103], v[146:149], v[178:181], v[100:103]
	v_mfma_f32_16x16x32_bf16 v[92:95], v[138:141], v[186:189], v[92:95]
	v_mfma_f32_16x16x32_bf16 v[84:87], v[146:149], v[186:189], v[84:87]
	v_mfma_f32_16x16x32_bf16 v[124:127], v[142:145], v[166:169], v[124:127]
	v_mfma_f32_16x16x32_bf16 v[120:123], v[150:153], v[166:169], v[120:123]
	v_mfma_f32_16x16x32_bf16 v[116:119], v[142:145], v[174:177], v[116:119]
	v_mfma_f32_16x16x32_bf16 v[112:115], v[150:153], v[174:177], v[112:115]
	v_mfma_f32_16x16x32_bf16 v[108:111], v[142:145], v[182:185], v[108:111]
	v_mfma_f32_16x16x32_bf16 v[100:103], v[150:153], v[182:185], v[100:103]
	v_mfma_f32_16x16x32_bf16 v[92:95], v[142:145], v[206:209], v[92:95]
	v_mfma_f32_16x16x32_bf16 v[84:87], v[150:153], v[206:209], v[84:87]
	s_barrier
	s_add_i32 s21, 0, 0x14000
	v_add_u32_e32 v154, s21, v136
	s_add_i32 s6, s66, s10
	ds_read_b128 v[214:217], v154
	ds_read_b128 v[218:221], v154 offset:1024
	ds_read_b128 v[222:225], v154 offset:2048
	ds_read_b128 v[226:229], v154 offset:3072
	v_lshl_add_u64 v[154:155], s[62:63], 0, v[156:157]
	s_mov_b32 m0, s6
	v_lshl_add_u64 v[230:231], s[62:63], 0, v[128:129]
	global_load_lds_dwordx4 v[154:155], off
	s_add_i32 m0, s6, 0x2000
	s_nop 0
	global_load_lds_dwordx4 v[230:231], off
	s_barrier
	s_waitcnt lgkmcnt(0)
	s_waitcnt lgkmcnt(0)
	v_mfma_f32_16x16x32_bf16 v[104:107], v[214:217], v[162:165], v[104:107]
	v_mfma_f32_16x16x32_bf16 v[96:99], v[222:225], v[162:165], v[96:99]
	v_mfma_f32_16x16x32_bf16 v[88:91], v[214:217], v[170:173], v[88:91]
	v_mfma_f32_16x16x32_bf16 v[80:83], v[222:225], v[170:173], v[80:83]
	v_mfma_f32_16x16x32_bf16 v[76:79], v[214:217], v[178:181], v[76:79]
	v_mfma_f32_16x16x32_bf16 v[72:75], v[222:225], v[178:181], v[72:75]
	v_mfma_f32_16x16x32_bf16 v[68:71], v[214:217], v[186:189], v[68:71]
	v_mfma_f32_16x16x32_bf16 v[64:67], v[222:225], v[186:189], v[64:67]
	v_mfma_f32_16x16x32_bf16 v[104:107], v[218:221], v[166:169], v[104:107]
	v_mfma_f32_16x16x32_bf16 v[96:99], v[226:229], v[166:169], v[96:99]
	v_mfma_f32_16x16x32_bf16 v[88:91], v[218:221], v[174:177], v[88:91]
	v_mfma_f32_16x16x32_bf16 v[80:83], v[226:229], v[174:177], v[80:83]
	v_mfma_f32_16x16x32_bf16 v[76:79], v[218:221], v[182:185], v[76:79]
	v_mfma_f32_16x16x32_bf16 v[72:75], v[226:229], v[182:185], v[72:75]
	v_mfma_f32_16x16x32_bf16 v[68:71], v[218:221], v[206:209], v[68:71]
	v_mfma_f32_16x16x32_bf16 v[64:67], v[226:229], v[206:209], v[64:67]
	s_mov_b32 m0, s19
	v_lshl_add_u64 v[232:233], s[2:3], 0, v[156:157]
	s_barrier
	ds_read_b128 v[162:165], v137 offset:16384
	ds_read_b128 v[166:169], v137 offset:17408
	ds_read_b128 v[170:173], v137 offset:18432
	ds_read_b128 v[174:177], v137 offset:19456
	ds_read_b128 v[178:181], v137 offset:20480
	ds_read_b128 v[182:185], v137 offset:21504
	ds_read_b128 v[186:189], v137 offset:22528
	ds_read_b128 v[206:209], v137 offset:23552
	global_load_lds_dwordx4 v[232:233], off
	v_lshl_add_u64 v[234:235], s[2:3], 0, v[128:129]
	s_mov_b32 m0, s24
	s_nop 0
	global_load_lds_dwordx4 v[234:235], off
	s_barrier
	s_waitcnt lgkmcnt(0)
	s_waitcnt lgkmcnt(0)
	v_mfma_f32_16x16x32_bf16 v[60:63], v[138:141], v[162:165], v[60:63]
	v_mfma_f32_16x16x32_bf16 v[56:59], v[146:149], v[162:165], v[56:59]
	v_mfma_f32_16x16x32_bf16 v[52:55], v[138:141], v[170:173], v[52:55]
	v_mfma_f32_16x16x32_bf16 v[48:51], v[146:149], v[170:173], v[48:51]
	v_mfma_f32_16x16x32_bf16 v[40:43], v[138:141], v[178:181], v[40:43]
	v_mfma_f32_16x16x32_bf16 v[32:35], v[146:149], v[178:181], v[32:35]
	v_mfma_f32_16x16x32_bf16 v[24:27], v[138:141], v[186:189], v[24:27]
	v_mfma_f32_16x16x32_bf16 v[16:19], v[146:149], v[186:189], v[16:19]
	v_mfma_f32_16x16x32_bf16 v[60:63], v[142:145], v[166:169], v[60:63]
	v_mfma_f32_16x16x32_bf16 v[56:59], v[150:153], v[166:169], v[56:59]
	v_mfma_f32_16x16x32_bf16 v[52:55], v[142:145], v[174:177], v[52:55]
	v_mfma_f32_16x16x32_bf16 v[48:51], v[150:153], v[174:177], v[48:51]
	v_mfma_f32_16x16x32_bf16 v[40:43], v[142:145], v[182:185], v[40:43]
	v_mfma_f32_16x16x32_bf16 v[32:35], v[150:153], v[182:185], v[32:35]
	v_mfma_f32_16x16x32_bf16 v[24:27], v[142:145], v[206:209], v[24:27]
	v_mfma_f32_16x16x32_bf16 v[16:19], v[150:153], v[206:209], v[16:19]
	s_barrier
	s_add_u32 s6, s62, 0x80000
	s_addc_u32 s7, s63, 0
	s_add_i32 s21, s21, s10
	v_lshl_add_u64 v[138:139], s[6:7], 0, v[156:157]
	s_mov_b32 m0, s21
	s_nop 0
	global_load_lds_dwordx4 v[138:139], off
	v_lshl_add_u64 v[138:139], s[6:7], 0, v[128:129]
	s_add_i32 m0, s21, 0x2000
	s_nop 0
	global_load_lds_dwordx4 v[138:139], off
	s_waitcnt vmcnt(6)
	s_barrier
	v_mfma_f32_16x16x32_bf16 v[44:47], v[214:217], v[162:165], v[44:47]
	v_mfma_f32_16x16x32_bf16 v[36:39], v[222:225], v[162:165], v[36:39]
	v_mfma_f32_16x16x32_bf16 v[28:31], v[214:217], v[170:173], v[28:31]
	v_mfma_f32_16x16x32_bf16 v[20:23], v[222:225], v[170:173], v[20:23]
	v_mfma_f32_16x16x32_bf16 v[12:15], v[214:217], v[178:181], v[12:15]
	v_mfma_f32_16x16x32_bf16 v[8:11], v[222:225], v[178:181], v[8:11]
	v_mfma_f32_16x16x32_bf16 v[4:7], v[214:217], v[186:189], v[4:7]
	v_mfma_f32_16x16x32_bf16 v[0:3], v[222:225], v[186:189], v[0:3]
	v_mfma_f32_16x16x32_bf16 v[44:47], v[218:221], v[166:169], v[44:47]
	v_mfma_f32_16x16x32_bf16 v[36:39], v[226:229], v[166:169], v[36:39]
	v_mfma_f32_16x16x32_bf16 v[28:31], v[218:221], v[174:177], v[28:31]
	v_mfma_f32_16x16x32_bf16 v[20:23], v[226:229], v[174:177], v[20:23]
	v_mfma_f32_16x16x32_bf16 v[12:15], v[218:221], v[182:185], v[12:15]
	v_mfma_f32_16x16x32_bf16 v[8:11], v[226:229], v[182:185], v[8:11]
	v_mfma_f32_16x16x32_bf16 v[4:7], v[218:221], v[206:209], v[4:7]
	v_mfma_f32_16x16x32_bf16 v[0:3], v[226:229], v[206:209], v[0:3]
	s_add_i32 s6, 0, 0x18000
	v_add_u32_e32 v150, s6, v136
	s_barrier
	ds_read_b128 v[138:141], v150
	ds_read_b128 v[142:145], v150 offset:1024
	ds_read_b128 v[146:149], v150 offset:2048
	ds_read_b128 v[150:153], v150 offset:3072
	s_add_u32 s2, s2, 0x80000
	s_addc_u32 s3, s3, 0
	s_mov_b32 m0, s25
	v_lshl_add_u64 v[214:215], s[2:3], 0, v[156:157]
	ds_read_b128 v[162:165], v137 offset:32768
	ds_read_b128 v[166:169], v137 offset:33792
	ds_read_b128 v[170:173], v137 offset:34816
	ds_read_b128 v[174:177], v137 offset:35840
	ds_read_b128 v[178:181], v137 offset:36864
	ds_read_b128 v[182:185], v137 offset:37888
	ds_read_b128 v[186:189], v137 offset:38912
	ds_read_b128 v[206:209], v137 offset:39936
	global_load_lds_dwordx4 v[214:215], off
	v_lshl_add_u64 v[214:215], s[2:3], 0, v[128:129]
	s_mov_b32 m0, s34
	s_nop 0
	global_load_lds_dwordx4 v[214:215], off
	s_waitcnt lgkmcnt(8)
	s_barrier
	s_waitcnt lgkmcnt(0)
	s_waitcnt lgkmcnt(0)
	v_mfma_f32_16x16x32_bf16 v[124:127], v[138:141], v[162:165], v[124:127]
	v_mfma_f32_16x16x32_bf16 v[120:123], v[146:149], v[162:165], v[120:123]
	v_mfma_f32_16x16x32_bf16 v[116:119], v[138:141], v[170:173], v[116:119]
	v_mfma_f32_16x16x32_bf16 v[112:115], v[146:149], v[170:173], v[112:115]
	v_mfma_f32_16x16x32_bf16 v[108:111], v[138:141], v[178:181], v[108:111]
	v_mfma_f32_16x16x32_bf16 v[100:103], v[146:149], v[178:181], v[100:103]
	v_mfma_f32_16x16x32_bf16 v[92:95], v[138:141], v[186:189], v[92:95]
	v_mfma_f32_16x16x32_bf16 v[84:87], v[146:149], v[186:189], v[84:87]
	v_mfma_f32_16x16x32_bf16 v[124:127], v[142:145], v[166:169], v[124:127]
	v_mfma_f32_16x16x32_bf16 v[120:123], v[150:153], v[166:169], v[120:123]
	v_mfma_f32_16x16x32_bf16 v[116:119], v[142:145], v[174:177], v[116:119]
	v_mfma_f32_16x16x32_bf16 v[112:115], v[150:153], v[174:177], v[112:115]
	v_mfma_f32_16x16x32_bf16 v[108:111], v[142:145], v[182:185], v[108:111]
	v_mfma_f32_16x16x32_bf16 v[100:103], v[150:153], v[182:185], v[100:103]
	v_mfma_f32_16x16x32_bf16 v[92:95], v[142:145], v[206:209], v[92:95]
	v_mfma_f32_16x16x32_bf16 v[84:87], v[150:153], v[206:209], v[84:87]
	s_barrier
	s_add_i32 s7, 0, 0x1c000
	s_add_i32 s2, s6, s10
	v_add_u32_e32 v161, s7, v136
	v_lshl_add_u64 v[154:155], v[154:155], 0, s[50:51]
	s_mov_b32 m0, s2
	ds_read_b128 v[214:217], v161
	ds_read_b128 v[218:221], v161 offset:1024
	ds_read_b128 v[222:225], v161 offset:2048
	ds_read_b128 v[226:229], v161 offset:3072
	global_load_lds_dwordx4 v[154:155], off
	v_lshl_add_u64 v[154:155], v[230:231], 0, s[50:51]
	s_add_i32 m0, s2, 0x2000
	s_nop 0
	global_load_lds_dwordx4 v[154:155], off
	s_barrier
	s_waitcnt lgkmcnt(0)
	s_waitcnt lgkmcnt(0)
	v_mfma_f32_16x16x32_bf16 v[104:107], v[214:217], v[162:165], v[104:107]
	v_mfma_f32_16x16x32_bf16 v[96:99], v[222:225], v[162:165], v[96:99]
	v_mfma_f32_16x16x32_bf16 v[88:91], v[214:217], v[170:173], v[88:91]
	v_mfma_f32_16x16x32_bf16 v[80:83], v[222:225], v[170:173], v[80:83]
	v_mfma_f32_16x16x32_bf16 v[76:79], v[214:217], v[178:181], v[76:79]
	v_mfma_f32_16x16x32_bf16 v[72:75], v[222:225], v[178:181], v[72:75]
	v_mfma_f32_16x16x32_bf16 v[68:71], v[214:217], v[186:189], v[68:71]
	v_mfma_f32_16x16x32_bf16 v[64:67], v[222:225], v[186:189], v[64:67]
	v_mfma_f32_16x16x32_bf16 v[104:107], v[218:221], v[166:169], v[104:107]
	v_mfma_f32_16x16x32_bf16 v[96:99], v[226:229], v[166:169], v[96:99]
	v_mfma_f32_16x16x32_bf16 v[88:91], v[218:221], v[174:177], v[88:91]
	v_mfma_f32_16x16x32_bf16 v[80:83], v[226:229], v[174:177], v[80:83]
	v_mfma_f32_16x16x32_bf16 v[76:79], v[218:221], v[182:185], v[76:79]
	v_mfma_f32_16x16x32_bf16 v[72:75], v[226:229], v[182:185], v[72:75]
	v_mfma_f32_16x16x32_bf16 v[68:71], v[218:221], v[206:209], v[68:71]
	v_mfma_f32_16x16x32_bf16 v[64:67], v[226:229], v[206:209], v[64:67]
	s_mov_b32 m0, s45
	v_lshl_add_u64 v[154:155], v[232:233], 0, s[50:51]
	s_barrier
	ds_read_b128 v[162:165], v137 offset:49152
	ds_read_b128 v[166:169], v137 offset:50176
	ds_read_b128 v[170:173], v137 offset:51200
	ds_read_b128 v[174:177], v137 offset:52224
	ds_read_b128 v[178:181], v137 offset:53248
	ds_read_b128 v[182:185], v137 offset:54272
	ds_read_b128 v[186:189], v137 offset:55296
	ds_read_b128 v[206:209], v137 offset:56320
	global_load_lds_dwordx4 v[154:155], off
	v_lshl_add_u64 v[154:155], v[234:235], 0, s[50:51]
	s_mov_b32 m0, s53
	s_nop 0
	global_load_lds_dwordx4 v[154:155], off
	s_barrier
	s_waitcnt lgkmcnt(0)
	s_waitcnt lgkmcnt(0)
	v_mfma_f32_16x16x32_bf16 v[60:63], v[138:141], v[162:165], v[60:63]
	v_mfma_f32_16x16x32_bf16 v[56:59], v[146:149], v[162:165], v[56:59]
	v_mfma_f32_16x16x32_bf16 v[52:55], v[138:141], v[170:173], v[52:55]
	v_mfma_f32_16x16x32_bf16 v[48:51], v[146:149], v[170:173], v[48:51]
	v_mfma_f32_16x16x32_bf16 v[40:43], v[138:141], v[178:181], v[40:43]
	v_mfma_f32_16x16x32_bf16 v[32:35], v[146:149], v[178:181], v[32:35]
	v_mfma_f32_16x16x32_bf16 v[24:27], v[138:141], v[186:189], v[24:27]
	v_mfma_f32_16x16x32_bf16 v[16:19], v[146:149], v[186:189], v[16:19]
	v_mfma_f32_16x16x32_bf16 v[60:63], v[142:145], v[166:169], v[60:63]
	v_mfma_f32_16x16x32_bf16 v[56:59], v[150:153], v[166:169], v[56:59]
	v_mfma_f32_16x16x32_bf16 v[52:55], v[142:145], v[174:177], v[52:55]
	v_mfma_f32_16x16x32_bf16 v[48:51], v[150:153], v[174:177], v[48:51]
	v_mfma_f32_16x16x32_bf16 v[40:43], v[142:145], v[182:185], v[40:43]
	v_mfma_f32_16x16x32_bf16 v[32:35], v[150:153], v[182:185], v[32:35]
	v_mfma_f32_16x16x32_bf16 v[24:27], v[142:145], v[206:209], v[24:27]
	v_mfma_f32_16x16x32_bf16 v[16:19], v[150:153], v[206:209], v[16:19]
	s_barrier
	s_add_u32 s2, s62, 0x80080
	s_addc_u32 s3, s63, 0
	s_add_i32 s6, s7, s10
	v_lshl_add_u64 v[138:139], s[2:3], 0, v[156:157]
	s_mov_b32 m0, s6
	s_nop 0
	global_load_lds_dwordx4 v[138:139], off
	v_lshl_add_u64 v[138:139], s[2:3], 0, v[128:129]
	s_add_i32 m0, s6, 0x2000
	s_nop 0
	global_load_lds_dwordx4 v[138:139], off
	s_waitcnt vmcnt(6)
	s_barrier
	v_mfma_f32_16x16x32_bf16 v[44:47], v[214:217], v[162:165], v[44:47]
	v_mfma_f32_16x16x32_bf16 v[36:39], v[222:225], v[162:165], v[36:39]
	v_mfma_f32_16x16x32_bf16 v[28:31], v[214:217], v[170:173], v[28:31]
	v_mfma_f32_16x16x32_bf16 v[20:23], v[222:225], v[170:173], v[20:23]
	v_mfma_f32_16x16x32_bf16 v[12:15], v[214:217], v[178:181], v[12:15]
	v_mfma_f32_16x16x32_bf16 v[8:11], v[222:225], v[178:181], v[8:11]
	v_mfma_f32_16x16x32_bf16 v[4:7], v[214:217], v[186:189], v[4:7]
	v_mfma_f32_16x16x32_bf16 v[0:3], v[222:225], v[186:189], v[0:3]
	v_mfma_f32_16x16x32_bf16 v[44:47], v[218:221], v[166:169], v[44:47]
	v_mfma_f32_16x16x32_bf16 v[36:39], v[226:229], v[166:169], v[36:39]
	v_mfma_f32_16x16x32_bf16 v[28:31], v[218:221], v[174:177], v[28:31]
	v_mfma_f32_16x16x32_bf16 v[20:23], v[226:229], v[174:177], v[20:23]
	v_mfma_f32_16x16x32_bf16 v[12:15], v[218:221], v[182:185], v[12:15]
	v_mfma_f32_16x16x32_bf16 v[8:11], v[226:229], v[182:185], v[8:11]
	v_mfma_f32_16x16x32_bf16 v[4:7], v[218:221], v[206:209], v[4:7]
	v_mfma_f32_16x16x32_bf16 v[0:3], v[226:229], v[206:209], v[0:3]
	s_add_i32 s54, s54, 2
	s_cmp_gt_u32 s54, 29
	s_mov_b64 s[6:7], s[60:61]
	s_barrier
	s_cbranch_scc0 .LBB0_286

.LBB0_325:
	s_add_i32 s83, s83, 1
	s_mul_i32 s6, s83, s18
	s_add_i32 s10, s6, s20
	s_cmpk_lt_i32 s10, 0x3b8
	s_cselect_b64 s[6:7], -1, 0
	s_cmpk_gt_i32 s10, 0x3b7
	s_cselect_b64 s[68:69], -1, 0
	s_and_b64 s[24:25], s[6:7], exec
	s_cselect_b32 s10, s10, 0
	s_ashr_i32 s21, s10, 31
	s_lshr_b32 s21, s21, 29
	s_add_i32 s21, s10, s21
	s_ashr_i32 s24, s21, 3
	s_and_b32 s21, s21, -8
	s_sub_i32 s10, s10, s21
	s_cmp_lt_i32 s10, 0
	s_movk_i32 s21, 0x78
	s_cselect_b32 s21, s21, 0x77
	s_mul_i32 s10, s21, s10
	s_add_i32 s21, s10, s24
	s_mul_hi_i32 s10, s21, 0x92492493
	s_add_i32 s10, s10, s21
	s_lshr_b32 s24, s10, 31
	s_ashr_i32 s10, s10, 4
	s_add_i32 s25, s10, s24
	s_lshl_b32 s37, s25, 2
	s_sub_i32 s10, 0x88, s37
	s_min_i32 s44, s10, 4
	s_abs_i32 s45, s44
	v_cvt_f32_u32_e32 v0, s45
	s_sub_i32 s46, 0, s45
	s_mul_i32 s25, s25, 28
	s_sub_i32 s21, s21, s25
	v_rcp_iflag_f32_e32 v0, v0
	s_mov_b32 s24, s36
	s_abs_i32 s36, s21
	s_xor_b32 s25, s21, s44
	v_mul_f32_e32 v0, 0x4f7ffffe, v0
	v_cvt_u32_f32_e32 v0, v0
	s_mov_b64 s[42:43], s[48:49]
	s_ashr_i32 s25, s25, 31
	s_mov_b32 s10, s66
	v_readfirstlane_b32 s47, v0
	s_mul_i32 s46, s46, s47
	s_mul_hi_u32 s46, s47, s46
	s_add_i32 s47, s47, s46
	s_mul_hi_u32 s46, s36, s47
	s_mul_i32 s47, s46, s45
	s_sub_i32 s36, s36, s47
	s_add_i32 s47, s46, 1
	s_sub_i32 s48, s36, s45
	s_cmp_ge_u32 s36, s45
	s_cselect_b32 s46, s47, s46
	s_cselect_b32 s36, s48, s36
	s_add_i32 s47, s46, 1
	s_cmp_ge_u32 s36, s45
	s_cselect_b32 s36, s47, s46
	s_xor_b32 s36, s36, s25
	s_sub_i32 s66, s36, s25
	s_mul_i32 s25, s66, s44
	s_sub_i32 s21, s21, s25
	s_add_i32 s36, s37, s21
	s_ashr_i32 s37, s36, 31
	s_lshl_b64 s[44:45], s[36:37], 19
	s_mov_b64 s[2:3], s[62:63]
	s_add_u32 s62, s58, s44
	s_addc_u32 s63, s59, s45
	s_and_b64 s[44:45], s[6:7], exec
	s_cselect_b32 s25, s63, s3
	s_cselect_b32 s37, s62, s2
	s_ashr_i32 s67, s66, 31
	s_lshl_b64 s[44:45], s[66:67], 19
	s_add_u32 s48, s19, s44
	s_addc_u32 s49, s34, s45
	s_and_b64 s[6:7], s[6:7], exec
	s_cselect_b32 s44, s49, s43
	s_cselect_b32 s45, s48, s42
	s_add_u32 s46, s42, 0x100
	s_addc_u32 s47, s43, 0
	s_add_u32 s6, s2, 0x40080
	s_addc_u32 s7, s3, 0
	s_mov_b32 s60, -2
	s_add_u32 s2, s6, 0xfffc0080
	s_addc_u32 s3, s7, -1
	s_add_i32 s21, 0, 0x10000
	v_add_u32_e32 v154, s21, v141
	ds_read_b128 v[136:139], v154
	ds_read_b128 v[150:153], v154 offset:1024
	ds_read_b128 v[162:165], v154 offset:2048
	ds_read_b128 v[166:169], v154 offset:3072
	s_cmp_eq_u32 s60, 12
	s_cselect_b32 s3, s25, s3
	s_cselect_b32 s2, s37, s2
	s_cselect_b32 s43, s44, s47
	s_cselect_b32 s42, s45, s46
	v_lshl_add_u64 v[154:155], s[6:7], 0, v[134:135]
	s_add_i32 m0, s53, 0xc000
	ds_read_b128 v[170:173], v149
	ds_read_b128 v[174:177], v149 offset:1024
	ds_read_b128 v[178:181], v149 offset:2048
	ds_read_b128 v[182:185], v149 offset:3072
	ds_read_b128 v[186:189], v149 offset:4096
	ds_read_b128 v[206:209], v149 offset:5120
	ds_read_b128 v[214:217], v149 offset:6144
	ds_read_b128 v[218:221], v149 offset:7168
	global_load_lds_dwordx4 v[154:155], off
	v_lshl_add_u64 v[154:155], s[6:7], 0, v[132:133]
	s_add_i32 m0, s53, 0xe000
	s_nop 0
	global_load_lds_dwordx4 v[154:155], off
	s_waitcnt lgkmcnt(8)
	s_barrier
	s_waitcnt lgkmcnt(0)
	s_waitcnt lgkmcnt(0)
	v_mfma_f32_16x16x32_bf16 v[124:127], v[136:139], v[170:173], 0
	v_mfma_f32_16x16x32_bf16 v[120:123], v[162:165], v[170:173], 0
	v_mfma_f32_16x16x32_bf16 v[108:111], v[136:139], v[178:181], 0
	v_mfma_f32_16x16x32_bf16 v[104:107], v[162:165], v[178:181], 0
	v_mfma_f32_16x16x32_bf16 v[92:95], v[136:139], v[186:189], 0
	v_mfma_f32_16x16x32_bf16 v[88:91], v[162:165], v[186:189], 0
	v_mfma_f32_16x16x32_bf16 v[76:79], v[136:139], v[214:217], 0
	v_mfma_f32_16x16x32_bf16 v[72:75], v[162:165], v[214:217], 0
	v_mfma_f32_16x16x32_bf16 v[124:127], v[150:153], v[174:177], v[124:127]
	v_mfma_f32_16x16x32_bf16 v[120:123], v[166:169], v[174:177], v[120:123]
	v_mfma_f32_16x16x32_bf16 v[108:111], v[150:153], v[182:185], v[108:111]
	v_mfma_f32_16x16x32_bf16 v[104:107], v[166:169], v[182:185], v[104:107]
	v_mfma_f32_16x16x32_bf16 v[92:95], v[150:153], v[206:209], v[92:95]
	v_mfma_f32_16x16x32_bf16 v[88:91], v[166:169], v[206:209], v[88:91]
	v_mfma_f32_16x16x32_bf16 v[76:79], v[150:153], v[218:221], v[76:79]
	v_mfma_f32_16x16x32_bf16 v[72:75], v[166:169], v[218:221], v[72:75]
	s_barrier
	s_add_i32 s61, 0, 0x14000
	v_add_u32_e32 v154, s61, v141
	s_add_i32 s21, s21, s35
	ds_read_b128 v[222:225], v154
	ds_read_b128 v[226:229], v154 offset:1024
	ds_read_b128 v[230:233], v154 offset:2048
	ds_read_b128 v[234:237], v154 offset:3072
	v_lshl_add_u64 v[154:155], s[42:43], 0, v[130:131]
	s_mov_b32 m0, s21
	v_lshl_add_u64 v[238:239], s[42:43], 0, v[128:129]
	global_load_lds_dwordx4 v[154:155], off
	s_add_i32 m0, s21, 0x2000
	s_nop 0
	global_load_lds_dwordx4 v[238:239], off
	s_barrier
	s_waitcnt lgkmcnt(0)
	s_waitcnt lgkmcnt(0)
	v_mfma_f32_16x16x32_bf16 v[116:119], v[222:225], v[170:173], 0
	v_mfma_f32_16x16x32_bf16 v[112:115], v[230:233], v[170:173], 0
	v_mfma_f32_16x16x32_bf16 v[100:103], v[222:225], v[178:181], 0
	v_mfma_f32_16x16x32_bf16 v[96:99], v[230:233], v[178:181], 0
	v_mfma_f32_16x16x32_bf16 v[84:87], v[222:225], v[186:189], 0
	v_mfma_f32_16x16x32_bf16 v[80:83], v[230:233], v[186:189], 0
	v_mfma_f32_16x16x32_bf16 v[68:71], v[222:225], v[214:217], 0
	v_mfma_f32_16x16x32_bf16 v[64:67], v[230:233], v[214:217], 0
	v_mfma_f32_16x16x32_bf16 v[116:119], v[226:229], v[174:177], v[116:119]
	v_mfma_f32_16x16x32_bf16 v[112:115], v[234:237], v[174:177], v[112:115]
	v_mfma_f32_16x16x32_bf16 v[100:103], v[226:229], v[182:185], v[100:103]
	v_mfma_f32_16x16x32_bf16 v[96:99], v[234:237], v[182:185], v[96:99]
	v_mfma_f32_16x16x32_bf16 v[84:87], v[226:229], v[206:209], v[84:87]
	v_mfma_f32_16x16x32_bf16 v[80:83], v[234:237], v[206:209], v[80:83]
	v_mfma_f32_16x16x32_bf16 v[68:71], v[226:229], v[218:221], v[68:71]
	v_mfma_f32_16x16x32_bf16 v[64:67], v[234:237], v[218:221], v[64:67]
	s_mov_b32 m0, s53
	v_lshl_add_u64 v[240:241], s[2:3], 0, v[130:131]
	s_barrier
	ds_read_b128 v[170:173], v149 offset:16384
	ds_read_b128 v[174:177], v149 offset:17408
	ds_read_b128 v[178:181], v149 offset:18432
	ds_read_b128 v[182:185], v149 offset:19456
	ds_read_b128 v[186:189], v149 offset:20480
	ds_read_b128 v[206:209], v149 offset:21504
	ds_read_b128 v[214:217], v149 offset:22528
	ds_read_b128 v[218:221], v149 offset:23552
	global_load_lds_dwordx4 v[240:241], off
	v_lshl_add_u64 v[242:243], s[2:3], 0, v[128:129]
	s_mov_b32 m0, s54
	s_nop 0
	global_load_lds_dwordx4 v[242:243], off
	s_barrier
	s_waitcnt lgkmcnt(0)
	s_waitcnt lgkmcnt(0)
	v_mfma_f32_16x16x32_bf16 v[60:63], v[136:139], v[170:173], 0
	v_mfma_f32_16x16x32_bf16 v[56:59], v[162:165], v[170:173], 0
	v_mfma_f32_16x16x32_bf16 v[44:47], v[136:139], v[178:181], 0
	v_mfma_f32_16x16x32_bf16 v[40:43], v[162:165], v[178:181], 0
	v_mfma_f32_16x16x32_bf16 v[28:31], v[136:139], v[186:189], 0
	v_mfma_f32_16x16x32_bf16 v[24:27], v[162:165], v[186:189], 0
	v_mfma_f32_16x16x32_bf16 v[12:15], v[136:139], v[214:217], 0
	v_mfma_f32_16x16x32_bf16 v[8:11], v[162:165], v[214:217], 0
	v_mfma_f32_16x16x32_bf16 v[60:63], v[150:153], v[174:177], v[60:63]
	v_mfma_f32_16x16x32_bf16 v[56:59], v[166:169], v[174:177], v[56:59]
	v_mfma_f32_16x16x32_bf16 v[44:47], v[150:153], v[182:185], v[44:47]
	v_mfma_f32_16x16x32_bf16 v[40:43], v[166:169], v[182:185], v[40:43]
	v_mfma_f32_16x16x32_bf16 v[28:31], v[150:153], v[206:209], v[28:31]
	v_mfma_f32_16x16x32_bf16 v[24:27], v[166:169], v[206:209], v[24:27]
	v_mfma_f32_16x16x32_bf16 v[12:15], v[150:153], v[218:221], v[12:15]
	v_mfma_f32_16x16x32_bf16 v[8:11], v[166:169], v[218:221], v[8:11]
	s_barrier
	s_add_u32 s80, s42, 0x40000
	s_addc_u32 s81, s43, 0
	s_add_i32 s21, s61, s35
	v_lshl_add_u64 v[136:137], s[80:81], 0, v[130:131]
	s_mov_b32 m0, s21
	s_nop 0
	global_load_lds_dwordx4 v[136:137], off
	v_lshl_add_u64 v[136:137], s[80:81], 0, v[128:129]
	s_add_i32 m0, s21, 0x2000
	s_nop 0
	global_load_lds_dwordx4 v[136:137], off
	s_waitcnt vmcnt(6)
	s_barrier
	v_mfma_f32_16x16x32_bf16 v[52:55], v[222:225], v[170:173], 0
	v_mfma_f32_16x16x32_bf16 v[48:51], v[230:233], v[170:173], 0
	v_mfma_f32_16x16x32_bf16 v[36:39], v[222:225], v[178:181], 0
	v_mfma_f32_16x16x32_bf16 v[32:35], v[230:233], v[178:181], 0
	v_mfma_f32_16x16x32_bf16 v[20:23], v[222:225], v[186:189], 0
	v_mfma_f32_16x16x32_bf16 v[16:19], v[230:233], v[186:189], 0
	v_mfma_f32_16x16x32_bf16 v[4:7], v[222:225], v[214:217], 0
	v_mfma_f32_16x16x32_bf16 v[0:3], v[230:233], v[214:217], 0
	v_mfma_f32_16x16x32_bf16 v[52:55], v[226:229], v[174:177], v[52:55]
	v_mfma_f32_16x16x32_bf16 v[48:51], v[234:237], v[174:177], v[48:51]
	v_mfma_f32_16x16x32_bf16 v[36:39], v[226:229], v[182:185], v[36:39]
	v_mfma_f32_16x16x32_bf16 v[32:35], v[234:237], v[182:185], v[32:35]
	v_mfma_f32_16x16x32_bf16 v[20:23], v[226:229], v[206:209], v[20:23]
	v_mfma_f32_16x16x32_bf16 v[16:19], v[234:237], v[206:209], v[16:19]
	v_mfma_f32_16x16x32_bf16 v[4:7], v[226:229], v[218:221], v[4:7]
	v_mfma_f32_16x16x32_bf16 v[0:3], v[234:237], v[218:221], v[0:3]
	s_add_i32 s21, 0, 0x18000
	v_add_u32_e32 v156, s21, v141
	s_barrier
	ds_read_b128 v[136:139], v156
	ds_read_b128 v[150:153], v156 offset:1024
	ds_read_b128 v[162:165], v156 offset:2048
	ds_read_b128 v[166:169], v156 offset:3072
	s_add_u32 s2, s2, 0x40000
	s_addc_u32 s3, s3, 0
	s_mov_b32 m0, s55
	v_lshl_add_u64 v[222:223], s[2:3], 0, v[130:131]
	ds_read_b128 v[170:173], v149 offset:32768
	ds_read_b128 v[174:177], v149 offset:33792
	ds_read_b128 v[178:181], v149 offset:34816
	ds_read_b128 v[182:185], v149 offset:35840
	ds_read_b128 v[186:189], v149 offset:36864
	ds_read_b128 v[206:209], v149 offset:37888
	ds_read_b128 v[214:217], v149 offset:38912
	ds_read_b128 v[218:221], v149 offset:39936
	global_load_lds_dwordx4 v[222:223], off
	v_lshl_add_u64 v[222:223], s[2:3], 0, v[128:129]
	s_mov_b32 m0, s78
	s_nop 0
	global_load_lds_dwordx4 v[222:223], off
	s_waitcnt lgkmcnt(8)
	s_barrier
	s_waitcnt lgkmcnt(0)
	s_waitcnt lgkmcnt(0)
	v_mfma_f32_16x16x32_bf16 v[124:127], v[136:139], v[170:173], v[124:127]
	v_mfma_f32_16x16x32_bf16 v[120:123], v[162:165], v[170:173], v[120:123]
	v_mfma_f32_16x16x32_bf16 v[108:111], v[136:139], v[178:181], v[108:111]
	v_mfma_f32_16x16x32_bf16 v[104:107], v[162:165], v[178:181], v[104:107]
	v_mfma_f32_16x16x32_bf16 v[92:95], v[136:139], v[186:189], v[92:95]
	v_mfma_f32_16x16x32_bf16 v[88:91], v[162:165], v[186:189], v[88:91]
	v_mfma_f32_16x16x32_bf16 v[76:79], v[136:139], v[214:217], v[76:79]
	v_mfma_f32_16x16x32_bf16 v[72:75], v[162:165], v[214:217], v[72:75]
	v_mfma_f32_16x16x32_bf16 v[124:127], v[150:153], v[174:177], v[124:127]
	v_mfma_f32_16x16x32_bf16 v[120:123], v[166:169], v[174:177], v[120:123]
	v_mfma_f32_16x16x32_bf16 v[108:111], v[150:153], v[182:185], v[108:111]
	v_mfma_f32_16x16x32_bf16 v[104:107], v[166:169], v[182:185], v[104:107]
	v_mfma_f32_16x16x32_bf16 v[92:95], v[150:153], v[206:209], v[92:95]
	v_mfma_f32_16x16x32_bf16 v[88:91], v[166:169], v[206:209], v[88:91]
	v_mfma_f32_16x16x32_bf16 v[76:79], v[150:153], v[218:221], v[76:79]
	v_mfma_f32_16x16x32_bf16 v[72:75], v[166:169], v[218:221], v[72:75]
	s_barrier
	s_add_i32 s61, 0, 0x1c000
	s_add_i32 s2, s21, s35
	v_add_u32_e32 v156, s61, v141
	v_lshl_add_u64 v[154:155], v[154:155], 0, s[50:51]
	s_mov_b32 m0, s2
	ds_read_b128 v[222:225], v156
	ds_read_b128 v[226:229], v156 offset:1024
	ds_read_b128 v[230:233], v156 offset:2048
	ds_read_b128 v[234:237], v156 offset:3072
	global_load_lds_dwordx4 v[154:155], off
	v_lshl_add_u64 v[154:155], v[238:239], 0, s[50:51]
	s_add_i32 m0, s2, 0x2000
	s_nop 0
	global_load_lds_dwordx4 v[154:155], off
	s_barrier
	s_waitcnt lgkmcnt(0)
	s_waitcnt lgkmcnt(0)
	v_mfma_f32_16x16x32_bf16 v[116:119], v[222:225], v[170:173], v[116:119]
	v_mfma_f32_16x16x32_bf16 v[112:115], v[230:233], v[170:173], v[112:115]
	v_mfma_f32_16x16x32_bf16 v[100:103], v[222:225], v[178:181], v[100:103]
	v_mfma_f32_16x16x32_bf16 v[96:99], v[230:233], v[178:181], v[96:99]
	v_mfma_f32_16x16x32_bf16 v[84:87], v[222:225], v[186:189], v[84:87]
	v_mfma_f32_16x16x32_bf16 v[80:83], v[230:233], v[186:189], v[80:83]
	v_mfma_f32_16x16x32_bf16 v[68:71], v[222:225], v[214:217], v[68:71]
	v_mfma_f32_16x16x32_bf16 v[64:67], v[230:233], v[214:217], v[64:67]
	v_mfma_f32_16x16x32_bf16 v[116:119], v[226:229], v[174:177], v[116:119]
	v_mfma_f32_16x16x32_bf16 v[112:115], v[234:237], v[174:177], v[112:115]
	v_mfma_f32_16x16x32_bf16 v[100:103], v[226:229], v[182:185], v[100:103]
	v_mfma_f32_16x16x32_bf16 v[96:99], v[234:237], v[182:185], v[96:99]
	v_mfma_f32_16x16x32_bf16 v[84:87], v[226:229], v[206:209], v[84:87]
	v_mfma_f32_16x16x32_bf16 v[80:83], v[234:237], v[206:209], v[80:83]
	v_mfma_f32_16x16x32_bf16 v[68:71], v[226:229], v[218:221], v[68:71]
	v_mfma_f32_16x16x32_bf16 v[64:67], v[234:237], v[218:221], v[64:67]
	s_mov_b32 m0, s79
	v_lshl_add_u64 v[154:155], v[240:241], 0, s[50:51]
	s_barrier
	ds_read_b128 v[170:173], v149 offset:49152
	ds_read_b128 v[174:177], v149 offset:50176
	ds_read_b128 v[178:181], v149 offset:51200
	ds_read_b128 v[182:185], v149 offset:52224
	ds_read_b128 v[186:189], v149 offset:53248
	ds_read_b128 v[206:209], v149 offset:54272
	ds_read_b128 v[214:217], v149 offset:55296
	ds_read_b128 v[218:221], v149 offset:56320
	global_load_lds_dwordx4 v[154:155], off
	v_lshl_add_u64 v[154:155], v[242:243], 0, s[50:51]
	s_mov_b32 m0, s82
	s_nop 0
	global_load_lds_dwordx4 v[154:155], off
	s_barrier
	s_waitcnt lgkmcnt(0)
	s_waitcnt lgkmcnt(0)
	v_mfma_f32_16x16x32_bf16 v[60:63], v[136:139], v[170:173], v[60:63]
	v_mfma_f32_16x16x32_bf16 v[56:59], v[162:165], v[170:173], v[56:59]
	v_mfma_f32_16x16x32_bf16 v[44:47], v[136:139], v[178:181], v[44:47]
	v_mfma_f32_16x16x32_bf16 v[40:43], v[162:165], v[178:181], v[40:43]
	v_mfma_f32_16x16x32_bf16 v[28:31], v[136:139], v[186:189], v[28:31]
	v_mfma_f32_16x16x32_bf16 v[24:27], v[162:165], v[186:189], v[24:27]
	v_mfma_f32_16x16x32_bf16 v[12:15], v[136:139], v[214:217], v[12:15]
	v_mfma_f32_16x16x32_bf16 v[8:11], v[162:165], v[214:217], v[8:11]
	v_mfma_f32_16x16x32_bf16 v[60:63], v[150:153], v[174:177], v[60:63]
	v_mfma_f32_16x16x32_bf16 v[56:59], v[166:169], v[174:177], v[56:59]
	v_mfma_f32_16x16x32_bf16 v[44:47], v[150:153], v[182:185], v[44:47]
	v_mfma_f32_16x16x32_bf16 v[40:43], v[166:169], v[182:185], v[40:43]
	v_mfma_f32_16x16x32_bf16 v[28:31], v[150:153], v[206:209], v[28:31]
	v_mfma_f32_16x16x32_bf16 v[24:27], v[166:169], v[206:209], v[24:27]
	v_mfma_f32_16x16x32_bf16 v[12:15], v[150:153], v[218:221], v[12:15]
	v_mfma_f32_16x16x32_bf16 v[8:11], v[166:169], v[218:221], v[8:11]
	s_barrier
	s_add_u32 s2, s42, 0x40080
	s_addc_u32 s3, s43, 0
	s_add_i32 s21, s61, s35
	v_lshl_add_u64 v[136:137], s[2:3], 0, v[130:131]
	s_mov_b32 m0, s21
	s_nop 0
	global_load_lds_dwordx4 v[136:137], off
	v_lshl_add_u64 v[136:137], s[2:3], 0, v[128:129]
	s_add_i32 m0, s21, 0x2000
	s_nop 0
	global_load_lds_dwordx4 v[136:137], off
	s_waitcnt vmcnt(6)
	s_barrier
	v_mfma_f32_16x16x32_bf16 v[52:55], v[222:225], v[170:173], v[52:55]
	v_mfma_f32_16x16x32_bf16 v[48:51], v[230:233], v[170:173], v[48:51]
	v_mfma_f32_16x16x32_bf16 v[36:39], v[222:225], v[178:181], v[36:39]
	v_mfma_f32_16x16x32_bf16 v[32:35], v[230:233], v[178:181], v[32:35]
	v_mfma_f32_16x16x32_bf16 v[20:23], v[222:225], v[186:189], v[20:23]
	v_mfma_f32_16x16x32_bf16 v[16:19], v[230:233], v[186:189], v[16:19]
	v_mfma_f32_16x16x32_bf16 v[4:7], v[222:225], v[214:217], v[4:7]
	v_mfma_f32_16x16x32_bf16 v[0:3], v[230:233], v[214:217], v[0:3]
	v_mfma_f32_16x16x32_bf16 v[52:55], v[226:229], v[174:177], v[52:55]
	v_mfma_f32_16x16x32_bf16 v[48:51], v[234:237], v[174:177], v[48:51]
	v_mfma_f32_16x16x32_bf16 v[36:39], v[226:229], v[182:185], v[36:39]
	v_mfma_f32_16x16x32_bf16 v[32:35], v[234:237], v[182:185], v[32:35]
	v_mfma_f32_16x16x32_bf16 v[20:23], v[226:229], v[206:209], v[20:23]
	v_mfma_f32_16x16x32_bf16 v[16:19], v[234:237], v[206:209], v[16:19]
	v_mfma_f32_16x16x32_bf16 v[4:7], v[226:229], v[218:221], v[4:7]
	v_mfma_f32_16x16x32_bf16 v[0:3], v[234:237], v[218:221], v[0:3]
	s_add_i32 s60, s60, 2
	s_add_u32 s46, s46, 0x100
	s_addc_u32 s47, s47, 0
	s_add_u32 s6, s6, 0x100
	s_addc_u32 s7, s7, 0
	s_cmp_gt_u32 s60, 13
	s_barrier
	s_cbranch_scc1 .Lpost_326
.LBB0_326:
	s_add_u32 s2, s6, 0xfffc0080
	s_addc_u32 s3, s7, -1
	s_add_i32 s21, 0, 0x10000
	v_add_u32_e32 v154, s21, v141
	ds_read_b128 v[136:139], v154
	ds_read_b128 v[150:153], v154 offset:1024
	ds_read_b128 v[162:165], v154 offset:2048
	ds_read_b128 v[166:169], v154 offset:3072
	s_cmp_eq_u32 s60, 12
	s_cselect_b32 s3, s25, s3
	s_cselect_b32 s2, s37, s2
	s_cselect_b32 s43, s44, s47
	s_cselect_b32 s42, s45, s46
	v_lshl_add_u64 v[154:155], s[6:7], 0, v[134:135]
	s_add_i32 m0, s53, 0xc000
	ds_read_b128 v[170:173], v149
	ds_read_b128 v[174:177], v149 offset:1024
	ds_read_b128 v[178:181], v149 offset:2048
	ds_read_b128 v[182:185], v149 offset:3072
	ds_read_b128 v[186:189], v149 offset:4096
	ds_read_b128 v[206:209], v149 offset:5120
	ds_read_b128 v[214:217], v149 offset:6144
	ds_read_b128 v[218:221], v149 offset:7168
	global_load_lds_dwordx4 v[154:155], off
	v_lshl_add_u64 v[154:155], s[6:7], 0, v[132:133]
	s_add_i32 m0, s53, 0xe000
	s_nop 0
	global_load_lds_dwordx4 v[154:155], off
	s_waitcnt lgkmcnt(8)
	s_barrier
	s_waitcnt lgkmcnt(0)
	s_waitcnt lgkmcnt(0)
	v_mfma_f32_16x16x32_bf16 v[124:127], v[136:139], v[170:173], v[124:127]
	v_mfma_f32_16x16x32_bf16 v[120:123], v[162:165], v[170:173], v[120:123]
	v_mfma_f32_16x16x32_bf16 v[108:111], v[136:139], v[178:181], v[108:111]
	v_mfma_f32_16x16x32_bf16 v[104:107], v[162:165], v[178:181], v[104:107]
	v_mfma_f32_16x16x32_bf16 v[92:95], v[136:139], v[186:189], v[92:95]
	v_mfma_f32_16x16x32_bf16 v[88:91], v[162:165], v[186:189], v[88:91]
	v_mfma_f32_16x16x32_bf16 v[76:79], v[136:139], v[214:217], v[76:79]
	v_mfma_f32_16x16x32_bf16 v[72:75], v[162:165], v[214:217], v[72:75]
	v_mfma_f32_16x16x32_bf16 v[124:127], v[150:153], v[174:177], v[124:127]
	v_mfma_f32_16x16x32_bf16 v[120:123], v[166:169], v[174:177], v[120:123]
	v_mfma_f32_16x16x32_bf16 v[108:111], v[150:153], v[182:185], v[108:111]
	v_mfma_f32_16x16x32_bf16 v[104:107], v[166:169], v[182:185], v[104:107]
	v_mfma_f32_16x16x32_bf16 v[92:95], v[150:153], v[206:209], v[92:95]
	v_mfma_f32_16x16x32_bf16 v[88:91], v[166:169], v[206:209], v[88:91]
	v_mfma_f32_16x16x32_bf16 v[76:79], v[150:153], v[218:221], v[76:79]
	v_mfma_f32_16x16x32_bf16 v[72:75], v[166:169], v[218:221], v[72:75]
	s_barrier
	s_add_i32 s61, 0, 0x14000
	v_add_u32_e32 v154, s61, v141
	s_add_i32 s21, s21, s35
	ds_read_b128 v[222:225], v154
	ds_read_b128 v[226:229], v154 offset:1024
	ds_read_b128 v[230:233], v154 offset:2048
	ds_read_b128 v[234:237], v154 offset:3072
	v_lshl_add_u64 v[154:155], s[42:43], 0, v[130:131]
	s_mov_b32 m0, s21
	v_lshl_add_u64 v[238:239], s[42:43], 0, v[128:129]
	global_load_lds_dwordx4 v[154:155], off
	s_add_i32 m0, s21, 0x2000
	s_nop 0
	global_load_lds_dwordx4 v[238:239], off
	s_barrier
	s_waitcnt lgkmcnt(0)
	s_waitcnt lgkmcnt(0)
	v_mfma_f32_16x16x32_bf16 v[116:119], v[222:225], v[170:173], v[116:119]
	v_mfma_f32_16x16x32_bf16 v[112:115], v[230:233], v[170:173], v[112:115]
	v_mfma_f32_16x16x32_bf16 v[100:103], v[222:225], v[178:181], v[100:103]
	v_mfma_f32_16x16x32_bf16 v[96:99], v[230:233], v[178:181], v[96:99]
	v_mfma_f32_16x16x32_bf16 v[84:87], v[222:225], v[186:189], v[84:87]
	v_mfma_f32_16x16x32_bf16 v[80:83], v[230:233], v[186:189], v[80:83]
	v_mfma_f32_16x16x32_bf16 v[68:71], v[222:225], v[214:217], v[68:71]
	v_mfma_f32_16x16x32_bf16 v[64:67], v[230:233], v[214:217], v[64:67]
	v_mfma_f32_16x16x32_bf16 v[116:119], v[226:229], v[174:177], v[116:119]
	v_mfma_f32_16x16x32_bf16 v[112:115], v[234:237], v[174:177], v[112:115]
	v_mfma_f32_16x16x32_bf16 v[100:103], v[226:229], v[182:185], v[100:103]
	v_mfma_f32_16x16x32_bf16 v[96:99], v[234:237], v[182:185], v[96:99]
	v_mfma_f32_16x16x32_bf16 v[84:87], v[226:229], v[206:209], v[84:87]
	v_mfma_f32_16x16x32_bf16 v[80:83], v[234:237], v[206:209], v[80:83]
	v_mfma_f32_16x16x32_bf16 v[68:71], v[226:229], v[218:221], v[68:71]
	v_mfma_f32_16x16x32_bf16 v[64:67], v[234:237], v[218:221], v[64:67]
	s_mov_b32 m0, s53
	v_lshl_add_u64 v[240:241], s[2:3], 0, v[130:131]
	s_barrier
	ds_read_b128 v[170:173], v149 offset:16384
	ds_read_b128 v[174:177], v149 offset:17408
	ds_read_b128 v[178:181], v149 offset:18432
	ds_read_b128 v[182:185], v149 offset:19456
	ds_read_b128 v[186:189], v149 offset:20480
	ds_read_b128 v[206:209], v149 offset:21504
	ds_read_b128 v[214:217], v149 offset:22528
	ds_read_b128 v[218:221], v149 offset:23552
	global_load_lds_dwordx4 v[240:241], off
	v_lshl_add_u64 v[242:243], s[2:3], 0, v[128:129]
	s_mov_b32 m0, s54
	s_nop 0
	global_load_lds_dwordx4 v[242:243], off
	s_barrier
	s_waitcnt lgkmcnt(0)
	s_waitcnt lgkmcnt(0)
	v_mfma_f32_16x16x32_bf16 v[60:63], v[136:139], v[170:173], v[60:63]
	v_mfma_f32_16x16x32_bf16 v[56:59], v[162:165], v[170:173], v[56:59]
	v_mfma_f32_16x16x32_bf16 v[44:47], v[136:139], v[178:181], v[44:47]
	v_mfma_f32_16x16x32_bf16 v[40:43], v[162:165], v[178:181], v[40:43]
	v_mfma_f32_16x16x32_bf16 v[28:31], v[136:139], v[186:189], v[28:31]
	v_mfma_f32_16x16x32_bf16 v[24:27], v[162:165], v[186:189], v[24:27]
	v_mfma_f32_16x16x32_bf16 v[12:15], v[136:139], v[214:217], v[12:15]
	v_mfma_f32_16x16x32_bf16 v[8:11], v[162:165], v[214:217], v[8:11]
	v_mfma_f32_16x16x32_bf16 v[60:63], v[150:153], v[174:177], v[60:63]
	v_mfma_f32_16x16x32_bf16 v[56:59], v[166:169], v[174:177], v[56:59]
	v_mfma_f32_16x16x32_bf16 v[44:47], v[150:153], v[182:185], v[44:47]
	v_mfma_f32_16x16x32_bf16 v[40:43], v[166:169], v[182:185], v[40:43]
	v_mfma_f32_16x16x32_bf16 v[28:31], v[150:153], v[206:209], v[28:31]
	v_mfma_f32_16x16x32_bf16 v[24:27], v[166:169], v[206:209], v[24:27]
	v_mfma_f32_16x16x32_bf16 v[12:15], v[150:153], v[218:221], v[12:15]
	v_mfma_f32_16x16x32_bf16 v[8:11], v[166:169], v[218:221], v[8:11]
	s_barrier
	s_add_u32 s80, s42, 0x40000
	s_addc_u32 s81, s43, 0
	s_add_i32 s21, s61, s35
	v_lshl_add_u64 v[136:137], s[80:81], 0, v[130:131]
	s_mov_b32 m0, s21
	s_nop 0
	global_load_lds_dwordx4 v[136:137], off
	v_lshl_add_u64 v[136:137], s[80:81], 0, v[128:129]
	s_add_i32 m0, s21, 0x2000
	s_nop 0
	global_load_lds_dwordx4 v[136:137], off
	s_waitcnt vmcnt(6)
	s_barrier
	v_mfma_f32_16x16x32_bf16 v[52:55], v[222:225], v[170:173], v[52:55]
	v_mfma_f32_16x16x32_bf16 v[48:51], v[230:233], v[170:173], v[48:51]
	v_mfma_f32_16x16x32_bf16 v[36:39], v[222:225], v[178:181], v[36:39]
	v_mfma_f32_16x16x32_bf16 v[32:35], v[230:233], v[178:181], v[32:35]
	v_mfma_f32_16x16x32_bf16 v[20:23], v[222:225], v[186:189], v[20:23]
	v_mfma_f32_16x16x32_bf16 v[16:19], v[230:233], v[186:189], v[16:19]
	v_mfma_f32_16x16x32_bf16 v[4:7], v[222:225], v[214:217], v[4:7]
	v_mfma_f32_16x16x32_bf16 v[0:3], v[230:233], v[214:217], v[0:3]
	v_mfma_f32_16x16x32_bf16 v[52:55], v[226:229], v[174:177], v[52:55]
	v_mfma_f32_16x16x32_bf16 v[48:51], v[234:237], v[174:177], v[48:51]
	v_mfma_f32_16x16x32_bf16 v[36:39], v[226:229], v[182:185], v[36:39]
	v_mfma_f32_16x16x32_bf16 v[32:35], v[234:237], v[182:185], v[32:35]
	v_mfma_f32_16x16x32_bf16 v[20:23], v[226:229], v[206:209], v[20:23]
	v_mfma_f32_16x16x32_bf16 v[16:19], v[234:237], v[206:209], v[16:19]
	v_mfma_f32_16x16x32_bf16 v[4:7], v[226:229], v[218:221], v[4:7]
	v_mfma_f32_16x16x32_bf16 v[0:3], v[234:237], v[218:221], v[0:3]
	s_add_i32 s21, 0, 0x18000
	v_add_u32_e32 v156, s21, v141
	s_barrier
	ds_read_b128 v[136:139], v156
	ds_read_b128 v[150:153], v156 offset:1024
	ds_read_b128 v[162:165], v156 offset:2048
	ds_read_b128 v[166:169], v156 offset:3072
	s_add_u32 s2, s2, 0x40000
	s_addc_u32 s3, s3, 0
	s_mov_b32 m0, s55
	v_lshl_add_u64 v[222:223], s[2:3], 0, v[130:131]
	ds_read_b128 v[170:173], v149 offset:32768
	ds_read_b128 v[174:177], v149 offset:33792
	ds_read_b128 v[178:181], v149 offset:34816
	ds_read_b128 v[182:185], v149 offset:35840
	ds_read_b128 v[186:189], v149 offset:36864
	ds_read_b128 v[206:209], v149 offset:37888
	ds_read_b128 v[214:217], v149 offset:38912
	ds_read_b128 v[218:221], v149 offset:39936
	global_load_lds_dwordx4 v[222:223], off
	v_lshl_add_u64 v[222:223], s[2:3], 0, v[128:129]
	s_mov_b32 m0, s78
	s_nop 0
	global_load_lds_dwordx4 v[222:223], off
	s_waitcnt lgkmcnt(8)
	s_barrier
	s_waitcnt lgkmcnt(0)
	s_waitcnt lgkmcnt(0)
	v_mfma_f32_16x16x32_bf16 v[124:127], v[136:139], v[170:173], v[124:127]
	v_mfma_f32_16x16x32_bf16 v[120:123], v[162:165], v[170:173], v[120:123]
	v_mfma_f32_16x16x32_bf16 v[108:111], v[136:139], v[178:181], v[108:111]
	v_mfma_f32_16x16x32_bf16 v[104:107], v[162:165], v[178:181], v[104:107]
	v_mfma_f32_16x16x32_bf16 v[92:95], v[136:139], v[186:189], v[92:95]
	v_mfma_f32_16x16x32_bf16 v[88:91], v[162:165], v[186:189], v[88:91]
	v_mfma_f32_16x16x32_bf16 v[76:79], v[136:139], v[214:217], v[76:79]
	v_mfma_f32_16x16x32_bf16 v[72:75], v[162:165], v[214:217], v[72:75]
	v_mfma_f32_16x16x32_bf16 v[124:127], v[150:153], v[174:177], v[124:127]
	v_mfma_f32_16x16x32_bf16 v[120:123], v[166:169], v[174:177], v[120:123]
	v_mfma_f32_16x16x32_bf16 v[108:111], v[150:153], v[182:185], v[108:111]
	v_mfma_f32_16x16x32_bf16 v[104:107], v[166:169], v[182:185], v[104:107]
	v_mfma_f32_16x16x32_bf16 v[92:95], v[150:153], v[206:209], v[92:95]
	v_mfma_f32_16x16x32_bf16 v[88:91], v[166:169], v[206:209], v[88:91]
	v_mfma_f32_16x16x32_bf16 v[76:79], v[150:153], v[218:221], v[76:79]
	v_mfma_f32_16x16x32_bf16 v[72:75], v[166:169], v[218:221], v[72:75]
	s_barrier
	s_add_i32 s61, 0, 0x1c000
	s_add_i32 s2, s21, s35
	v_add_u32_e32 v156, s61, v141
	v_lshl_add_u64 v[154:155], v[154:155], 0, s[50:51]
	s_mov_b32 m0, s2
	ds_read_b128 v[222:225], v156
	ds_read_b128 v[226:229], v156 offset:1024
	ds_read_b128 v[230:233], v156 offset:2048
	ds_read_b128 v[234:237], v156 offset:3072
	global_load_lds_dwordx4 v[154:155], off
	v_lshl_add_u64 v[154:155], v[238:239], 0, s[50:51]
	s_add_i32 m0, s2, 0x2000
	s_nop 0
	global_load_lds_dwordx4 v[154:155], off
	s_barrier
	s_waitcnt lgkmcnt(0)
	s_waitcnt lgkmcnt(0)
	v_mfma_f32_16x16x32_bf16 v[116:119], v[222:225], v[170:173], v[116:119]
	v_mfma_f32_16x16x32_bf16 v[112:115], v[230:233], v[170:173], v[112:115]
	v_mfma_f32_16x16x32_bf16 v[100:103], v[222:225], v[178:181], v[100:103]
	v_mfma_f32_16x16x32_bf16 v[96:99], v[230:233], v[178:181], v[96:99]
	v_mfma_f32_16x16x32_bf16 v[84:87], v[222:225], v[186:189], v[84:87]
	v_mfma_f32_16x16x32_bf16 v[80:83], v[230:233], v[186:189], v[80:83]
	v_mfma_f32_16x16x32_bf16 v[68:71], v[222:225], v[214:217], v[68:71]
	v_mfma_f32_16x16x32_bf16 v[64:67], v[230:233], v[214:217], v[64:67]
	v_mfma_f32_16x16x32_bf16 v[116:119], v[226:229], v[174:177], v[116:119]
	v_mfma_f32_16x16x32_bf16 v[112:115], v[234:237], v[174:177], v[112:115]
	v_mfma_f32_16x16x32_bf16 v[100:103], v[226:229], v[182:185], v[100:103]
	v_mfma_f32_16x16x32_bf16 v[96:99], v[234:237], v[182:185], v[96:99]
	v_mfma_f32_16x16x32_bf16 v[84:87], v[226:229], v[206:209], v[84:87]
	v_mfma_f32_16x16x32_bf16 v[80:83], v[234:237], v[206:209], v[80:83]
	v_mfma_f32_16x16x32_bf16 v[68:71], v[226:229], v[218:221], v[68:71]
	v_mfma_f32_16x16x32_bf16 v[64:67], v[234:237], v[218:221], v[64:67]
	s_mov_b32 m0, s79
	v_lshl_add_u64 v[154:155], v[240:241], 0, s[50:51]
	s_barrier
	ds_read_b128 v[170:173], v149 offset:49152
	ds_read_b128 v[174:177], v149 offset:50176
	ds_read_b128 v[178:181], v149 offset:51200
	ds_read_b128 v[182:185], v149 offset:52224
	ds_read_b128 v[186:189], v149 offset:53248
	ds_read_b128 v[206:209], v149 offset:54272
	ds_read_b128 v[214:217], v149 offset:55296
	ds_read_b128 v[218:221], v149 offset:56320
	global_load_lds_dwordx4 v[154:155], off
	v_lshl_add_u64 v[154:155], v[242:243], 0, s[50:51]
	s_mov_b32 m0, s82
	s_nop 0
	global_load_lds_dwordx4 v[154:155], off
	s_barrier
	s_waitcnt lgkmcnt(0)
	s_waitcnt lgkmcnt(0)
	v_mfma_f32_16x16x32_bf16 v[60:63], v[136:139], v[170:173], v[60:63]
	v_mfma_f32_16x16x32_bf16 v[56:59], v[162:165], v[170:173], v[56:59]
	v_mfma_f32_16x16x32_bf16 v[44:47], v[136:139], v[178:181], v[44:47]
	v_mfma_f32_16x16x32_bf16 v[40:43], v[162:165], v[178:181], v[40:43]
	v_mfma_f32_16x16x32_bf16 v[28:31], v[136:139], v[186:189], v[28:31]
	v_mfma_f32_16x16x32_bf16 v[24:27], v[162:165], v[186:189], v[24:27]
	v_mfma_f32_16x16x32_bf16 v[12:15], v[136:139], v[214:217], v[12:15]
	v_mfma_f32_16x16x32_bf16 v[8:11], v[162:165], v[214:217], v[8:11]
	v_mfma_f32_16x16x32_bf16 v[60:63], v[150:153], v[174:177], v[60:63]
	v_mfma_f32_16x16x32_bf16 v[56:59], v[166:169], v[174:177], v[56:59]
	v_mfma_f32_16x16x32_bf16 v[44:47], v[150:153], v[182:185], v[44:47]
	v_mfma_f32_16x16x32_bf16 v[40:43], v[166:169], v[182:185], v[40:43]
	v_mfma_f32_16x16x32_bf16 v[28:31], v[150:153], v[206:209], v[28:31]
	v_mfma_f32_16x16x32_bf16 v[24:27], v[166:169], v[206:209], v[24:27]
	v_mfma_f32_16x16x32_bf16 v[12:15], v[150:153], v[218:221], v[12:15]
	v_mfma_f32_16x16x32_bf16 v[8:11], v[166:169], v[218:221], v[8:11]
	s_barrier
	s_add_u32 s2, s42, 0x40080
	s_addc_u32 s3, s43, 0
	s_add_i32 s21, s61, s35
	v_lshl_add_u64 v[136:137], s[2:3], 0, v[130:131]
	s_mov_b32 m0, s21
	s_nop 0
	global_load_lds_dwordx4 v[136:137], off
	v_lshl_add_u64 v[136:137], s[2:3], 0, v[128:129]
	s_add_i32 m0, s21, 0x2000
	s_nop 0
	global_load_lds_dwordx4 v[136:137], off
	s_waitcnt vmcnt(6)
	s_barrier
	v_mfma_f32_16x16x32_bf16 v[52:55], v[222:225], v[170:173], v[52:55]
	v_mfma_f32_16x16x32_bf16 v[48:51], v[230:233], v[170:173], v[48:51]
	v_mfma_f32_16x16x32_bf16 v[36:39], v[222:225], v[178:181], v[36:39]
	v_mfma_f32_16x16x32_bf16 v[32:35], v[230:233], v[178:181], v[32:35]
	v_mfma_f32_16x16x32_bf16 v[20:23], v[222:225], v[186:189], v[20:23]
	v_mfma_f32_16x16x32_bf16 v[16:19], v[230:233], v[186:189], v[16:19]
	v_mfma_f32_16x16x32_bf16 v[4:7], v[222:225], v[214:217], v[4:7]
	v_mfma_f32_16x16x32_bf16 v[0:3], v[230:233], v[214:217], v[0:3]
	v_mfma_f32_16x16x32_bf16 v[52:55], v[226:229], v[174:177], v[52:55]
	v_mfma_f32_16x16x32_bf16 v[48:51], v[234:237], v[174:177], v[48:51]
	v_mfma_f32_16x16x32_bf16 v[36:39], v[226:229], v[182:185], v[36:39]
	v_mfma_f32_16x16x32_bf16 v[32:35], v[234:237], v[182:185], v[32:35]
	v_mfma_f32_16x16x32_bf16 v[20:23], v[226:229], v[206:209], v[20:23]
	v_mfma_f32_16x16x32_bf16 v[16:19], v[234:237], v[206:209], v[16:19]
	v_mfma_f32_16x16x32_bf16 v[4:7], v[226:229], v[218:221], v[4:7]
	v_mfma_f32_16x16x32_bf16 v[0:3], v[234:237], v[218:221], v[0:3]
	s_add_i32 s60, s60, 2
	s_add_u32 s46, s46, 0x100
	s_addc_u32 s47, s47, 0
	s_add_u32 s6, s6, 0x100
	s_addc_u32 s7, s7, 0
	s_cmp_gt_u32 s60, 13
	s_barrier
	s_cbranch_scc0 .LBB0_326

.LBB0_513:
	s_add_i32 s82, s84, -2
	s_add_u32 s83, s6, 0x100
	s_addc_u32 vcc_lo, s7, 0
	s_add_u32 s6, s60, 0x80
	s_addc_u32 s7, s61, 0
	s_mov_b32 s2, 0
	s_add_i32 vcc_hi, s2, 2
	s_add_u32 s21, s6, 0x80
	s_addc_u32 s3, s7, 0
	s_add_i32 s74, 0, 0x10000
	v_add_u32_e32 v140, s74, v161
	ds_read_b128 v[128:131], v140
	ds_read_b128 v[132:135], v140 offset:1024
	ds_read_b128 v[136:139], v140 offset:2048
	ds_read_b128 v[140:143], v140 offset:3072
	s_cmp_eq_u32 s82, s2
	s_cselect_b32 s2, s80, s21
	s_cselect_b32 s3, s81, s3
	s_cselect_b32 s61, s39, vcc_lo
	s_cselect_b32 s60, s38, s83
	v_lshl_add_u64 v[206:207], s[6:7], 0, v[168:169]
	s_add_i32 m0, s88, 0xc000
	ds_read_b128 v[144:147], v214
	ds_read_b128 v[148:151], v214 offset:1024
	ds_read_b128 v[152:155], v214 offset:2048
	ds_read_b128 v[170:173], v214 offset:3072
	ds_read_b128 v[174:177], v214 offset:4096
	ds_read_b128 v[178:181], v214 offset:5120
	ds_read_b128 v[182:185], v214 offset:6144
	ds_read_b128 v[186:189], v214 offset:7168
	global_load_lds_dwordx4 v[206:207], off
	v_lshl_add_u64 v[206:207], s[6:7], 0, v[166:167]
	s_add_i32 m0, s88, 0xe000
	s_nop 0
	global_load_lds_dwordx4 v[206:207], off
	s_waitcnt lgkmcnt(8)
	s_barrier
	s_waitcnt lgkmcnt(0)
	s_waitcnt lgkmcnt(0)
	v_mfma_f32_16x16x32_bf16 v[124:127], v[128:131], v[144:147], 0
	v_mfma_f32_16x16x32_bf16 v[120:123], v[136:139], v[144:147], 0
	v_mfma_f32_16x16x32_bf16 v[116:119], v[128:131], v[152:155], 0
	v_mfma_f32_16x16x32_bf16 v[108:111], v[136:139], v[152:155], 0
	v_mfma_f32_16x16x32_bf16 v[100:103], v[128:131], v[174:177], 0
	v_mfma_f32_16x16x32_bf16 v[92:95], v[136:139], v[174:177], 0
	v_mfma_f32_16x16x32_bf16 v[84:87], v[128:131], v[182:185], 0
	v_mfma_f32_16x16x32_bf16 v[76:79], v[136:139], v[182:185], 0
	v_mfma_f32_16x16x32_bf16 v[124:127], v[132:135], v[148:151], v[124:127]
	v_mfma_f32_16x16x32_bf16 v[120:123], v[140:143], v[148:151], v[120:123]
	v_mfma_f32_16x16x32_bf16 v[116:119], v[132:135], v[170:173], v[116:119]
	v_mfma_f32_16x16x32_bf16 v[108:111], v[140:143], v[170:173], v[108:111]
	v_mfma_f32_16x16x32_bf16 v[100:103], v[132:135], v[178:181], v[100:103]
	v_mfma_f32_16x16x32_bf16 v[92:95], v[140:143], v[178:181], v[92:95]
	v_mfma_f32_16x16x32_bf16 v[84:87], v[132:135], v[186:189], v[84:87]
	v_mfma_f32_16x16x32_bf16 v[76:79], v[140:143], v[186:189], v[76:79]
	s_barrier
	s_add_i32 s21, 0, 0x14000
	s_add_i32 s74, s74, s53
	v_add_u32_e32 v215, s21, v161
	v_lshl_add_u64 v[228:229], s[60:61], 0, v[156:157]
	s_mov_b32 m0, s74
	ds_read_b128 v[206:209], v215
	ds_read_b128 v[216:219], v215 offset:1024
	ds_read_b128 v[220:223], v215 offset:2048
	ds_read_b128 v[224:227], v215 offset:3072
	global_load_lds_dwordx4 v[228:229], off
	v_lshl_add_u64 v[230:231], s[60:61], 0, v[162:163]
	s_add_i32 m0, s74, 0x2000
	s_nop 0
	global_load_lds_dwordx4 v[230:231], off
	s_barrier
	s_waitcnt lgkmcnt(0)
	s_waitcnt lgkmcnt(0)
	v_mfma_f32_16x16x32_bf16 v[112:115], v[206:209], v[144:147], 0
	v_mfma_f32_16x16x32_bf16 v[104:107], v[220:223], v[144:147], 0
	v_mfma_f32_16x16x32_bf16 v[96:99], v[206:209], v[152:155], 0
	v_mfma_f32_16x16x32_bf16 v[88:91], v[220:223], v[152:155], 0
	v_mfma_f32_16x16x32_bf16 v[80:83], v[206:209], v[174:177], 0
	v_mfma_f32_16x16x32_bf16 v[72:75], v[220:223], v[174:177], 0
	v_mfma_f32_16x16x32_bf16 v[68:71], v[206:209], v[182:185], 0
	v_mfma_f32_16x16x32_bf16 v[64:67], v[220:223], v[182:185], 0
	v_mfma_f32_16x16x32_bf16 v[112:115], v[216:219], v[148:151], v[112:115]
	v_mfma_f32_16x16x32_bf16 v[104:107], v[224:227], v[148:151], v[104:107]
	v_mfma_f32_16x16x32_bf16 v[96:99], v[216:219], v[170:173], v[96:99]
	v_mfma_f32_16x16x32_bf16 v[88:91], v[224:227], v[170:173], v[88:91]
	v_mfma_f32_16x16x32_bf16 v[80:83], v[216:219], v[178:181], v[80:83]
	v_mfma_f32_16x16x32_bf16 v[72:75], v[224:227], v[178:181], v[72:75]
	v_mfma_f32_16x16x32_bf16 v[68:71], v[216:219], v[186:189], v[68:71]
	v_mfma_f32_16x16x32_bf16 v[64:67], v[224:227], v[186:189], v[64:67]
	s_mov_b32 m0, s88
	v_lshl_add_u64 v[232:233], s[2:3], 0, v[156:157]
	s_barrier
	ds_read_b128 v[144:147], v214 offset:16384
	ds_read_b128 v[148:151], v214 offset:17408
	ds_read_b128 v[152:155], v214 offset:18432
	ds_read_b128 v[170:173], v214 offset:19456
	ds_read_b128 v[174:177], v214 offset:20480
	ds_read_b128 v[178:181], v214 offset:21504
	ds_read_b128 v[182:185], v214 offset:22528
	ds_read_b128 v[186:189], v214 offset:23552
	global_load_lds_dwordx4 v[232:233], off
	v_lshl_add_u64 v[234:235], s[2:3], 0, v[162:163]
	s_mov_b32 m0, s89
	s_nop 0
	global_load_lds_dwordx4 v[234:235], off
	s_barrier
	s_waitcnt lgkmcnt(0)
	s_waitcnt lgkmcnt(0)
	v_mfma_f32_16x16x32_bf16 v[60:63], v[128:131], v[144:147], 0
	v_mfma_f32_16x16x32_bf16 v[56:59], v[136:139], v[144:147], 0
	v_mfma_f32_16x16x32_bf16 v[52:55], v[128:131], v[152:155], 0
	v_mfma_f32_16x16x32_bf16 v[44:47], v[136:139], v[152:155], 0
	v_mfma_f32_16x16x32_bf16 v[36:39], v[128:131], v[174:177], 0
	v_mfma_f32_16x16x32_bf16 v[28:31], v[136:139], v[174:177], 0
	v_mfma_f32_16x16x32_bf16 v[20:23], v[128:131], v[182:185], 0
	v_mfma_f32_16x16x32_bf16 v[12:15], v[136:139], v[182:185], 0
	v_mfma_f32_16x16x32_bf16 v[60:63], v[132:135], v[148:151], v[60:63]
	v_mfma_f32_16x16x32_bf16 v[56:59], v[140:143], v[148:151], v[56:59]
	v_mfma_f32_16x16x32_bf16 v[52:55], v[132:135], v[170:173], v[52:55]
	v_mfma_f32_16x16x32_bf16 v[44:47], v[140:143], v[170:173], v[44:47]
	v_mfma_f32_16x16x32_bf16 v[36:39], v[132:135], v[178:181], v[36:39]
	v_mfma_f32_16x16x32_bf16 v[28:31], v[140:143], v[178:181], v[28:31]
	v_mfma_f32_16x16x32_bf16 v[20:23], v[132:135], v[186:189], v[20:23]
	v_mfma_f32_16x16x32_bf16 v[12:15], v[140:143], v[186:189], v[12:15]
	s_barrier
	s_add_u32 s60, s60, s54
	s_addc_u32 s61, s61, 0
	s_add_i32 s21, s21, s53
	v_lshl_add_u64 v[236:237], s[60:61], 0, v[156:157]
	s_mov_b32 m0, s21
	v_lshl_add_u64 v[238:239], s[60:61], 0, v[162:163]
	global_load_lds_dwordx4 v[236:237], off
	s_add_i32 m0, s21, 0x2000
	s_nop 0
	global_load_lds_dwordx4 v[238:239], off
	s_waitcnt vmcnt(6)
	s_barrier
	v_mfma_f32_16x16x32_bf16 v[48:51], v[206:209], v[144:147], 0
	v_mfma_f32_16x16x32_bf16 v[40:43], v[220:223], v[144:147], 0
	v_mfma_f32_16x16x32_bf16 v[32:35], v[206:209], v[152:155], 0
	v_mfma_f32_16x16x32_bf16 v[24:27], v[220:223], v[152:155], 0
	v_mfma_f32_16x16x32_bf16 v[16:19], v[206:209], v[174:177], 0
	v_mfma_f32_16x16x32_bf16 v[8:11], v[220:223], v[174:177], 0
	v_mfma_f32_16x16x32_bf16 v[4:7], v[206:209], v[182:185], 0
	v_mfma_f32_16x16x32_bf16 v[0:3], v[220:223], v[182:185], 0
	v_mfma_f32_16x16x32_bf16 v[48:51], v[216:219], v[148:151], v[48:51]
	v_mfma_f32_16x16x32_bf16 v[40:43], v[224:227], v[148:151], v[40:43]
	v_mfma_f32_16x16x32_bf16 v[32:35], v[216:219], v[170:173], v[32:35]
	v_mfma_f32_16x16x32_bf16 v[24:27], v[224:227], v[170:173], v[24:27]
	v_mfma_f32_16x16x32_bf16 v[16:19], v[216:219], v[178:181], v[16:19]
	v_mfma_f32_16x16x32_bf16 v[8:11], v[224:227], v[178:181], v[8:11]
	v_mfma_f32_16x16x32_bf16 v[4:7], v[216:219], v[186:189], v[4:7]
	v_mfma_f32_16x16x32_bf16 v[0:3], v[224:227], v[186:189], v[0:3]
	s_add_i32 s21, 0, 0x18000
	v_add_u32_e32 v140, s21, v161
	s_barrier
	ds_read_b128 v[128:131], v140
	ds_read_b128 v[132:135], v140 offset:1024
	ds_read_b128 v[136:139], v140 offset:2048
	ds_read_b128 v[140:143], v140 offset:3072
	s_add_u32 s2, s2, s54
	s_addc_u32 s3, s3, 0
	s_mov_b32 m0, s94
	v_lshl_add_u64 v[206:207], s[2:3], 0, v[156:157]
	ds_read_b128 v[144:147], v214 offset:32768
	ds_read_b128 v[148:151], v214 offset:33792
	ds_read_b128 v[152:155], v214 offset:34816
	ds_read_b128 v[170:173], v214 offset:35840
	ds_read_b128 v[174:177], v214 offset:36864
	ds_read_b128 v[178:181], v214 offset:37888
	ds_read_b128 v[182:185], v214 offset:38912
	ds_read_b128 v[186:189], v214 offset:39936
	global_load_lds_dwordx4 v[206:207], off
	v_lshl_add_u64 v[206:207], s[2:3], 0, v[162:163]
	s_mov_b32 m0, s95
	s_nop 0
	global_load_lds_dwordx4 v[206:207], off
	s_waitcnt lgkmcnt(8)
	s_barrier
	s_waitcnt lgkmcnt(0)
	s_waitcnt lgkmcnt(0)
	v_mfma_f32_16x16x32_bf16 v[124:127], v[128:131], v[144:147], v[124:127]
	v_mfma_f32_16x16x32_bf16 v[120:123], v[136:139], v[144:147], v[120:123]
	v_mfma_f32_16x16x32_bf16 v[116:119], v[128:131], v[152:155], v[116:119]
	v_mfma_f32_16x16x32_bf16 v[108:111], v[136:139], v[152:155], v[108:111]
	v_mfma_f32_16x16x32_bf16 v[100:103], v[128:131], v[174:177], v[100:103]
	v_mfma_f32_16x16x32_bf16 v[92:95], v[136:139], v[174:177], v[92:95]
	v_mfma_f32_16x16x32_bf16 v[84:87], v[128:131], v[182:185], v[84:87]
	v_mfma_f32_16x16x32_bf16 v[76:79], v[136:139], v[182:185], v[76:79]
	v_mfma_f32_16x16x32_bf16 v[124:127], v[132:135], v[148:151], v[124:127]
	v_mfma_f32_16x16x32_bf16 v[120:123], v[140:143], v[148:151], v[120:123]
	v_mfma_f32_16x16x32_bf16 v[116:119], v[132:135], v[170:173], v[116:119]
	v_mfma_f32_16x16x32_bf16 v[108:111], v[140:143], v[170:173], v[108:111]
	v_mfma_f32_16x16x32_bf16 v[100:103], v[132:135], v[178:181], v[100:103]
	v_mfma_f32_16x16x32_bf16 v[92:95], v[140:143], v[178:181], v[92:95]
	v_mfma_f32_16x16x32_bf16 v[84:87], v[132:135], v[186:189], v[84:87]
	v_mfma_f32_16x16x32_bf16 v[76:79], v[140:143], v[186:189], v[76:79]
	s_barrier
	s_add_i32 s2, 0, 0x1c000
	s_add_i32 s3, s21, s53
	v_add_u32_e32 v215, s2, v161
	v_lshl_add_u64 v[228:229], v[228:229], 0, s[50:51]
	s_mov_b32 m0, s3
	ds_read_b128 v[206:209], v215
	ds_read_b128 v[216:219], v215 offset:1024
	ds_read_b128 v[220:223], v215 offset:2048
	ds_read_b128 v[224:227], v215 offset:3072
	global_load_lds_dwordx4 v[228:229], off
	v_lshl_add_u64 v[228:229], v[230:231], 0, s[50:51]
	s_add_i32 m0, s3, 0x2000
	s_nop 0
	global_load_lds_dwordx4 v[228:229], off
	s_barrier
	s_waitcnt lgkmcnt(0)
	s_waitcnt lgkmcnt(0)
	v_mfma_f32_16x16x32_bf16 v[112:115], v[206:209], v[144:147], v[112:115]
	v_mfma_f32_16x16x32_bf16 v[104:107], v[220:223], v[144:147], v[104:107]
	v_mfma_f32_16x16x32_bf16 v[96:99], v[206:209], v[152:155], v[96:99]
	v_mfma_f32_16x16x32_bf16 v[88:91], v[220:223], v[152:155], v[88:91]
	v_mfma_f32_16x16x32_bf16 v[80:83], v[206:209], v[174:177], v[80:83]
	v_mfma_f32_16x16x32_bf16 v[72:75], v[220:223], v[174:177], v[72:75]
	v_mfma_f32_16x16x32_bf16 v[68:71], v[206:209], v[182:185], v[68:71]
	v_mfma_f32_16x16x32_bf16 v[64:67], v[220:223], v[182:185], v[64:67]
	v_mfma_f32_16x16x32_bf16 v[112:115], v[216:219], v[148:151], v[112:115]
	v_mfma_f32_16x16x32_bf16 v[104:107], v[224:227], v[148:151], v[104:107]
	v_mfma_f32_16x16x32_bf16 v[96:99], v[216:219], v[170:173], v[96:99]
	v_mfma_f32_16x16x32_bf16 v[88:91], v[224:227], v[170:173], v[88:91]
	v_mfma_f32_16x16x32_bf16 v[80:83], v[216:219], v[178:181], v[80:83]
	v_mfma_f32_16x16x32_bf16 v[72:75], v[224:227], v[178:181], v[72:75]
	v_mfma_f32_16x16x32_bf16 v[68:71], v[216:219], v[186:189], v[68:71]
	v_mfma_f32_16x16x32_bf16 v[64:67], v[224:227], v[186:189], v[64:67]
	s_mov_b32 m0, s96
	v_lshl_add_u64 v[228:229], v[232:233], 0, s[50:51]
	s_barrier
	ds_read_b128 v[144:147], v214 offset:49152
	ds_read_b128 v[148:151], v214 offset:50176
	ds_read_b128 v[152:155], v214 offset:51200
	ds_read_b128 v[170:173], v214 offset:52224
	ds_read_b128 v[174:177], v214 offset:53248
	ds_read_b128 v[178:181], v214 offset:54272
	ds_read_b128 v[182:185], v214 offset:55296
	ds_read_b128 v[186:189], v214 offset:56320
	global_load_lds_dwordx4 v[228:229], off
	v_lshl_add_u64 v[228:229], v[234:235], 0, s[50:51]
	s_mov_b32 m0, s97
	s_nop 0
	global_load_lds_dwordx4 v[228:229], off
	s_barrier
	s_waitcnt lgkmcnt(0)
	s_waitcnt lgkmcnt(0)
	v_mfma_f32_16x16x32_bf16 v[60:63], v[128:131], v[144:147], v[60:63]
	v_mfma_f32_16x16x32_bf16 v[56:59], v[136:139], v[144:147], v[56:59]
	v_mfma_f32_16x16x32_bf16 v[52:55], v[128:131], v[152:155], v[52:55]
	v_mfma_f32_16x16x32_bf16 v[44:47], v[136:139], v[152:155], v[44:47]
	v_mfma_f32_16x16x32_bf16 v[36:39], v[128:131], v[174:177], v[36:39]
	v_mfma_f32_16x16x32_bf16 v[28:31], v[136:139], v[174:177], v[28:31]
	v_mfma_f32_16x16x32_bf16 v[20:23], v[128:131], v[182:185], v[20:23]
	v_mfma_f32_16x16x32_bf16 v[12:15], v[136:139], v[182:185], v[12:15]
	v_mfma_f32_16x16x32_bf16 v[60:63], v[132:135], v[148:151], v[60:63]
	v_mfma_f32_16x16x32_bf16 v[56:59], v[140:143], v[148:151], v[56:59]
	v_mfma_f32_16x16x32_bf16 v[52:55], v[132:135], v[170:173], v[52:55]
	v_mfma_f32_16x16x32_bf16 v[44:47], v[140:143], v[170:173], v[44:47]
	v_mfma_f32_16x16x32_bf16 v[36:39], v[132:135], v[178:181], v[36:39]
	v_mfma_f32_16x16x32_bf16 v[28:31], v[140:143], v[178:181], v[28:31]
	v_mfma_f32_16x16x32_bf16 v[20:23], v[132:135], v[186:189], v[20:23]
	v_mfma_f32_16x16x32_bf16 v[12:15], v[140:143], v[186:189], v[12:15]
	s_barrier
	s_add_i32 s2, s2, s53
	v_lshl_add_u64 v[128:129], v[236:237], 0, s[50:51]
	s_mov_b32 m0, s2
	s_nop 0
	global_load_lds_dwordx4 v[128:129], off
	v_lshl_add_u64 v[128:129], v[238:239], 0, s[50:51]
	s_add_i32 m0, s2, 0x2000
	s_nop 0
	global_load_lds_dwordx4 v[128:129], off
	s_waitcnt vmcnt(6)
	s_barrier
	v_mfma_f32_16x16x32_bf16 v[48:51], v[206:209], v[144:147], v[48:51]
	v_mfma_f32_16x16x32_bf16 v[40:43], v[220:223], v[144:147], v[40:43]
	v_mfma_f32_16x16x32_bf16 v[32:35], v[206:209], v[152:155], v[32:35]
	v_mfma_f32_16x16x32_bf16 v[24:27], v[220:223], v[152:155], v[24:27]
	v_mfma_f32_16x16x32_bf16 v[16:19], v[206:209], v[174:177], v[16:19]
	v_mfma_f32_16x16x32_bf16 v[8:11], v[220:223], v[174:177], v[8:11]
	v_mfma_f32_16x16x32_bf16 v[4:7], v[206:209], v[182:185], v[4:7]
	v_mfma_f32_16x16x32_bf16 v[0:3], v[220:223], v[182:185], v[0:3]
	v_mfma_f32_16x16x32_bf16 v[48:51], v[216:219], v[148:151], v[48:51]
	v_mfma_f32_16x16x32_bf16 v[40:43], v[224:227], v[148:151], v[40:43]
	v_mfma_f32_16x16x32_bf16 v[32:35], v[216:219], v[170:173], v[32:35]
	v_mfma_f32_16x16x32_bf16 v[24:27], v[224:227], v[170:173], v[24:27]
	v_mfma_f32_16x16x32_bf16 v[16:19], v[216:219], v[178:181], v[16:19]
	v_mfma_f32_16x16x32_bf16 v[8:11], v[224:227], v[178:181], v[8:11]
	v_mfma_f32_16x16x32_bf16 v[4:7], v[216:219], v[186:189], v[4:7]
	v_mfma_f32_16x16x32_bf16 v[0:3], v[224:227], v[186:189], v[0:3]
	s_add_u32 s83, s83, 0x100
	s_addc_u32 vcc_lo, vcc_lo, 0
	s_add_u32 s6, s6, 0x100
	s_addc_u32 s7, s7, 0
	s_cmp_ge_u32 vcc_hi, s84
	s_mov_b32 s2, vcc_hi
	s_barrier
	s_cbranch_scc1 .Lpost_514
.LBB0_514:
	s_add_i32 vcc_hi, s2, 2
	s_add_u32 s21, s6, 0x80
	s_addc_u32 s3, s7, 0
	s_add_i32 s74, 0, 0x10000
	v_add_u32_e32 v140, s74, v161
	ds_read_b128 v[128:131], v140
	ds_read_b128 v[132:135], v140 offset:1024
	ds_read_b128 v[136:139], v140 offset:2048
	ds_read_b128 v[140:143], v140 offset:3072
	s_cmp_eq_u32 s82, s2
	s_cselect_b32 s2, s80, s21
	s_cselect_b32 s3, s81, s3
	s_cselect_b32 s61, s39, vcc_lo
	s_cselect_b32 s60, s38, s83
	v_lshl_add_u64 v[206:207], s[6:7], 0, v[168:169]
	s_add_i32 m0, s88, 0xc000
	ds_read_b128 v[144:147], v214
	ds_read_b128 v[148:151], v214 offset:1024
	ds_read_b128 v[152:155], v214 offset:2048
	ds_read_b128 v[170:173], v214 offset:3072
	ds_read_b128 v[174:177], v214 offset:4096
	ds_read_b128 v[178:181], v214 offset:5120
	ds_read_b128 v[182:185], v214 offset:6144
	ds_read_b128 v[186:189], v214 offset:7168
	global_load_lds_dwordx4 v[206:207], off
	v_lshl_add_u64 v[206:207], s[6:7], 0, v[166:167]
	s_add_i32 m0, s88, 0xe000
	s_nop 0
	global_load_lds_dwordx4 v[206:207], off
	s_waitcnt lgkmcnt(8)
	s_barrier
	s_waitcnt lgkmcnt(0)
	s_waitcnt lgkmcnt(0)
	v_mfma_f32_16x16x32_bf16 v[124:127], v[128:131], v[144:147], v[124:127]
	v_mfma_f32_16x16x32_bf16 v[120:123], v[136:139], v[144:147], v[120:123]
	v_mfma_f32_16x16x32_bf16 v[116:119], v[128:131], v[152:155], v[116:119]
	v_mfma_f32_16x16x32_bf16 v[108:111], v[136:139], v[152:155], v[108:111]
	v_mfma_f32_16x16x32_bf16 v[100:103], v[128:131], v[174:177], v[100:103]
	v_mfma_f32_16x16x32_bf16 v[92:95], v[136:139], v[174:177], v[92:95]
	v_mfma_f32_16x16x32_bf16 v[84:87], v[128:131], v[182:185], v[84:87]
	v_mfma_f32_16x16x32_bf16 v[76:79], v[136:139], v[182:185], v[76:79]
	v_mfma_f32_16x16x32_bf16 v[124:127], v[132:135], v[148:151], v[124:127]
	v_mfma_f32_16x16x32_bf16 v[120:123], v[140:143], v[148:151], v[120:123]
	v_mfma_f32_16x16x32_bf16 v[116:119], v[132:135], v[170:173], v[116:119]
	v_mfma_f32_16x16x32_bf16 v[108:111], v[140:143], v[170:173], v[108:111]
	v_mfma_f32_16x16x32_bf16 v[100:103], v[132:135], v[178:181], v[100:103]
	v_mfma_f32_16x16x32_bf16 v[92:95], v[140:143], v[178:181], v[92:95]
	v_mfma_f32_16x16x32_bf16 v[84:87], v[132:135], v[186:189], v[84:87]
	v_mfma_f32_16x16x32_bf16 v[76:79], v[140:143], v[186:189], v[76:79]
	s_barrier
	s_add_i32 s21, 0, 0x14000
	s_add_i32 s74, s74, s53
	v_add_u32_e32 v215, s21, v161
	v_lshl_add_u64 v[228:229], s[60:61], 0, v[156:157]
	s_mov_b32 m0, s74
	ds_read_b128 v[206:209], v215
	ds_read_b128 v[216:219], v215 offset:1024
	ds_read_b128 v[220:223], v215 offset:2048
	ds_read_b128 v[224:227], v215 offset:3072
	global_load_lds_dwordx4 v[228:229], off
	v_lshl_add_u64 v[230:231], s[60:61], 0, v[162:163]
	s_add_i32 m0, s74, 0x2000
	s_nop 0
	global_load_lds_dwordx4 v[230:231], off
	s_barrier
	s_waitcnt lgkmcnt(0)
	s_waitcnt lgkmcnt(0)
	v_mfma_f32_16x16x32_bf16 v[112:115], v[206:209], v[144:147], v[112:115]
	v_mfma_f32_16x16x32_bf16 v[104:107], v[220:223], v[144:147], v[104:107]
	v_mfma_f32_16x16x32_bf16 v[96:99], v[206:209], v[152:155], v[96:99]
	v_mfma_f32_16x16x32_bf16 v[88:91], v[220:223], v[152:155], v[88:91]
	v_mfma_f32_16x16x32_bf16 v[80:83], v[206:209], v[174:177], v[80:83]
	v_mfma_f32_16x16x32_bf16 v[72:75], v[220:223], v[174:177], v[72:75]
	v_mfma_f32_16x16x32_bf16 v[68:71], v[206:209], v[182:185], v[68:71]
	v_mfma_f32_16x16x32_bf16 v[64:67], v[220:223], v[182:185], v[64:67]
	v_mfma_f32_16x16x32_bf16 v[112:115], v[216:219], v[148:151], v[112:115]
	v_mfma_f32_16x16x32_bf16 v[104:107], v[224:227], v[148:151], v[104:107]
	v_mfma_f32_16x16x32_bf16 v[96:99], v[216:219], v[170:173], v[96:99]
	v_mfma_f32_16x16x32_bf16 v[88:91], v[224:227], v[170:173], v[88:91]
	v_mfma_f32_16x16x32_bf16 v[80:83], v[216:219], v[178:181], v[80:83]
	v_mfma_f32_16x16x32_bf16 v[72:75], v[224:227], v[178:181], v[72:75]
	v_mfma_f32_16x16x32_bf16 v[68:71], v[216:219], v[186:189], v[68:71]
	v_mfma_f32_16x16x32_bf16 v[64:67], v[224:227], v[186:189], v[64:67]
	s_mov_b32 m0, s88
	v_lshl_add_u64 v[232:233], s[2:3], 0, v[156:157]
	s_barrier
	ds_read_b128 v[144:147], v214 offset:16384
	ds_read_b128 v[148:151], v214 offset:17408
	ds_read_b128 v[152:155], v214 offset:18432
	ds_read_b128 v[170:173], v214 offset:19456
	ds_read_b128 v[174:177], v214 offset:20480
	ds_read_b128 v[178:181], v214 offset:21504
	ds_read_b128 v[182:185], v214 offset:22528
	ds_read_b128 v[186:189], v214 offset:23552
	global_load_lds_dwordx4 v[232:233], off
	v_lshl_add_u64 v[234:235], s[2:3], 0, v[162:163]
	s_mov_b32 m0, s89
	s_nop 0
	global_load_lds_dwordx4 v[234:235], off
	s_barrier
	s_waitcnt lgkmcnt(0)
	s_waitcnt lgkmcnt(0)
	v_mfma_f32_16x16x32_bf16 v[60:63], v[128:131], v[144:147], v[60:63]
	v_mfma_f32_16x16x32_bf16 v[56:59], v[136:139], v[144:147], v[56:59]
	v_mfma_f32_16x16x32_bf16 v[52:55], v[128:131], v[152:155], v[52:55]
	v_mfma_f32_16x16x32_bf16 v[44:47], v[136:139], v[152:155], v[44:47]
	v_mfma_f32_16x16x32_bf16 v[36:39], v[128:131], v[174:177], v[36:39]
	v_mfma_f32_16x16x32_bf16 v[28:31], v[136:139], v[174:177], v[28:31]
	v_mfma_f32_16x16x32_bf16 v[20:23], v[128:131], v[182:185], v[20:23]
	v_mfma_f32_16x16x32_bf16 v[12:15], v[136:139], v[182:185], v[12:15]
	v_mfma_f32_16x16x32_bf16 v[60:63], v[132:135], v[148:151], v[60:63]
	v_mfma_f32_16x16x32_bf16 v[56:59], v[140:143], v[148:151], v[56:59]
	v_mfma_f32_16x16x32_bf16 v[52:55], v[132:135], v[170:173], v[52:55]
	v_mfma_f32_16x16x32_bf16 v[44:47], v[140:143], v[170:173], v[44:47]
	v_mfma_f32_16x16x32_bf16 v[36:39], v[132:135], v[178:181], v[36:39]
	v_mfma_f32_16x16x32_bf16 v[28:31], v[140:143], v[178:181], v[28:31]
	v_mfma_f32_16x16x32_bf16 v[20:23], v[132:135], v[186:189], v[20:23]
	v_mfma_f32_16x16x32_bf16 v[12:15], v[140:143], v[186:189], v[12:15]
	s_barrier
	s_add_u32 s60, s60, s54
	s_addc_u32 s61, s61, 0
	s_add_i32 s21, s21, s53
	v_lshl_add_u64 v[236:237], s[60:61], 0, v[156:157]
	s_mov_b32 m0, s21
	v_lshl_add_u64 v[238:239], s[60:61], 0, v[162:163]
	global_load_lds_dwordx4 v[236:237], off
	s_add_i32 m0, s21, 0x2000
	s_nop 0
	global_load_lds_dwordx4 v[238:239], off
	s_waitcnt vmcnt(6)
	s_barrier
	v_mfma_f32_16x16x32_bf16 v[48:51], v[206:209], v[144:147], v[48:51]
	v_mfma_f32_16x16x32_bf16 v[40:43], v[220:223], v[144:147], v[40:43]
	v_mfma_f32_16x16x32_bf16 v[32:35], v[206:209], v[152:155], v[32:35]
	v_mfma_f32_16x16x32_bf16 v[24:27], v[220:223], v[152:155], v[24:27]
	v_mfma_f32_16x16x32_bf16 v[16:19], v[206:209], v[174:177], v[16:19]
	v_mfma_f32_16x16x32_bf16 v[8:11], v[220:223], v[174:177], v[8:11]
	v_mfma_f32_16x16x32_bf16 v[4:7], v[206:209], v[182:185], v[4:7]
	v_mfma_f32_16x16x32_bf16 v[0:3], v[220:223], v[182:185], v[0:3]
	v_mfma_f32_16x16x32_bf16 v[48:51], v[216:219], v[148:151], v[48:51]
	v_mfma_f32_16x16x32_bf16 v[40:43], v[224:227], v[148:151], v[40:43]
	v_mfma_f32_16x16x32_bf16 v[32:35], v[216:219], v[170:173], v[32:35]
	v_mfma_f32_16x16x32_bf16 v[24:27], v[224:227], v[170:173], v[24:27]
	v_mfma_f32_16x16x32_bf16 v[16:19], v[216:219], v[178:181], v[16:19]
	v_mfma_f32_16x16x32_bf16 v[8:11], v[224:227], v[178:181], v[8:11]
	v_mfma_f32_16x16x32_bf16 v[4:7], v[216:219], v[186:189], v[4:7]
	v_mfma_f32_16x16x32_bf16 v[0:3], v[224:227], v[186:189], v[0:3]
	s_add_i32 s21, 0, 0x18000
	v_add_u32_e32 v140, s21, v161
	s_barrier
	ds_read_b128 v[128:131], v140
	ds_read_b128 v[132:135], v140 offset:1024
	ds_read_b128 v[136:139], v140 offset:2048
	ds_read_b128 v[140:143], v140 offset:3072
	s_add_u32 s2, s2, s54
	s_addc_u32 s3, s3, 0
	s_mov_b32 m0, s94
	v_lshl_add_u64 v[206:207], s[2:3], 0, v[156:157]
	ds_read_b128 v[144:147], v214 offset:32768
	ds_read_b128 v[148:151], v214 offset:33792
	ds_read_b128 v[152:155], v214 offset:34816
	ds_read_b128 v[170:173], v214 offset:35840
	ds_read_b128 v[174:177], v214 offset:36864
	ds_read_b128 v[178:181], v214 offset:37888
	ds_read_b128 v[182:185], v214 offset:38912
	ds_read_b128 v[186:189], v214 offset:39936
	global_load_lds_dwordx4 v[206:207], off
	v_lshl_add_u64 v[206:207], s[2:3], 0, v[162:163]
	s_mov_b32 m0, s95
	s_nop 0
	global_load_lds_dwordx4 v[206:207], off
	s_waitcnt lgkmcnt(8)
	s_barrier
	s_waitcnt lgkmcnt(0)
	s_waitcnt lgkmcnt(0)
	v_mfma_f32_16x16x32_bf16 v[124:127], v[128:131], v[144:147], v[124:127]
	v_mfma_f32_16x16x32_bf16 v[120:123], v[136:139], v[144:147], v[120:123]
	v_mfma_f32_16x16x32_bf16 v[116:119], v[128:131], v[152:155], v[116:119]
	v_mfma_f32_16x16x32_bf16 v[108:111], v[136:139], v[152:155], v[108:111]
	v_mfma_f32_16x16x32_bf16 v[100:103], v[128:131], v[174:177], v[100:103]
	v_mfma_f32_16x16x32_bf16 v[92:95], v[136:139], v[174:177], v[92:95]
	v_mfma_f32_16x16x32_bf16 v[84:87], v[128:131], v[182:185], v[84:87]
	v_mfma_f32_16x16x32_bf16 v[76:79], v[136:139], v[182:185], v[76:79]
	v_mfma_f32_16x16x32_bf16 v[124:127], v[132:135], v[148:151], v[124:127]
	v_mfma_f32_16x16x32_bf16 v[120:123], v[140:143], v[148:151], v[120:123]
	v_mfma_f32_16x16x32_bf16 v[116:119], v[132:135], v[170:173], v[116:119]
	v_mfma_f32_16x16x32_bf16 v[108:111], v[140:143], v[170:173], v[108:111]
	v_mfma_f32_16x16x32_bf16 v[100:103], v[132:135], v[178:181], v[100:103]
	v_mfma_f32_16x16x32_bf16 v[92:95], v[140:143], v[178:181], v[92:95]
	v_mfma_f32_16x16x32_bf16 v[84:87], v[132:135], v[186:189], v[84:87]
	v_mfma_f32_16x16x32_bf16 v[76:79], v[140:143], v[186:189], v[76:79]
	s_barrier
	s_add_i32 s2, 0, 0x1c000
	s_add_i32 s3, s21, s53
	v_add_u32_e32 v215, s2, v161
	v_lshl_add_u64 v[228:229], v[228:229], 0, s[50:51]
	s_mov_b32 m0, s3
	ds_read_b128 v[206:209], v215
	ds_read_b128 v[216:219], v215 offset:1024
	ds_read_b128 v[220:223], v215 offset:2048
	ds_read_b128 v[224:227], v215 offset:3072
	global_load_lds_dwordx4 v[228:229], off
	v_lshl_add_u64 v[228:229], v[230:231], 0, s[50:51]
	s_add_i32 m0, s3, 0x2000
	s_nop 0
	global_load_lds_dwordx4 v[228:229], off
	s_barrier
	s_waitcnt lgkmcnt(0)
	s_waitcnt lgkmcnt(0)
	v_mfma_f32_16x16x32_bf16 v[112:115], v[206:209], v[144:147], v[112:115]
	v_mfma_f32_16x16x32_bf16 v[104:107], v[220:223], v[144:147], v[104:107]
	v_mfma_f32_16x16x32_bf16 v[96:99], v[206:209], v[152:155], v[96:99]
	v_mfma_f32_16x16x32_bf16 v[88:91], v[220:223], v[152:155], v[88:91]
	v_mfma_f32_16x16x32_bf16 v[80:83], v[206:209], v[174:177], v[80:83]
	v_mfma_f32_16x16x32_bf16 v[72:75], v[220:223], v[174:177], v[72:75]
	v_mfma_f32_16x16x32_bf16 v[68:71], v[206:209], v[182:185], v[68:71]
	v_mfma_f32_16x16x32_bf16 v[64:67], v[220:223], v[182:185], v[64:67]
	v_mfma_f32_16x16x32_bf16 v[112:115], v[216:219], v[148:151], v[112:115]
	v_mfma_f32_16x16x32_bf16 v[104:107], v[224:227], v[148:151], v[104:107]
	v_mfma_f32_16x16x32_bf16 v[96:99], v[216:219], v[170:173], v[96:99]
	v_mfma_f32_16x16x32_bf16 v[88:91], v[224:227], v[170:173], v[88:91]
	v_mfma_f32_16x16x32_bf16 v[80:83], v[216:219], v[178:181], v[80:83]
	v_mfma_f32_16x16x32_bf16 v[72:75], v[224:227], v[178:181], v[72:75]
	v_mfma_f32_16x16x32_bf16 v[68:71], v[216:219], v[186:189], v[68:71]
	v_mfma_f32_16x16x32_bf16 v[64:67], v[224:227], v[186:189], v[64:67]
	s_mov_b32 m0, s96
	v_lshl_add_u64 v[228:229], v[232:233], 0, s[50:51]
	s_barrier
	ds_read_b128 v[144:147], v214 offset:49152
	ds_read_b128 v[148:151], v214 offset:50176
	ds_read_b128 v[152:155], v214 offset:51200
	ds_read_b128 v[170:173], v214 offset:52224
	ds_read_b128 v[174:177], v214 offset:53248
	ds_read_b128 v[178:181], v214 offset:54272
	ds_read_b128 v[182:185], v214 offset:55296
	ds_read_b128 v[186:189], v214 offset:56320
	global_load_lds_dwordx4 v[228:229], off
	v_lshl_add_u64 v[228:229], v[234:235], 0, s[50:51]
	s_mov_b32 m0, s97
	s_nop 0
	global_load_lds_dwordx4 v[228:229], off
	s_barrier
	s_waitcnt lgkmcnt(0)
	s_waitcnt lgkmcnt(0)
	v_mfma_f32_16x16x32_bf16 v[60:63], v[128:131], v[144:147], v[60:63]
	v_mfma_f32_16x16x32_bf16 v[56:59], v[136:139], v[144:147], v[56:59]
	v_mfma_f32_16x16x32_bf16 v[52:55], v[128:131], v[152:155], v[52:55]
	v_mfma_f32_16x16x32_bf16 v[44:47], v[136:139], v[152:155], v[44:47]
	v_mfma_f32_16x16x32_bf16 v[36:39], v[128:131], v[174:177], v[36:39]
	v_mfma_f32_16x16x32_bf16 v[28:31], v[136:139], v[174:177], v[28:31]
	v_mfma_f32_16x16x32_bf16 v[20:23], v[128:131], v[182:185], v[20:23]
	v_mfma_f32_16x16x32_bf16 v[12:15], v[136:139], v[182:185], v[12:15]
	v_mfma_f32_16x16x32_bf16 v[60:63], v[132:135], v[148:151], v[60:63]
	v_mfma_f32_16x16x32_bf16 v[56:59], v[140:143], v[148:151], v[56:59]
	v_mfma_f32_16x16x32_bf16 v[52:55], v[132:135], v[170:173], v[52:55]
	v_mfma_f32_16x16x32_bf16 v[44:47], v[140:143], v[170:173], v[44:47]
	v_mfma_f32_16x16x32_bf16 v[36:39], v[132:135], v[178:181], v[36:39]
	v_mfma_f32_16x16x32_bf16 v[28:31], v[140:143], v[178:181], v[28:31]
	v_mfma_f32_16x16x32_bf16 v[20:23], v[132:135], v[186:189], v[20:23]
	v_mfma_f32_16x16x32_bf16 v[12:15], v[140:143], v[186:189], v[12:15]
	s_barrier
	s_add_i32 s2, s2, s53
	v_lshl_add_u64 v[128:129], v[236:237], 0, s[50:51]
	s_mov_b32 m0, s2
	s_nop 0
	global_load_lds_dwordx4 v[128:129], off
	v_lshl_add_u64 v[128:129], v[238:239], 0, s[50:51]
	s_add_i32 m0, s2, 0x2000
	s_nop 0
	global_load_lds_dwordx4 v[128:129], off
	s_waitcnt vmcnt(6)
	s_barrier
	v_mfma_f32_16x16x32_bf16 v[48:51], v[206:209], v[144:147], v[48:51]
	v_mfma_f32_16x16x32_bf16 v[40:43], v[220:223], v[144:147], v[40:43]
	v_mfma_f32_16x16x32_bf16 v[32:35], v[206:209], v[152:155], v[32:35]
	v_mfma_f32_16x16x32_bf16 v[24:27], v[220:223], v[152:155], v[24:27]
	v_mfma_f32_16x16x32_bf16 v[16:19], v[206:209], v[174:177], v[16:19]
	v_mfma_f32_16x16x32_bf16 v[8:11], v[220:223], v[174:177], v[8:11]
	v_mfma_f32_16x16x32_bf16 v[4:7], v[206:209], v[182:185], v[4:7]
	v_mfma_f32_16x16x32_bf16 v[0:3], v[220:223], v[182:185], v[0:3]
	v_mfma_f32_16x16x32_bf16 v[48:51], v[216:219], v[148:151], v[48:51]
	v_mfma_f32_16x16x32_bf16 v[40:43], v[224:227], v[148:151], v[40:43]
	v_mfma_f32_16x16x32_bf16 v[32:35], v[216:219], v[170:173], v[32:35]
	v_mfma_f32_16x16x32_bf16 v[24:27], v[224:227], v[170:173], v[24:27]
	v_mfma_f32_16x16x32_bf16 v[16:19], v[216:219], v[178:181], v[16:19]
	v_mfma_f32_16x16x32_bf16 v[8:11], v[224:227], v[178:181], v[8:11]
	v_mfma_f32_16x16x32_bf16 v[4:7], v[216:219], v[186:189], v[4:7]
	v_mfma_f32_16x16x32_bf16 v[0:3], v[224:227], v[186:189], v[0:3]
	s_add_u32 s83, s83, 0x100
	s_addc_u32 vcc_lo, vcc_lo, 0
	s_add_u32 s6, s6, 0x100
	s_addc_u32 s7, s7, 0
	s_cmp_ge_u32 vcc_hi, s84
	s_mov_b32 s2, vcc_hi
	s_barrier
	s_cbranch_scc0 .LBB0_514

.LBB0_554:
	s_add_i32 s68, s68, 1
	s_mul_i32 s2, s68, s18
	s_add_i32 s10, s2, s20
	s_cmp_lt_i32 s10, s19
	s_cselect_b64 s[2:3], -1, 0
	s_cmp_ge_i32 s10, s19
	s_cselect_b64 s[38:39], -1, 0
	s_and_b64 s[6:7], s[2:3], exec
	s_cselect_b32 s6, s10, 0
	s_ashr_i32 s7, s6, 31
	s_lshr_b32 s7, s7, 29
	s_add_i32 s7, s6, s7
	s_ashr_i32 s10, s7, 3
	s_and_b32 s7, s7, -8
	s_sub_i32 s6, s6, s7
	s_cmp_lt_i32 s6, 0
	s_cselect_b32 s7, s61, s60
	s_mul_i32 s6, s7, s6
	s_add_i32 s10, s6, s10
	s_mul_hi_i32 s6, s10, 0x2e8ba2e9
	s_lshr_b32 s7, s6, 31
	s_ashr_i32 s6, s6, 4
	s_add_i32 s24, s6, s7
	s_lshl_b32 s25, s24, 2
	s_sub_i32 s6, s9, s25
	s_min_i32 s41, s6, 4
	s_abs_i32 s40, s41
	v_cvt_f32_u32_e32 v0, s40
	s_mov_b64 s[6:7], s[34:35]
	s_mov_b64 s[54:55], s[36:37]
	s_sub_i32 s35, 0, s40
	v_rcp_iflag_f32_e32 v0, v0
	s_mulk_i32 s24, 0x58
	s_sub_i32 s10, s10, s24
	s_abs_i32 s34, s10
	v_mul_f32_e32 v0, 0x4f7ffffe, v0
	v_cvt_u32_f32_e32 v0, v0
	s_xor_b32 s24, s10, s41
	s_ashr_i32 s24, s24, 31
	s_mov_b32 s73, -2
	v_readfirstlane_b32 s36, v0
	s_mul_i32 s35, s35, s36
	s_mul_hi_u32 s35, s36, s35
	s_add_i32 s36, s36, s35
	s_mul_hi_u32 s35, s34, s36
	s_mul_i32 s36, s35, s40
	s_sub_i32 s34, s34, s36
	s_add_i32 s36, s35, 1
	s_sub_i32 s37, s34, s40
	s_cmp_ge_u32 s34, s40
	s_cselect_b32 s35, s36, s35
	s_cselect_b32 s34, s37, s34
	s_add_i32 s36, s35, 1
	s_cmp_ge_u32 s34, s40
	s_cselect_b32 s34, s36, s35
	s_xor_b32 s34, s34, s24
	s_sub_i32 s40, s34, s24
	s_mul_i32 s24, s40, s41
	s_sub_i32 s10, s10, s24
	s_add_i32 s42, s25, s10
	s_ashr_i32 s43, s42, 31
	s_lshl_b64 s[24:25], s[42:43], 19
	s_add_u32 s34, s58, s24
	s_addc_u32 s35, s59, s25
	s_and_b64 s[24:25], s[2:3], exec
	s_cselect_b32 s10, s35, s7
	s_cselect_b32 s24, s34, s6
	s_ashr_i32 s41, s40, 31
	s_lshl_b64 s[36:37], s[40:41], 19
	s_add_u32 s36, s44, s36
	s_addc_u32 s37, s45, s37
	s_and_b64 s[2:3], s[2:3], exec
	s_cselect_b32 s25, s37, s55
	s_cselect_b32 s41, s36, s54
	s_add_u32 s43, s54, 0x100
	s_addc_u32 s69, s55, 0
	s_add_u32 s6, s6, 0x40080
	s_addc_u32 s7, s7, 0
	s_add_u32 s2, s6, 0xfffc0080
	s_addc_u32 s3, s7, -1
	s_add_i32 s77, 0, 0x10000
	v_add_u32_e32 v150, s77, v139
	ds_read_b128 v[134:137], v150
	ds_read_b128 v[142:145], v150 offset:1024
	ds_read_b128 v[146:149], v150 offset:2048
	ds_read_b128 v[150:153], v150 offset:3072
	s_cmp_eq_u32 s73, 12
	s_cselect_b32 s3, s10, s3
	s_cselect_b32 s2, s24, s2
	s_cselect_b32 s55, s25, s69
	s_cselect_b32 s54, s41, s43
	v_lshl_add_u64 v[154:155], s[6:7], 0, v[132:133]
	s_add_i32 m0, s47, 0xc000
	ds_read_b128 v[162:165], v141
	ds_read_b128 v[166:169], v141 offset:1024
	ds_read_b128 v[170:173], v141 offset:2048
	ds_read_b128 v[174:177], v141 offset:3072
	ds_read_b128 v[178:181], v141 offset:4096
	ds_read_b128 v[182:185], v141 offset:5120
	ds_read_b128 v[186:189], v141 offset:6144
	ds_read_b128 v[214:217], v141 offset:7168
	global_load_lds_dwordx4 v[154:155], off
	v_lshl_add_u64 v[154:155], s[6:7], 0, v[130:131]
	s_add_i32 m0, s47, 0xe000
	s_nop 0
	global_load_lds_dwordx4 v[154:155], off
	s_waitcnt lgkmcnt(8)
	s_barrier
	s_waitcnt lgkmcnt(0)
	s_waitcnt lgkmcnt(0)
	v_mfma_f32_16x16x32_bf16 v[124:127], v[134:137], v[162:165], 0
	v_mfma_f32_16x16x32_bf16 v[116:119], v[146:149], v[162:165], 0
	v_mfma_f32_16x16x32_bf16 v[108:111], v[134:137], v[170:173], 0
	v_mfma_f32_16x16x32_bf16 v[100:103], v[146:149], v[170:173], 0
	v_mfma_f32_16x16x32_bf16 v[92:95], v[134:137], v[178:181], 0
	v_mfma_f32_16x16x32_bf16 v[84:87], v[146:149], v[178:181], 0
	v_mfma_f32_16x16x32_bf16 v[76:79], v[134:137], v[186:189], 0
	v_mfma_f32_16x16x32_bf16 v[68:71], v[146:149], v[186:189], 0
	v_mfma_f32_16x16x32_bf16 v[124:127], v[142:145], v[166:169], v[124:127]
	v_mfma_f32_16x16x32_bf16 v[116:119], v[150:153], v[166:169], v[116:119]
	v_mfma_f32_16x16x32_bf16 v[108:111], v[142:145], v[174:177], v[108:111]
	v_mfma_f32_16x16x32_bf16 v[100:103], v[150:153], v[174:177], v[100:103]
	v_mfma_f32_16x16x32_bf16 v[92:95], v[142:145], v[182:185], v[92:95]
	v_mfma_f32_16x16x32_bf16 v[84:87], v[150:153], v[182:185], v[84:87]
	v_mfma_f32_16x16x32_bf16 v[76:79], v[142:145], v[214:217], v[76:79]
	v_mfma_f32_16x16x32_bf16 v[68:71], v[150:153], v[214:217], v[68:71]
	s_barrier
	s_add_i32 s80, 0, 0x14000
	v_add_u32_e32 v154, s80, v139
	s_add_i32 s77, s77, s53
	ds_read_b128 v[218:221], v154
	ds_read_b128 v[222:225], v154 offset:1024
	ds_read_b128 v[226:229], v154 offset:2048
	ds_read_b128 v[230:233], v154 offset:3072
	v_lshl_add_u64 v[154:155], s[54:55], 0, v[156:157]
	s_mov_b32 m0, s77
	v_lshl_add_u64 v[206:207], s[54:55], 0, v[128:129]
	global_load_lds_dwordx4 v[154:155], off
	s_add_i32 m0, s77, 0x2000
	s_nop 0
	global_load_lds_dwordx4 v[206:207], off
	s_barrier
	s_waitcnt lgkmcnt(0)
	s_waitcnt lgkmcnt(0)
	v_mfma_f32_16x16x32_bf16 v[120:123], v[218:221], v[162:165], 0
	v_mfma_f32_16x16x32_bf16 v[112:115], v[226:229], v[162:165], 0
	v_mfma_f32_16x16x32_bf16 v[104:107], v[218:221], v[170:173], 0
	v_mfma_f32_16x16x32_bf16 v[96:99], v[226:229], v[170:173], 0
	v_mfma_f32_16x16x32_bf16 v[88:91], v[218:221], v[178:181], 0
	v_mfma_f32_16x16x32_bf16 v[80:83], v[226:229], v[178:181], 0
	v_mfma_f32_16x16x32_bf16 v[72:75], v[218:221], v[186:189], 0
	v_mfma_f32_16x16x32_bf16 v[64:67], v[226:229], v[186:189], 0
	v_mfma_f32_16x16x32_bf16 v[120:123], v[222:225], v[166:169], v[120:123]
	v_mfma_f32_16x16x32_bf16 v[112:115], v[230:233], v[166:169], v[112:115]
	v_mfma_f32_16x16x32_bf16 v[104:107], v[222:225], v[174:177], v[104:107]
	v_mfma_f32_16x16x32_bf16 v[96:99], v[230:233], v[174:177], v[96:99]
	v_mfma_f32_16x16x32_bf16 v[88:91], v[222:225], v[182:185], v[88:91]
	v_mfma_f32_16x16x32_bf16 v[80:83], v[230:233], v[182:185], v[80:83]
	v_mfma_f32_16x16x32_bf16 v[72:75], v[222:225], v[214:217], v[72:75]
	v_mfma_f32_16x16x32_bf16 v[64:67], v[230:233], v[214:217], v[64:67]
	s_mov_b32 m0, s47
	v_lshl_add_u64 v[208:209], s[2:3], 0, v[156:157]
	s_barrier
	ds_read_b128 v[162:165], v141 offset:16384
	ds_read_b128 v[166:169], v141 offset:17408
	ds_read_b128 v[170:173], v141 offset:18432
	ds_read_b128 v[174:177], v141 offset:19456
	ds_read_b128 v[178:181], v141 offset:20480
	ds_read_b128 v[182:185], v141 offset:21504
	ds_read_b128 v[186:189], v141 offset:22528
	ds_read_b128 v[214:217], v141 offset:23552
	global_load_lds_dwordx4 v[208:209], off
	v_lshl_add_u64 v[234:235], s[2:3], 0, v[128:129]
	s_mov_b32 m0, s49
	s_nop 0
	global_load_lds_dwordx4 v[234:235], off
	s_barrier
	s_waitcnt lgkmcnt(0)
	s_waitcnt lgkmcnt(0)
	v_mfma_f32_16x16x32_bf16 v[60:63], v[134:137], v[162:165], 0
	v_mfma_f32_16x16x32_bf16 v[52:55], v[146:149], v[162:165], 0
	v_mfma_f32_16x16x32_bf16 v[44:47], v[134:137], v[170:173], 0
	v_mfma_f32_16x16x32_bf16 v[36:39], v[146:149], v[170:173], 0
	v_mfma_f32_16x16x32_bf16 v[28:31], v[134:137], v[178:181], 0
	v_mfma_f32_16x16x32_bf16 v[20:23], v[146:149], v[178:181], 0
	v_mfma_f32_16x16x32_bf16 v[12:15], v[134:137], v[186:189], 0
	v_mfma_f32_16x16x32_bf16 v[4:7], v[146:149], v[186:189], 0
	v_mfma_f32_16x16x32_bf16 v[60:63], v[142:145], v[166:169], v[60:63]
	v_mfma_f32_16x16x32_bf16 v[52:55], v[150:153], v[166:169], v[52:55]
	v_mfma_f32_16x16x32_bf16 v[44:47], v[142:145], v[174:177], v[44:47]
	v_mfma_f32_16x16x32_bf16 v[36:39], v[150:153], v[174:177], v[36:39]
	v_mfma_f32_16x16x32_bf16 v[28:31], v[142:145], v[182:185], v[28:31]
	v_mfma_f32_16x16x32_bf16 v[20:23], v[150:153], v[182:185], v[20:23]
	v_mfma_f32_16x16x32_bf16 v[12:15], v[142:145], v[214:217], v[12:15]
	v_mfma_f32_16x16x32_bf16 v[4:7], v[150:153], v[214:217], v[4:7]
	s_barrier
	s_add_u32 s78, s54, 0x40000
	s_addc_u32 s79, s55, 0
	s_add_i32 s77, s80, s53
	v_lshl_add_u64 v[134:135], s[78:79], 0, v[156:157]
	s_mov_b32 m0, s77
	s_nop 0
	global_load_lds_dwordx4 v[134:135], off
	v_lshl_add_u64 v[134:135], s[78:79], 0, v[128:129]
	s_add_i32 m0, s77, 0x2000
	s_nop 0
	global_load_lds_dwordx4 v[134:135], off
	s_waitcnt vmcnt(6)
	s_barrier
	v_mfma_f32_16x16x32_bf16 v[56:59], v[218:221], v[162:165], 0
	v_mfma_f32_16x16x32_bf16 v[48:51], v[226:229], v[162:165], 0
	v_mfma_f32_16x16x32_bf16 v[40:43], v[218:221], v[170:173], 0
	v_mfma_f32_16x16x32_bf16 v[32:35], v[226:229], v[170:173], 0
	v_mfma_f32_16x16x32_bf16 v[24:27], v[218:221], v[178:181], 0
	v_mfma_f32_16x16x32_bf16 v[16:19], v[226:229], v[178:181], 0
	v_mfma_f32_16x16x32_bf16 v[8:11], v[218:221], v[186:189], 0
	v_mfma_f32_16x16x32_bf16 v[0:3], v[226:229], v[186:189], 0
	v_mfma_f32_16x16x32_bf16 v[56:59], v[222:225], v[166:169], v[56:59]
	v_mfma_f32_16x16x32_bf16 v[48:51], v[230:233], v[166:169], v[48:51]
	v_mfma_f32_16x16x32_bf16 v[40:43], v[222:225], v[174:177], v[40:43]
	v_mfma_f32_16x16x32_bf16 v[32:35], v[230:233], v[174:177], v[32:35]
	v_mfma_f32_16x16x32_bf16 v[24:27], v[222:225], v[182:185], v[24:27]
	v_mfma_f32_16x16x32_bf16 v[16:19], v[230:233], v[182:185], v[16:19]
	v_mfma_f32_16x16x32_bf16 v[8:11], v[222:225], v[214:217], v[8:11]
	v_mfma_f32_16x16x32_bf16 v[0:3], v[230:233], v[214:217], v[0:3]
	s_add_i32 s77, 0, 0x18000
	v_add_u32_e32 v150, s77, v139
	s_barrier
	ds_read_b128 v[134:137], v150
	ds_read_b128 v[142:145], v150 offset:1024
	ds_read_b128 v[146:149], v150 offset:2048
	ds_read_b128 v[150:153], v150 offset:3072
	s_add_u32 s2, s2, 0x40000
	s_addc_u32 s3, s3, 0
	s_mov_b32 m0, s62
	v_lshl_add_u64 v[218:219], s[2:3], 0, v[156:157]
	ds_read_b128 v[162:165], v141 offset:32768
	ds_read_b128 v[166:169], v141 offset:33792
	ds_read_b128 v[170:173], v141 offset:34816
	ds_read_b128 v[174:177], v141 offset:35840
	ds_read_b128 v[178:181], v141 offset:36864
	ds_read_b128 v[182:185], v141 offset:37888
	ds_read_b128 v[186:189], v141 offset:38912
	ds_read_b128 v[214:217], v141 offset:39936
	global_load_lds_dwordx4 v[218:219], off
	v_lshl_add_u64 v[218:219], s[2:3], 0, v[128:129]
	s_mov_b32 m0, s63
	s_nop 0
	global_load_lds_dwordx4 v[218:219], off
	s_waitcnt lgkmcnt(8)
	s_barrier
	s_waitcnt lgkmcnt(0)
	s_waitcnt lgkmcnt(0)
	v_mfma_f32_16x16x32_bf16 v[124:127], v[134:137], v[162:165], v[124:127]
	v_mfma_f32_16x16x32_bf16 v[116:119], v[146:149], v[162:165], v[116:119]
	v_mfma_f32_16x16x32_bf16 v[108:111], v[134:137], v[170:173], v[108:111]
	v_mfma_f32_16x16x32_bf16 v[100:103], v[146:149], v[170:173], v[100:103]
	v_mfma_f32_16x16x32_bf16 v[92:95], v[134:137], v[178:181], v[92:95]
	v_mfma_f32_16x16x32_bf16 v[84:87], v[146:149], v[178:181], v[84:87]
	v_mfma_f32_16x16x32_bf16 v[76:79], v[134:137], v[186:189], v[76:79]
	v_mfma_f32_16x16x32_bf16 v[68:71], v[146:149], v[186:189], v[68:71]
	v_mfma_f32_16x16x32_bf16 v[124:127], v[142:145], v[166:169], v[124:127]
	v_mfma_f32_16x16x32_bf16 v[116:119], v[150:153], v[166:169], v[116:119]
	v_mfma_f32_16x16x32_bf16 v[108:111], v[142:145], v[174:177], v[108:111]
	v_mfma_f32_16x16x32_bf16 v[100:103], v[150:153], v[174:177], v[100:103]
	v_mfma_f32_16x16x32_bf16 v[92:95], v[142:145], v[182:185], v[92:95]
	v_mfma_f32_16x16x32_bf16 v[84:87], v[150:153], v[182:185], v[84:87]
	v_mfma_f32_16x16x32_bf16 v[76:79], v[142:145], v[214:217], v[76:79]
	v_mfma_f32_16x16x32_bf16 v[68:71], v[150:153], v[214:217], v[68:71]
	s_barrier
	s_add_i32 s78, 0, 0x1c000
	s_add_i32 s2, s77, s53
	v_add_u32_e32 v161, s78, v139
	v_lshl_add_u64 v[154:155], v[154:155], 0, s[50:51]
	s_mov_b32 m0, s2
	ds_read_b128 v[218:221], v161
	ds_read_b128 v[222:225], v161 offset:1024
	ds_read_b128 v[226:229], v161 offset:2048
	ds_read_b128 v[230:233], v161 offset:3072
	global_load_lds_dwordx4 v[154:155], off
	v_lshl_add_u64 v[154:155], v[206:207], 0, s[50:51]
	s_add_i32 m0, s2, 0x2000
	s_nop 0
	global_load_lds_dwordx4 v[154:155], off
	s_barrier
	s_waitcnt lgkmcnt(0)
	s_waitcnt lgkmcnt(0)
	v_mfma_f32_16x16x32_bf16 v[120:123], v[218:221], v[162:165], v[120:123]
	v_mfma_f32_16x16x32_bf16 v[112:115], v[226:229], v[162:165], v[112:115]
	v_mfma_f32_16x16x32_bf16 v[104:107], v[218:221], v[170:173], v[104:107]
	v_mfma_f32_16x16x32_bf16 v[96:99], v[226:229], v[170:173], v[96:99]
	v_mfma_f32_16x16x32_bf16 v[88:91], v[218:221], v[178:181], v[88:91]
	v_mfma_f32_16x16x32_bf16 v[80:83], v[226:229], v[178:181], v[80:83]
	v_mfma_f32_16x16x32_bf16 v[72:75], v[218:221], v[186:189], v[72:75]
	v_mfma_f32_16x16x32_bf16 v[64:67], v[226:229], v[186:189], v[64:67]
	v_mfma_f32_16x16x32_bf16 v[120:123], v[222:225], v[166:169], v[120:123]
	v_mfma_f32_16x16x32_bf16 v[112:115], v[230:233], v[166:169], v[112:115]
	v_mfma_f32_16x16x32_bf16 v[104:107], v[222:225], v[174:177], v[104:107]
	v_mfma_f32_16x16x32_bf16 v[96:99], v[230:233], v[174:177], v[96:99]
	v_mfma_f32_16x16x32_bf16 v[88:91], v[222:225], v[182:185], v[88:91]
	v_mfma_f32_16x16x32_bf16 v[80:83], v[230:233], v[182:185], v[80:83]
	v_mfma_f32_16x16x32_bf16 v[72:75], v[222:225], v[214:217], v[72:75]
	v_mfma_f32_16x16x32_bf16 v[64:67], v[230:233], v[214:217], v[64:67]
	s_mov_b32 m0, s66
	v_lshl_add_u64 v[154:155], v[208:209], 0, s[50:51]
	s_barrier
	ds_read_b128 v[162:165], v141 offset:49152
	ds_read_b128 v[166:169], v141 offset:50176
	ds_read_b128 v[170:173], v141 offset:51200
	ds_read_b128 v[174:177], v141 offset:52224
	ds_read_b128 v[178:181], v141 offset:53248
	ds_read_b128 v[182:185], v141 offset:54272
	ds_read_b128 v[186:189], v141 offset:55296
	ds_read_b128 v[214:217], v141 offset:56320
	global_load_lds_dwordx4 v[154:155], off
	v_lshl_add_u64 v[154:155], v[234:235], 0, s[50:51]
	s_mov_b32 m0, s67
	s_nop 0
	global_load_lds_dwordx4 v[154:155], off
	s_barrier
	s_waitcnt lgkmcnt(0)
	s_waitcnt lgkmcnt(0)
	v_mfma_f32_16x16x32_bf16 v[60:63], v[134:137], v[162:165], v[60:63]
	v_mfma_f32_16x16x32_bf16 v[52:55], v[146:149], v[162:165], v[52:55]
	v_mfma_f32_16x16x32_bf16 v[44:47], v[134:137], v[170:173], v[44:47]
	v_mfma_f32_16x16x32_bf16 v[36:39], v[146:149], v[170:173], v[36:39]
	v_mfma_f32_16x16x32_bf16 v[28:31], v[134:137], v[178:181], v[28:31]
	v_mfma_f32_16x16x32_bf16 v[20:23], v[146:149], v[178:181], v[20:23]
	v_mfma_f32_16x16x32_bf16 v[12:15], v[134:137], v[186:189], v[12:15]
	v_mfma_f32_16x16x32_bf16 v[4:7], v[146:149], v[186:189], v[4:7]
	v_mfma_f32_16x16x32_bf16 v[60:63], v[142:145], v[166:169], v[60:63]
	v_mfma_f32_16x16x32_bf16 v[52:55], v[150:153], v[166:169], v[52:55]
	v_mfma_f32_16x16x32_bf16 v[44:47], v[142:145], v[174:177], v[44:47]
	v_mfma_f32_16x16x32_bf16 v[36:39], v[150:153], v[174:177], v[36:39]
	v_mfma_f32_16x16x32_bf16 v[28:31], v[142:145], v[182:185], v[28:31]
	v_mfma_f32_16x16x32_bf16 v[20:23], v[150:153], v[182:185], v[20:23]
	v_mfma_f32_16x16x32_bf16 v[12:15], v[142:145], v[214:217], v[12:15]
	v_mfma_f32_16x16x32_bf16 v[4:7], v[150:153], v[214:217], v[4:7]
	s_barrier
	s_add_u32 s2, s54, 0x40080
	s_addc_u32 s3, s55, 0
	s_add_i32 s54, s78, s53
	v_lshl_add_u64 v[134:135], s[2:3], 0, v[156:157]
	s_mov_b32 m0, s54
	s_nop 0
	global_load_lds_dwordx4 v[134:135], off
	v_lshl_add_u64 v[134:135], s[2:3], 0, v[128:129]
	s_add_i32 m0, s54, 0x2000
	s_nop 0
	global_load_lds_dwordx4 v[134:135], off
	s_waitcnt vmcnt(6)
	s_barrier
	v_mfma_f32_16x16x32_bf16 v[56:59], v[218:221], v[162:165], v[56:59]
	v_mfma_f32_16x16x32_bf16 v[48:51], v[226:229], v[162:165], v[48:51]
	v_mfma_f32_16x16x32_bf16 v[40:43], v[218:221], v[170:173], v[40:43]
	v_mfma_f32_16x16x32_bf16 v[32:35], v[226:229], v[170:173], v[32:35]
	v_mfma_f32_16x16x32_bf16 v[24:27], v[218:221], v[178:181], v[24:27]
	v_mfma_f32_16x16x32_bf16 v[16:19], v[226:229], v[178:181], v[16:19]
	v_mfma_f32_16x16x32_bf16 v[8:11], v[218:221], v[186:189], v[8:11]
	v_mfma_f32_16x16x32_bf16 v[0:3], v[226:229], v[186:189], v[0:3]
	v_mfma_f32_16x16x32_bf16 v[56:59], v[222:225], v[166:169], v[56:59]
	v_mfma_f32_16x16x32_bf16 v[48:51], v[230:233], v[166:169], v[48:51]
	v_mfma_f32_16x16x32_bf16 v[40:43], v[222:225], v[174:177], v[40:43]
	v_mfma_f32_16x16x32_bf16 v[32:35], v[230:233], v[174:177], v[32:35]
	v_mfma_f32_16x16x32_bf16 v[24:27], v[222:225], v[182:185], v[24:27]
	v_mfma_f32_16x16x32_bf16 v[16:19], v[230:233], v[182:185], v[16:19]
	v_mfma_f32_16x16x32_bf16 v[8:11], v[222:225], v[214:217], v[8:11]
	v_mfma_f32_16x16x32_bf16 v[0:3], v[230:233], v[214:217], v[0:3]
	s_add_i32 s73, s73, 2
	s_add_u32 s43, s43, 0x100
	s_addc_u32 s69, s69, 0
	s_add_u32 s6, s6, 0x100
	s_addc_u32 s7, s7, 0
	s_cmp_gt_u32 s73, 13
	s_barrier
	s_cbranch_scc1 .Lpost_555
.LBB0_555:
	s_add_u32 s2, s6, 0xfffc0080
	s_addc_u32 s3, s7, -1
	s_add_i32 s77, 0, 0x10000
	v_add_u32_e32 v150, s77, v139
	ds_read_b128 v[134:137], v150
	ds_read_b128 v[142:145], v150 offset:1024
	ds_read_b128 v[146:149], v150 offset:2048
	ds_read_b128 v[150:153], v150 offset:3072
	s_cmp_eq_u32 s73, 12
	s_cselect_b32 s3, s10, s3
	s_cselect_b32 s2, s24, s2
	s_cselect_b32 s55, s25, s69
	s_cselect_b32 s54, s41, s43
	v_lshl_add_u64 v[154:155], s[6:7], 0, v[132:133]
	s_add_i32 m0, s47, 0xc000
	ds_read_b128 v[162:165], v141
	ds_read_b128 v[166:169], v141 offset:1024
	ds_read_b128 v[170:173], v141 offset:2048
	ds_read_b128 v[174:177], v141 offset:3072
	ds_read_b128 v[178:181], v141 offset:4096
	ds_read_b128 v[182:185], v141 offset:5120
	ds_read_b128 v[186:189], v141 offset:6144
	ds_read_b128 v[214:217], v141 offset:7168
	global_load_lds_dwordx4 v[154:155], off
	v_lshl_add_u64 v[154:155], s[6:7], 0, v[130:131]
	s_add_i32 m0, s47, 0xe000
	s_nop 0
	global_load_lds_dwordx4 v[154:155], off
	s_waitcnt lgkmcnt(8)
	s_barrier
	s_waitcnt lgkmcnt(0)
	s_waitcnt lgkmcnt(0)
	v_mfma_f32_16x16x32_bf16 v[124:127], v[134:137], v[162:165], v[124:127]
	v_mfma_f32_16x16x32_bf16 v[116:119], v[146:149], v[162:165], v[116:119]
	v_mfma_f32_16x16x32_bf16 v[108:111], v[134:137], v[170:173], v[108:111]
	v_mfma_f32_16x16x32_bf16 v[100:103], v[146:149], v[170:173], v[100:103]
	v_mfma_f32_16x16x32_bf16 v[92:95], v[134:137], v[178:181], v[92:95]
	v_mfma_f32_16x16x32_bf16 v[84:87], v[146:149], v[178:181], v[84:87]
	v_mfma_f32_16x16x32_bf16 v[76:79], v[134:137], v[186:189], v[76:79]
	v_mfma_f32_16x16x32_bf16 v[68:71], v[146:149], v[186:189], v[68:71]
	v_mfma_f32_16x16x32_bf16 v[124:127], v[142:145], v[166:169], v[124:127]
	v_mfma_f32_16x16x32_bf16 v[116:119], v[150:153], v[166:169], v[116:119]
	v_mfma_f32_16x16x32_bf16 v[108:111], v[142:145], v[174:177], v[108:111]
	v_mfma_f32_16x16x32_bf16 v[100:103], v[150:153], v[174:177], v[100:103]
	v_mfma_f32_16x16x32_bf16 v[92:95], v[142:145], v[182:185], v[92:95]
	v_mfma_f32_16x16x32_bf16 v[84:87], v[150:153], v[182:185], v[84:87]
	v_mfma_f32_16x16x32_bf16 v[76:79], v[142:145], v[214:217], v[76:79]
	v_mfma_f32_16x16x32_bf16 v[68:71], v[150:153], v[214:217], v[68:71]
	s_barrier
	s_add_i32 s80, 0, 0x14000
	v_add_u32_e32 v154, s80, v139
	s_add_i32 s77, s77, s53
	ds_read_b128 v[218:221], v154
	ds_read_b128 v[222:225], v154 offset:1024
	ds_read_b128 v[226:229], v154 offset:2048
	ds_read_b128 v[230:233], v154 offset:3072
	v_lshl_add_u64 v[154:155], s[54:55], 0, v[156:157]
	s_mov_b32 m0, s77
	v_lshl_add_u64 v[206:207], s[54:55], 0, v[128:129]
	global_load_lds_dwordx4 v[154:155], off
	s_add_i32 m0, s77, 0x2000
	s_nop 0
	global_load_lds_dwordx4 v[206:207], off
	s_barrier
	s_waitcnt lgkmcnt(0)
	s_waitcnt lgkmcnt(0)
	v_mfma_f32_16x16x32_bf16 v[120:123], v[218:221], v[162:165], v[120:123]
	v_mfma_f32_16x16x32_bf16 v[112:115], v[226:229], v[162:165], v[112:115]
	v_mfma_f32_16x16x32_bf16 v[104:107], v[218:221], v[170:173], v[104:107]
	v_mfma_f32_16x16x32_bf16 v[96:99], v[226:229], v[170:173], v[96:99]
	v_mfma_f32_16x16x32_bf16 v[88:91], v[218:221], v[178:181], v[88:91]
	v_mfma_f32_16x16x32_bf16 v[80:83], v[226:229], v[178:181], v[80:83]
	v_mfma_f32_16x16x32_bf16 v[72:75], v[218:221], v[186:189], v[72:75]
	v_mfma_f32_16x16x32_bf16 v[64:67], v[226:229], v[186:189], v[64:67]
	v_mfma_f32_16x16x32_bf16 v[120:123], v[222:225], v[166:169], v[120:123]
	v_mfma_f32_16x16x32_bf16 v[112:115], v[230:233], v[166:169], v[112:115]
	v_mfma_f32_16x16x32_bf16 v[104:107], v[222:225], v[174:177], v[104:107]
	v_mfma_f32_16x16x32_bf16 v[96:99], v[230:233], v[174:177], v[96:99]
	v_mfma_f32_16x16x32_bf16 v[88:91], v[222:225], v[182:185], v[88:91]
	v_mfma_f32_16x16x32_bf16 v[80:83], v[230:233], v[182:185], v[80:83]
	v_mfma_f32_16x16x32_bf16 v[72:75], v[222:225], v[214:217], v[72:75]
	v_mfma_f32_16x16x32_bf16 v[64:67], v[230:233], v[214:217], v[64:67]
	s_mov_b32 m0, s47
	v_lshl_add_u64 v[208:209], s[2:3], 0, v[156:157]
	s_barrier
	ds_read_b128 v[162:165], v141 offset:16384
	ds_read_b128 v[166:169], v141 offset:17408
	ds_read_b128 v[170:173], v141 offset:18432
	ds_read_b128 v[174:177], v141 offset:19456
	ds_read_b128 v[178:181], v141 offset:20480
	ds_read_b128 v[182:185], v141 offset:21504
	ds_read_b128 v[186:189], v141 offset:22528
	ds_read_b128 v[214:217], v141 offset:23552
	global_load_lds_dwordx4 v[208:209], off
	v_lshl_add_u64 v[234:235], s[2:3], 0, v[128:129]
	s_mov_b32 m0, s49
	s_nop 0
	global_load_lds_dwordx4 v[234:235], off
	s_barrier
	s_waitcnt lgkmcnt(0)
	s_waitcnt lgkmcnt(0)
	v_mfma_f32_16x16x32_bf16 v[60:63], v[134:137], v[162:165], v[60:63]
	v_mfma_f32_16x16x32_bf16 v[52:55], v[146:149], v[162:165], v[52:55]
	v_mfma_f32_16x16x32_bf16 v[44:47], v[134:137], v[170:173], v[44:47]
	v_mfma_f32_16x16x32_bf16 v[36:39], v[146:149], v[170:173], v[36:39]
	v_mfma_f32_16x16x32_bf16 v[28:31], v[134:137], v[178:181], v[28:31]
	v_mfma_f32_16x16x32_bf16 v[20:23], v[146:149], v[178:181], v[20:23]
	v_mfma_f32_16x16x32_bf16 v[12:15], v[134:137], v[186:189], v[12:15]
	v_mfma_f32_16x16x32_bf16 v[4:7], v[146:149], v[186:189], v[4:7]
	v_mfma_f32_16x16x32_bf16 v[60:63], v[142:145], v[166:169], v[60:63]
	v_mfma_f32_16x16x32_bf16 v[52:55], v[150:153], v[166:169], v[52:55]
	v_mfma_f32_16x16x32_bf16 v[44:47], v[142:145], v[174:177], v[44:47]
	v_mfma_f32_16x16x32_bf16 v[36:39], v[150:153], v[174:177], v[36:39]
	v_mfma_f32_16x16x32_bf16 v[28:31], v[142:145], v[182:185], v[28:31]
	v_mfma_f32_16x16x32_bf16 v[20:23], v[150:153], v[182:185], v[20:23]
	v_mfma_f32_16x16x32_bf16 v[12:15], v[142:145], v[214:217], v[12:15]
	v_mfma_f32_16x16x32_bf16 v[4:7], v[150:153], v[214:217], v[4:7]
	s_barrier
	s_add_u32 s78, s54, 0x40000
	s_addc_u32 s79, s55, 0
	s_add_i32 s77, s80, s53
	v_lshl_add_u64 v[134:135], s[78:79], 0, v[156:157]
	s_mov_b32 m0, s77
	s_nop 0
	global_load_lds_dwordx4 v[134:135], off
	v_lshl_add_u64 v[134:135], s[78:79], 0, v[128:129]
	s_add_i32 m0, s77, 0x2000
	s_nop 0
	global_load_lds_dwordx4 v[134:135], off
	s_waitcnt vmcnt(6)
	s_barrier
	v_mfma_f32_16x16x32_bf16 v[56:59], v[218:221], v[162:165], v[56:59]
	v_mfma_f32_16x16x32_bf16 v[48:51], v[226:229], v[162:165], v[48:51]
	v_mfma_f32_16x16x32_bf16 v[40:43], v[218:221], v[170:173], v[40:43]
	v_mfma_f32_16x16x32_bf16 v[32:35], v[226:229], v[170:173], v[32:35]
	v_mfma_f32_16x16x32_bf16 v[24:27], v[218:221], v[178:181], v[24:27]
	v_mfma_f32_16x16x32_bf16 v[16:19], v[226:229], v[178:181], v[16:19]
	v_mfma_f32_16x16x32_bf16 v[8:11], v[218:221], v[186:189], v[8:11]
	v_mfma_f32_16x16x32_bf16 v[0:3], v[226:229], v[186:189], v[0:3]
	v_mfma_f32_16x16x32_bf16 v[56:59], v[222:225], v[166:169], v[56:59]
	v_mfma_f32_16x16x32_bf16 v[48:51], v[230:233], v[166:169], v[48:51]
	v_mfma_f32_16x16x32_bf16 v[40:43], v[222:225], v[174:177], v[40:43]
	v_mfma_f32_16x16x32_bf16 v[32:35], v[230:233], v[174:177], v[32:35]
	v_mfma_f32_16x16x32_bf16 v[24:27], v[222:225], v[182:185], v[24:27]
	v_mfma_f32_16x16x32_bf16 v[16:19], v[230:233], v[182:185], v[16:19]
	v_mfma_f32_16x16x32_bf16 v[8:11], v[222:225], v[214:217], v[8:11]
	v_mfma_f32_16x16x32_bf16 v[0:3], v[230:233], v[214:217], v[0:3]
	s_add_i32 s77, 0, 0x18000
	v_add_u32_e32 v150, s77, v139
	s_barrier
	ds_read_b128 v[134:137], v150
	ds_read_b128 v[142:145], v150 offset:1024
	ds_read_b128 v[146:149], v150 offset:2048
	ds_read_b128 v[150:153], v150 offset:3072
	s_add_u32 s2, s2, 0x40000
	s_addc_u32 s3, s3, 0
	s_mov_b32 m0, s62
	v_lshl_add_u64 v[218:219], s[2:3], 0, v[156:157]
	ds_read_b128 v[162:165], v141 offset:32768
	ds_read_b128 v[166:169], v141 offset:33792
	ds_read_b128 v[170:173], v141 offset:34816
	ds_read_b128 v[174:177], v141 offset:35840
	ds_read_b128 v[178:181], v141 offset:36864
	ds_read_b128 v[182:185], v141 offset:37888
	ds_read_b128 v[186:189], v141 offset:38912
	ds_read_b128 v[214:217], v141 offset:39936
	global_load_lds_dwordx4 v[218:219], off
	v_lshl_add_u64 v[218:219], s[2:3], 0, v[128:129]
	s_mov_b32 m0, s63
	s_nop 0
	global_load_lds_dwordx4 v[218:219], off
	s_waitcnt lgkmcnt(8)
	s_barrier
	s_waitcnt lgkmcnt(0)
	s_waitcnt lgkmcnt(0)
	v_mfma_f32_16x16x32_bf16 v[124:127], v[134:137], v[162:165], v[124:127]
	v_mfma_f32_16x16x32_bf16 v[116:119], v[146:149], v[162:165], v[116:119]
	v_mfma_f32_16x16x32_bf16 v[108:111], v[134:137], v[170:173], v[108:111]
	v_mfma_f32_16x16x32_bf16 v[100:103], v[146:149], v[170:173], v[100:103]
	v_mfma_f32_16x16x32_bf16 v[92:95], v[134:137], v[178:181], v[92:95]
	v_mfma_f32_16x16x32_bf16 v[84:87], v[146:149], v[178:181], v[84:87]
	v_mfma_f32_16x16x32_bf16 v[76:79], v[134:137], v[186:189], v[76:79]
	v_mfma_f32_16x16x32_bf16 v[68:71], v[146:149], v[186:189], v[68:71]
	v_mfma_f32_16x16x32_bf16 v[124:127], v[142:145], v[166:169], v[124:127]
	v_mfma_f32_16x16x32_bf16 v[116:119], v[150:153], v[166:169], v[116:119]
	v_mfma_f32_16x16x32_bf16 v[108:111], v[142:145], v[174:177], v[108:111]
	v_mfma_f32_16x16x32_bf16 v[100:103], v[150:153], v[174:177], v[100:103]
	v_mfma_f32_16x16x32_bf16 v[92:95], v[142:145], v[182:185], v[92:95]
	v_mfma_f32_16x16x32_bf16 v[84:87], v[150:153], v[182:185], v[84:87]
	v_mfma_f32_16x16x32_bf16 v[76:79], v[142:145], v[214:217], v[76:79]
	v_mfma_f32_16x16x32_bf16 v[68:71], v[150:153], v[214:217], v[68:71]
	s_barrier
	s_add_i32 s78, 0, 0x1c000
	s_add_i32 s2, s77, s53
	v_add_u32_e32 v161, s78, v139
	v_lshl_add_u64 v[154:155], v[154:155], 0, s[50:51]
	s_mov_b32 m0, s2
	ds_read_b128 v[218:221], v161
	ds_read_b128 v[222:225], v161 offset:1024
	ds_read_b128 v[226:229], v161 offset:2048
	ds_read_b128 v[230:233], v161 offset:3072
	global_load_lds_dwordx4 v[154:155], off
	v_lshl_add_u64 v[154:155], v[206:207], 0, s[50:51]
	s_add_i32 m0, s2, 0x2000
	s_nop 0
	global_load_lds_dwordx4 v[154:155], off
	s_barrier
	s_waitcnt lgkmcnt(0)
	s_waitcnt lgkmcnt(0)
	v_mfma_f32_16x16x32_bf16 v[120:123], v[218:221], v[162:165], v[120:123]
	v_mfma_f32_16x16x32_bf16 v[112:115], v[226:229], v[162:165], v[112:115]
	v_mfma_f32_16x16x32_bf16 v[104:107], v[218:221], v[170:173], v[104:107]
	v_mfma_f32_16x16x32_bf16 v[96:99], v[226:229], v[170:173], v[96:99]
	v_mfma_f32_16x16x32_bf16 v[88:91], v[218:221], v[178:181], v[88:91]
	v_mfma_f32_16x16x32_bf16 v[80:83], v[226:229], v[178:181], v[80:83]
	v_mfma_f32_16x16x32_bf16 v[72:75], v[218:221], v[186:189], v[72:75]
	v_mfma_f32_16x16x32_bf16 v[64:67], v[226:229], v[186:189], v[64:67]
	v_mfma_f32_16x16x32_bf16 v[120:123], v[222:225], v[166:169], v[120:123]
	v_mfma_f32_16x16x32_bf16 v[112:115], v[230:233], v[166:169], v[112:115]
	v_mfma_f32_16x16x32_bf16 v[104:107], v[222:225], v[174:177], v[104:107]
	v_mfma_f32_16x16x32_bf16 v[96:99], v[230:233], v[174:177], v[96:99]
	v_mfma_f32_16x16x32_bf16 v[88:91], v[222:225], v[182:185], v[88:91]
	v_mfma_f32_16x16x32_bf16 v[80:83], v[230:233], v[182:185], v[80:83]
	v_mfma_f32_16x16x32_bf16 v[72:75], v[222:225], v[214:217], v[72:75]
	v_mfma_f32_16x16x32_bf16 v[64:67], v[230:233], v[214:217], v[64:67]
	s_mov_b32 m0, s66
	v_lshl_add_u64 v[154:155], v[208:209], 0, s[50:51]
	s_barrier
	ds_read_b128 v[162:165], v141 offset:49152
	ds_read_b128 v[166:169], v141 offset:50176
	ds_read_b128 v[170:173], v141 offset:51200
	ds_read_b128 v[174:177], v141 offset:52224
	ds_read_b128 v[178:181], v141 offset:53248
	ds_read_b128 v[182:185], v141 offset:54272
	ds_read_b128 v[186:189], v141 offset:55296
	ds_read_b128 v[214:217], v141 offset:56320
	global_load_lds_dwordx4 v[154:155], off
	v_lshl_add_u64 v[154:155], v[234:235], 0, s[50:51]
	s_mov_b32 m0, s67
	s_nop 0
	global_load_lds_dwordx4 v[154:155], off
	s_barrier
	s_waitcnt lgkmcnt(0)
	s_waitcnt lgkmcnt(0)
	v_mfma_f32_16x16x32_bf16 v[60:63], v[134:137], v[162:165], v[60:63]
	v_mfma_f32_16x16x32_bf16 v[52:55], v[146:149], v[162:165], v[52:55]
	v_mfma_f32_16x16x32_bf16 v[44:47], v[134:137], v[170:173], v[44:47]
	v_mfma_f32_16x16x32_bf16 v[36:39], v[146:149], v[170:173], v[36:39]
	v_mfma_f32_16x16x32_bf16 v[28:31], v[134:137], v[178:181], v[28:31]
	v_mfma_f32_16x16x32_bf16 v[20:23], v[146:149], v[178:181], v[20:23]
	v_mfma_f32_16x16x32_bf16 v[12:15], v[134:137], v[186:189], v[12:15]
	v_mfma_f32_16x16x32_bf16 v[4:7], v[146:149], v[186:189], v[4:7]
	v_mfma_f32_16x16x32_bf16 v[60:63], v[142:145], v[166:169], v[60:63]
	v_mfma_f32_16x16x32_bf16 v[52:55], v[150:153], v[166:169], v[52:55]
	v_mfma_f32_16x16x32_bf16 v[44:47], v[142:145], v[174:177], v[44:47]
	v_mfma_f32_16x16x32_bf16 v[36:39], v[150:153], v[174:177], v[36:39]
	v_mfma_f32_16x16x32_bf16 v[28:31], v[142:145], v[182:185], v[28:31]
	v_mfma_f32_16x16x32_bf16 v[20:23], v[150:153], v[182:185], v[20:23]
	v_mfma_f32_16x16x32_bf16 v[12:15], v[142:145], v[214:217], v[12:15]
	v_mfma_f32_16x16x32_bf16 v[4:7], v[150:153], v[214:217], v[4:7]
	s_barrier
	s_add_u32 s2, s54, 0x40080
	s_addc_u32 s3, s55, 0
	s_add_i32 s54, s78, s53
	v_lshl_add_u64 v[134:135], s[2:3], 0, v[156:157]
	s_mov_b32 m0, s54
	s_nop 0
	global_load_lds_dwordx4 v[134:135], off
	v_lshl_add_u64 v[134:135], s[2:3], 0, v[128:129]
	s_add_i32 m0, s54, 0x2000
	s_nop 0
	global_load_lds_dwordx4 v[134:135], off
	s_waitcnt vmcnt(6)
	s_barrier
	v_mfma_f32_16x16x32_bf16 v[56:59], v[218:221], v[162:165], v[56:59]
	v_mfma_f32_16x16x32_bf16 v[48:51], v[226:229], v[162:165], v[48:51]
	v_mfma_f32_16x16x32_bf16 v[40:43], v[218:221], v[170:173], v[40:43]
	v_mfma_f32_16x16x32_bf16 v[32:35], v[226:229], v[170:173], v[32:35]
	v_mfma_f32_16x16x32_bf16 v[24:27], v[218:221], v[178:181], v[24:27]
	v_mfma_f32_16x16x32_bf16 v[16:19], v[226:229], v[178:181], v[16:19]
	v_mfma_f32_16x16x32_bf16 v[8:11], v[218:221], v[186:189], v[8:11]
	v_mfma_f32_16x16x32_bf16 v[0:3], v[226:229], v[186:189], v[0:3]
	v_mfma_f32_16x16x32_bf16 v[56:59], v[222:225], v[166:169], v[56:59]
	v_mfma_f32_16x16x32_bf16 v[48:51], v[230:233], v[166:169], v[48:51]
	v_mfma_f32_16x16x32_bf16 v[40:43], v[222:225], v[174:177], v[40:43]
	v_mfma_f32_16x16x32_bf16 v[32:35], v[230:233], v[174:177], v[32:35]
	v_mfma_f32_16x16x32_bf16 v[24:27], v[222:225], v[182:185], v[24:27]
	v_mfma_f32_16x16x32_bf16 v[16:19], v[230:233], v[182:185], v[16:19]
	v_mfma_f32_16x16x32_bf16 v[8:11], v[222:225], v[214:217], v[8:11]
	v_mfma_f32_16x16x32_bf16 v[0:3], v[230:233], v[214:217], v[0:3]
	s_add_i32 s73, s73, 2
	s_add_u32 s43, s43, 0x100
	s_addc_u32 s69, s69, 0
	s_add_u32 s6, s6, 0x100
	s_addc_u32 s7, s7, 0
	s_cmp_gt_u32 s73, 13
	s_barrier
	s_cbranch_scc0 .LBB0_555
